# accumulator chains visited in boustrophedon order (neighbouring chains share a fragment register); on top of v40
# speedup vs baseline: 1.0143x; 1.0036x over previous
; #define PG8_STAGEX(rs, bufoff, soff, voff) do { _Pragma("unroll") for (int _i = 0; _i < 2; ++_i) \
;         __builtin_amdgcn_raw_ptr_buffer_load_lds(rs, (LAS unsigned*)(lds + (bufoff) + ldsw + _i * 8192), 16, (voff)[_i], (soff), 0, 0); } while (0)
; #define PG8_LDA(dst, b, h) do { _Pragma("unroll") for (int m = 0; m < 4; ++m) _Pragma("unroll") for (int k = 0; k < 2; ++k) dst[m][k] = *(const LAS bf16x8*)(lds + PG8_SA(b, h) + aoff + m * 2048 + k * 1024); } while (0)
; #define PG8_LDB(dst, b, h) do { _Pragma("unroll") for (int n = 0; n < 2; ++n) _Pragma("unroll") for (int k = 0; k < 2; ++k) dst[n][k] = *(const LAS bf16x8*)(lds + PG8_SB(b, h) + boff + n * 2048 + k * 1024); } while (0)
; #define PG8_WAIT_V(n) asm volatile("s_waitcnt vmcnt(" #n ")" ::: "memory")
; #define PG8_WAIT_L(n) asm volatile("s_waitcnt lgkmcnt(" #n ")" ::: "memory")
; #define PG8_BAR __builtin_amdgcn_s_barrier()
; #define PG8_SCHED __builtin_amdgcn_sched_barrier(0)
;     ...
;         for (int t = 0; t < nt; t += 2) {
;             const bool last = (t == nt - 2);
;             const unsigned a1 = cA + (unsigned)(t + 1) * kstep;
;             const unsigned a2 = last ? nA : cA + (unsigned)(t + 2) * kstep, b2 = last ? nB : cB + (unsigned)(t + 2) * kstep;
;             const unsigned a3 = a2 + kstep, b3 = b2 + kstep;
;             PG8_LDB(B0, 0, 0); PG8_LDB(B1, 0, 1); PG8_SCHED; PG8_LDA(At, 0, 0); PG8_STAGEX(rsA, PG8_SA(1, 1), a1 + hstepA, voffA);
;             PG8_WAIT_V(8); PG8_WAIT_L(0); PG8_BAR; PG8_MMA(0, 0, At, B0); PG8_MMA(0, 1, At, B1); PG8_BAR; PG8_SCHED;
;             PG8_LDA(At, 0, 1); PG8_STAGEX(rsB, PG8_SB(0, 0), b2, voffB); PG8_STAGEX(rsB, PG8_SB(0, 1), b2 + hstepB, voffB); PG8_STAGEX(rsA, PG8_SA(0, 0), a2, voffA);
;             PG8_WAIT_V(8); PG8_WAIT_L(0); PG8_BAR; PG8_MMA(1, 0, At, B0); PG8_MMA(1, 1, At, B1); PG8_BAR; PG8_SCHED;
.LBB0_223:
	v_add_u32_e32 v102, 0x10000, v172
	v_add_u32_e32 v146, 0x14000, v172
	ds_read_b128 v[82:85], v102
	ds_read_b128 v[86:89], v102 offset:1024
	ds_read_b128 v[98:101], v102 offset:2048
	ds_read_b128 v[102:105], v102 offset:3072
	ds_read_b128 v[150:153], v146
	ds_read_b128 v[154:157], v146 offset:1024
	ds_read_b128 v[182:185], v146 offset:2048
	ds_read_b128 v[186:189], v146 offset:3072
	s_add_i32 s42, s50, 0xfff80080
	s_cmp_eq_u32 s52, 28
	s_cselect_b32 s55, s30, s42
	s_cselect_b32 s54, s31, s51
	s_or_b32 s53, s55, 0x80
	s_mov_b32 m0, s22
	ds_read_b128 v[190:193], v173
	ds_read_b128 v[194:197], v173 offset:1024
	ds_read_b128 v[198:201], v173 offset:2048
	ds_read_b128 v[202:205], v173 offset:3072
	ds_read_b128 v[206:209], v173 offset:4096
	ds_read_b128 v[210:213], v173 offset:5120
	ds_read_b128 v[214:217], v173 offset:6144
	ds_read_b128 v[218:221], v173 offset:7168
	buffer_load_dwordx4 v159, s[76:79], s50 offen lds
	s_mov_b32 m0, s23
	s_nop 0
	buffer_load_dwordx4 v163, s[76:79], s50 offen lds
	s_waitcnt vmcnt(8)
	s_waitcnt lgkmcnt(0)
	s_setprio 1
	s_barrier
	v_mfma_f32_16x16x32_bf16 v[142:145], v[82:85], v[190:193], v[142:145]
	v_mfma_f32_16x16x32_bf16 v[142:145], v[86:89], v[194:197], v[142:145]
	v_mfma_f32_16x16x32_bf16 v[134:137], v[98:101], v[190:193], v[134:137]
	v_mfma_f32_16x16x32_bf16 v[134:137], v[102:105], v[194:197], v[134:137]
	v_mfma_f32_16x16x32_bf16 v[118:121], v[98:101], v[198:201], v[118:121]
	v_mfma_f32_16x16x32_bf16 v[118:121], v[102:105], v[202:205], v[118:121]
	v_mfma_f32_16x16x32_bf16 v[126:129], v[82:85], v[198:201], v[126:129]
	v_mfma_f32_16x16x32_bf16 v[126:129], v[86:89], v[202:205], v[126:129]
	v_mfma_f32_16x16x32_bf16 v[110:113], v[82:85], v[206:209], v[110:113]
	v_mfma_f32_16x16x32_bf16 v[110:113], v[86:89], v[210:213], v[110:113]
	v_mfma_f32_16x16x32_bf16 v[94:97], v[98:101], v[206:209], v[94:97]
	v_mfma_f32_16x16x32_bf16 v[94:97], v[102:105], v[210:213], v[94:97]
	v_mfma_f32_16x16x32_bf16 v[70:73], v[98:101], v[214:217], v[70:73]
	v_mfma_f32_16x16x32_bf16 v[70:73], v[102:105], v[218:221], v[70:73]
	v_mfma_f32_16x16x32_bf16 v[78:81], v[82:85], v[214:217], v[78:81]
	v_mfma_f32_16x16x32_bf16 v[78:81], v[86:89], v[218:221], v[78:81]
	v_mfma_f32_16x16x32_bf16 v[138:141], v[150:153], v[190:193], v[138:141]
	v_mfma_f32_16x16x32_bf16 v[138:141], v[154:157], v[194:197], v[138:141]
	v_mfma_f32_16x16x32_bf16 v[130:133], v[182:185], v[190:193], v[130:133]
	v_mfma_f32_16x16x32_bf16 v[130:133], v[186:189], v[194:197], v[130:133]
	v_mfma_f32_16x16x32_bf16 v[114:117], v[182:185], v[198:201], v[114:117]
	v_mfma_f32_16x16x32_bf16 v[114:117], v[186:189], v[202:205], v[114:117]
	v_mfma_f32_16x16x32_bf16 v[122:125], v[150:153], v[198:201], v[122:125]
	v_mfma_f32_16x16x32_bf16 v[122:125], v[154:157], v[202:205], v[122:125]
	v_mfma_f32_16x16x32_bf16 v[106:109], v[150:153], v[206:209], v[106:109]
	v_mfma_f32_16x16x32_bf16 v[106:109], v[154:157], v[210:213], v[106:109]
	v_mfma_f32_16x16x32_bf16 v[90:93], v[182:185], v[206:209], v[90:93]
	v_mfma_f32_16x16x32_bf16 v[90:93], v[186:189], v[210:213], v[90:93]
	v_mfma_f32_16x16x32_bf16 v[66:69], v[182:185], v[214:217], v[66:69]
	v_mfma_f32_16x16x32_bf16 v[66:69], v[186:189], v[218:221], v[66:69]
	v_mfma_f32_16x16x32_bf16 v[74:77], v[150:153], v[214:217], v[74:77]
	v_mfma_f32_16x16x32_bf16 v[74:77], v[154:157], v[218:221], v[74:77]
	s_barrier
	s_setprio 0
	s_mov_b32 m0, s9
	s_mov_b32 s42, s78
	s_mov_b32 s43, s79
	ds_read_b128 v[190:193], v173 offset:16384
	ds_read_b128 v[194:197], v173 offset:17408
	ds_read_b128 v[198:201], v173 offset:18432
	ds_read_b128 v[202:205], v173 offset:19456
	ds_read_b128 v[206:209], v173 offset:20480
	ds_read_b128 v[210:213], v173 offset:21504
	ds_read_b128 v[214:217], v173 offset:22528
	ds_read_b128 v[218:221], v173 offset:23552
	buffer_load_dwordx4 v161, s[40:43], s54 offen lds
	s_mov_b32 m0, s10
	s_add_i32 s56, s54, 0x80000
	buffer_load_dwordx4 v165, s[40:43], s54 offen lds
	s_mov_b32 m0, s11
	s_nop 0
	buffer_load_dwordx4 v161, s[40:43], s56 offen lds
	s_mov_b32 m0, s12
	s_nop 0
	buffer_load_dwordx4 v165, s[40:43], s56 offen lds
	s_mov_b32 m0, s8
	s_nop 0
	buffer_load_dwordx4 v159, s[76:79], s55 offen lds
	s_mov_b32 m0, s13
	s_nop 0
	buffer_load_dwordx4 v163, s[76:79], s55 offen lds
	s_waitcnt vmcnt(8)
	s_waitcnt lgkmcnt(0)
	s_setprio 1
	s_barrier
	v_mfma_f32_16x16x32_bf16 v[62:65], v[82:85], v[190:193], v[62:65]
	v_mfma_f32_16x16x32_bf16 v[62:65], v[86:89], v[194:197], v[62:65]
	v_mfma_f32_16x16x32_bf16 v[54:57], v[98:101], v[190:193], v[54:57]
	v_mfma_f32_16x16x32_bf16 v[54:57], v[102:105], v[194:197], v[54:57]
	v_mfma_f32_16x16x32_bf16 v[38:41], v[98:101], v[198:201], v[38:41]
	v_mfma_f32_16x16x32_bf16 v[38:41], v[102:105], v[202:205], v[38:41]
	v_mfma_f32_16x16x32_bf16 v[46:49], v[82:85], v[198:201], v[46:49]
	v_mfma_f32_16x16x32_bf16 v[46:49], v[86:89], v[202:205], v[46:49]
	v_mfma_f32_16x16x32_bf16 v[30:33], v[82:85], v[206:209], v[30:33]
	v_mfma_f32_16x16x32_bf16 v[30:33], v[86:89], v[210:213], v[30:33]
	v_mfma_f32_16x16x32_bf16 v[22:25], v[98:101], v[206:209], v[22:25]
	v_mfma_f32_16x16x32_bf16 v[22:25], v[102:105], v[210:213], v[22:25]
	v_mfma_f32_16x16x32_bf16 v[6:9], v[98:101], v[214:217], v[6:9]
	v_mfma_f32_16x16x32_bf16 v[6:9], v[102:105], v[218:221], v[6:9]
	v_mfma_f32_16x16x32_bf16 v[14:17], v[82:85], v[214:217], v[14:17]
	v_mfma_f32_16x16x32_bf16 v[14:17], v[86:89], v[218:221], v[14:17]
	v_mfma_f32_16x16x32_bf16 v[58:61], v[150:153], v[190:193], v[58:61]
	v_mfma_f32_16x16x32_bf16 v[58:61], v[154:157], v[194:197], v[58:61]
	v_mfma_f32_16x16x32_bf16 v[50:53], v[182:185], v[190:193], v[50:53]
	v_mfma_f32_16x16x32_bf16 v[50:53], v[186:189], v[194:197], v[50:53]
	v_mfma_f32_16x16x32_bf16 v[34:37], v[182:185], v[198:201], v[34:37]
	v_mfma_f32_16x16x32_bf16 v[34:37], v[186:189], v[202:205], v[34:37]
	v_mfma_f32_16x16x32_bf16 v[42:45], v[150:153], v[198:201], v[42:45]
	v_mfma_f32_16x16x32_bf16 v[42:45], v[154:157], v[202:205], v[42:45]
	v_mfma_f32_16x16x32_bf16 v[26:29], v[150:153], v[206:209], v[26:29]
	v_mfma_f32_16x16x32_bf16 v[26:29], v[154:157], v[210:213], v[26:29]
	v_mfma_f32_16x16x32_bf16 v[18:21], v[182:185], v[206:209], v[18:21]
	v_mfma_f32_16x16x32_bf16 v[18:21], v[186:189], v[210:213], v[18:21]
	v_mfma_f32_16x16x32_bf16 v[2:5], v[182:185], v[214:217], v[2:5]
	v_mfma_f32_16x16x32_bf16 v[2:5], v[186:189], v[218:221], v[2:5]
	v_mfma_f32_16x16x32_bf16 v[10:13], v[150:153], v[214:217], v[10:13]
	v_mfma_f32_16x16x32_bf16 v[10:13], v[154:157], v[218:221], v[10:13]
	s_barrier
; #define PG8_STAGEX(rs, bufoff, soff, voff) do { _Pragma("unroll") for (int _i = 0; _i < 2; ++_i) \
;         __builtin_amdgcn_raw_ptr_buffer_load_lds(rs, (LAS unsigned*)(lds + (bufoff) + ldsw + _i * 8192), 16, (voff)[_i], (soff), 0, 0); } while (0)
; #define PG8_LDA(dst, b, h) do { _Pragma("unroll") for (int m = 0; m < 4; ++m) _Pragma("unroll") for (int k = 0; k < 2; ++k) dst[m][k] = *(const LAS bf16x8*)(lds + PG8_SA(b, h) + aoff + m * 2048 + k * 1024); } while (0)
; #define PG8_LDB(dst, b, h) do { _Pragma("unroll") for (int n = 0; n < 2; ++n) _Pragma("unroll") for (int k = 0; k < 2; ++k) dst[n][k] = *(const LAS bf16x8*)(lds + PG8_SB(b, h) + boff + n * 2048 + k * 1024); } while (0)
; #define PG8_WAIT_V(n) asm volatile("s_waitcnt vmcnt(" #n ")" ::: "memory")
; #define PG8_WAIT_L(n) asm volatile("s_waitcnt lgkmcnt(" #n ")" ::: "memory")
; #define PG8_BAR __builtin_amdgcn_s_barrier()
; #define PG8_SCHED __builtin_amdgcn_sched_barrier(0)
;     ...
;             PG8_LDB(B0, 1, 0); PG8_LDB(B1, 1, 1); PG8_SCHED; PG8_LDA(At, 1, 0); PG8_STAGEX(rsA, PG8_SA(0, 1), a2 + hstepA, voffA);
;             PG8_WAIT_V(8); PG8_WAIT_L(0); PG8_BAR; PG8_MMA(0, 0, At, B0); PG8_MMA(0, 1, At, B1); PG8_BAR; PG8_SCHED;
;             PG8_LDA(At, 1, 1); PG8_STAGEX(rsB, PG8_SB(1, 0), b3, voffB); PG8_STAGEX(rsB, PG8_SB(1, 1), b3 + hstepB, voffB); PG8_STAGEX(rsA, PG8_SA(1, 0), a3, voffA);
;             PG8_WAIT_V(8); PG8_WAIT_L(0); PG8_BAR; PG8_MMA(1, 0, At, B0); PG8_MMA(1, 1, At, B1); PG8_BAR; PG8_SCHED;
;         }
;     ...
;         if (wr == 0) PG8_BAR;
	s_setprio 0
	v_add_u32_e32 v102, 0x18000, v172
	v_add_u32_e32 v146, 0x1c000, v172
	ds_read_b128 v[82:85], v102
	ds_read_b128 v[86:89], v102 offset:1024
	ds_read_b128 v[98:101], v102 offset:2048
	ds_read_b128 v[102:105], v102 offset:3072
	ds_read_b128 v[150:153], v146
	ds_read_b128 v[154:157], v146 offset:1024
	ds_read_b128 v[182:185], v146 offset:2048
	ds_read_b128 v[186:189], v146 offset:3072
	s_add_i32 s55, s55, 0x80000
	s_mov_b32 m0, s14
	ds_read_b128 v[190:193], v173 offset:32768
	ds_read_b128 v[194:197], v173 offset:33792
	ds_read_b128 v[198:201], v173 offset:34816
	ds_read_b128 v[202:205], v173 offset:35840
	ds_read_b128 v[206:209], v173 offset:36864
	ds_read_b128 v[210:213], v173 offset:37888
	ds_read_b128 v[214:217], v173 offset:38912
	ds_read_b128 v[218:221], v173 offset:39936
	buffer_load_dwordx4 v159, s[76:79], s55 offen lds
	s_mov_b32 m0, s15
	s_nop 0
	buffer_load_dwordx4 v163, s[76:79], s55 offen lds
	s_waitcnt vmcnt(8)
	s_waitcnt lgkmcnt(0)
	s_setprio 1
	s_barrier
	v_mfma_f32_16x16x32_bf16 v[142:145], v[82:85], v[190:193], v[142:145]
	v_mfma_f32_16x16x32_bf16 v[142:145], v[86:89], v[194:197], v[142:145]
	v_mfma_f32_16x16x32_bf16 v[134:137], v[98:101], v[190:193], v[134:137]
	v_mfma_f32_16x16x32_bf16 v[134:137], v[102:105], v[194:197], v[134:137]
	v_mfma_f32_16x16x32_bf16 v[118:121], v[98:101], v[198:201], v[118:121]
	v_mfma_f32_16x16x32_bf16 v[118:121], v[102:105], v[202:205], v[118:121]
	v_mfma_f32_16x16x32_bf16 v[126:129], v[82:85], v[198:201], v[126:129]
	v_mfma_f32_16x16x32_bf16 v[126:129], v[86:89], v[202:205], v[126:129]
	v_mfma_f32_16x16x32_bf16 v[110:113], v[82:85], v[206:209], v[110:113]
	v_mfma_f32_16x16x32_bf16 v[110:113], v[86:89], v[210:213], v[110:113]
	v_mfma_f32_16x16x32_bf16 v[94:97], v[98:101], v[206:209], v[94:97]
	v_mfma_f32_16x16x32_bf16 v[94:97], v[102:105], v[210:213], v[94:97]
	v_mfma_f32_16x16x32_bf16 v[70:73], v[98:101], v[214:217], v[70:73]
	v_mfma_f32_16x16x32_bf16 v[70:73], v[102:105], v[218:221], v[70:73]
	v_mfma_f32_16x16x32_bf16 v[78:81], v[82:85], v[214:217], v[78:81]
	v_mfma_f32_16x16x32_bf16 v[78:81], v[86:89], v[218:221], v[78:81]
	v_mfma_f32_16x16x32_bf16 v[138:141], v[150:153], v[190:193], v[138:141]
	v_mfma_f32_16x16x32_bf16 v[138:141], v[154:157], v[194:197], v[138:141]
	v_mfma_f32_16x16x32_bf16 v[130:133], v[182:185], v[190:193], v[130:133]
	v_mfma_f32_16x16x32_bf16 v[130:133], v[186:189], v[194:197], v[130:133]
	v_mfma_f32_16x16x32_bf16 v[114:117], v[182:185], v[198:201], v[114:117]
	v_mfma_f32_16x16x32_bf16 v[114:117], v[186:189], v[202:205], v[114:117]
	v_mfma_f32_16x16x32_bf16 v[122:125], v[150:153], v[198:201], v[122:125]
	v_mfma_f32_16x16x32_bf16 v[122:125], v[154:157], v[202:205], v[122:125]
	v_mfma_f32_16x16x32_bf16 v[106:109], v[150:153], v[206:209], v[106:109]
	v_mfma_f32_16x16x32_bf16 v[106:109], v[154:157], v[210:213], v[106:109]
	v_mfma_f32_16x16x32_bf16 v[90:93], v[182:185], v[206:209], v[90:93]
	v_mfma_f32_16x16x32_bf16 v[90:93], v[186:189], v[210:213], v[90:93]
	v_mfma_f32_16x16x32_bf16 v[66:69], v[182:185], v[214:217], v[66:69]
	v_mfma_f32_16x16x32_bf16 v[66:69], v[186:189], v[218:221], v[66:69]
	v_mfma_f32_16x16x32_bf16 v[74:77], v[150:153], v[214:217], v[74:77]
	v_mfma_f32_16x16x32_bf16 v[74:77], v[154:157], v[218:221], v[74:77]
	s_barrier
	s_setprio 0
	s_mov_b32 m0, s16
	s_or_b32 s55, s54, 0x80
	ds_read_b128 v[190:193], v173 offset:49152
	ds_read_b128 v[194:197], v173 offset:50176
	ds_read_b128 v[198:201], v173 offset:51200
	ds_read_b128 v[202:205], v173 offset:52224
	ds_read_b128 v[206:209], v173 offset:53248
	ds_read_b128 v[210:213], v173 offset:54272
	ds_read_b128 v[214:217], v173 offset:55296
	ds_read_b128 v[218:221], v173 offset:56320
	buffer_load_dwordx4 v161, s[40:43], s55 offen lds
	s_mov_b32 m0, s17
	s_add_i32 s54, s54, 0x80080
	buffer_load_dwordx4 v165, s[40:43], s55 offen lds
	s_mov_b32 m0, s20
	s_nop 0
	buffer_load_dwordx4 v161, s[40:43], s54 offen lds
	s_mov_b32 m0, s21
	s_nop 0
	buffer_load_dwordx4 v165, s[40:43], s54 offen lds
	s_mov_b32 m0, s18
	s_nop 0
	buffer_load_dwordx4 v159, s[76:79], s53 offen lds
	s_mov_b32 m0, s19
	s_nop 0
	buffer_load_dwordx4 v163, s[76:79], s53 offen lds
	s_waitcnt vmcnt(8)
	s_waitcnt lgkmcnt(0)
	s_setprio 1
	s_barrier
	v_mfma_f32_16x16x32_bf16 v[62:65], v[82:85], v[190:193], v[62:65]
	v_mfma_f32_16x16x32_bf16 v[62:65], v[86:89], v[194:197], v[62:65]
	v_mfma_f32_16x16x32_bf16 v[54:57], v[98:101], v[190:193], v[54:57]
	v_mfma_f32_16x16x32_bf16 v[54:57], v[102:105], v[194:197], v[54:57]
	v_mfma_f32_16x16x32_bf16 v[38:41], v[98:101], v[198:201], v[38:41]
	v_mfma_f32_16x16x32_bf16 v[38:41], v[102:105], v[202:205], v[38:41]
	v_mfma_f32_16x16x32_bf16 v[46:49], v[82:85], v[198:201], v[46:49]
	v_mfma_f32_16x16x32_bf16 v[46:49], v[86:89], v[202:205], v[46:49]
	v_mfma_f32_16x16x32_bf16 v[30:33], v[82:85], v[206:209], v[30:33]
	v_mfma_f32_16x16x32_bf16 v[30:33], v[86:89], v[210:213], v[30:33]
	v_mfma_f32_16x16x32_bf16 v[22:25], v[98:101], v[206:209], v[22:25]
	v_mfma_f32_16x16x32_bf16 v[22:25], v[102:105], v[210:213], v[22:25]
	v_mfma_f32_16x16x32_bf16 v[6:9], v[98:101], v[214:217], v[6:9]
	v_mfma_f32_16x16x32_bf16 v[6:9], v[102:105], v[218:221], v[6:9]
	v_mfma_f32_16x16x32_bf16 v[14:17], v[82:85], v[214:217], v[14:17]
	v_mfma_f32_16x16x32_bf16 v[14:17], v[86:89], v[218:221], v[14:17]
	v_mfma_f32_16x16x32_bf16 v[58:61], v[150:153], v[190:193], v[58:61]
	v_mfma_f32_16x16x32_bf16 v[58:61], v[154:157], v[194:197], v[58:61]
	v_mfma_f32_16x16x32_bf16 v[50:53], v[182:185], v[190:193], v[50:53]
	v_mfma_f32_16x16x32_bf16 v[50:53], v[186:189], v[194:197], v[50:53]
	v_mfma_f32_16x16x32_bf16 v[34:37], v[182:185], v[198:201], v[34:37]
	v_mfma_f32_16x16x32_bf16 v[34:37], v[186:189], v[202:205], v[34:37]
	v_mfma_f32_16x16x32_bf16 v[42:45], v[150:153], v[198:201], v[42:45]
	v_mfma_f32_16x16x32_bf16 v[42:45], v[154:157], v[202:205], v[42:45]
	v_mfma_f32_16x16x32_bf16 v[26:29], v[150:153], v[206:209], v[26:29]
	v_mfma_f32_16x16x32_bf16 v[26:29], v[154:157], v[210:213], v[26:29]
	v_mfma_f32_16x16x32_bf16 v[18:21], v[182:185], v[206:209], v[18:21]
	v_mfma_f32_16x16x32_bf16 v[18:21], v[186:189], v[210:213], v[18:21]
	v_mfma_f32_16x16x32_bf16 v[2:5], v[182:185], v[214:217], v[2:5]
	v_mfma_f32_16x16x32_bf16 v[2:5], v[186:189], v[218:221], v[2:5]
	v_mfma_f32_16x16x32_bf16 v[10:13], v[150:153], v[214:217], v[10:13]
	v_mfma_f32_16x16x32_bf16 v[10:13], v[154:157], v[218:221], v[10:13]
	s_barrier
	s_setprio 0
	s_add_i32 s52, s52, 2
	s_addk_i32 s50, 0x100
	s_addk_i32 s51, 0x100
	s_cmp_gt_u32 s52, 29
	s_cbranch_scc0 .LBB0_223
	s_and_b64 vcc, exec, s[46:47]
	s_cbranch_vccz .LBB0_226
	s_barrier

; #define PG8_STAGEX(rs, bufoff, soff, voff) do { _Pragma("unroll") for (int _i = 0; _i < 2; ++_i) \
;         __builtin_amdgcn_raw_ptr_buffer_load_lds(rs, (LAS unsigned*)(lds + (bufoff) + ldsw + _i * 8192), 16, (voff)[_i], (soff), 0, 0); } while (0)
; #define PG8_LDA(dst, b, h) do { _Pragma("unroll") for (int m = 0; m < 4; ++m) _Pragma("unroll") for (int k = 0; k < 2; ++k) dst[m][k] = *(const LAS bf16x8*)(lds + PG8_SA(b, h) + aoff + m * 2048 + k * 1024); } while (0)
; #define PG8_LDB(dst, b, h) do { _Pragma("unroll") for (int n = 0; n < 2; ++n) _Pragma("unroll") for (int k = 0; k < 2; ++k) dst[n][k] = *(const LAS bf16x8*)(lds + PG8_SB(b, h) + boff + n * 2048 + k * 1024); } while (0)
; #define PG8_WAIT_V(n) asm volatile("s_waitcnt vmcnt(" #n ")" ::: "memory")
; #define PG8_WAIT_L(n) asm volatile("s_waitcnt lgkmcnt(" #n ")" ::: "memory")
; #define PG8_BAR __builtin_amdgcn_s_barrier()
; #define PG8_SCHED __builtin_amdgcn_sched_barrier(0)
;     ...
;             for (int t = 0; t < nt; t += 2) {
;                 const bool last = (t == nt - 2);
;                 const unsigned a1 = cA + (unsigned)(t + 1) * kstep;
;                 const unsigned a2 = last ? nA : cA + (unsigned)(t + 2) * kstep, b2 = last ? nB : cB + (unsigned)(t + 2) * kstep;
;                 const unsigned a3 = a2 + kstep, b3 = b2 + kstep;
;                 if (w0) { PG8_LDB(B0, 0, 0); PG8_LDB(B1, 0, 1); PG8_SCHED; PG8_LDA(At, 0, 0); }
;                 PG8_WAIT_L(0); PG8_BAR; if (w0) { PG8_MMA(0, 0, At, B0); PG8_MMA(0, 1, At, B1); } PG8_BAR; PG8_SCHED;
;                 PG8_STAGEX(rsB, PG8_SB(0, 0), b2, voffB); PG8_STAGEX(rsB, PG8_SB(0, 1), b2 + hstepB, voffB); PG8_STAGEX(rsA, PG8_SA(0, 0), a2, voffA);
;                 PG8_WAIT_V(6); PG8_BAR; PG8_BAR; PG8_SCHED;
.LBB0_240:
	v_add_u32_e32 v86, 0x10000, v72
	v_add_u32_e32 v102, 0x14000, v72
	ds_read_b128 v[74:77], v86
	ds_read_b128 v[78:81], v86 offset:1024
	ds_read_b128 v[82:85], v86 offset:2048
	ds_read_b128 v[86:89], v86 offset:3072
	ds_read_b128 v[90:93], v102
	ds_read_b128 v[94:97], v102 offset:1024
	ds_read_b128 v[98:101], v102 offset:2048
	ds_read_b128 v[102:105], v102 offset:3072
	s_cmp_lg_u32 s27, 28
	s_cselect_b32 s28, s26, 0
	s_add_i32 s29, s28, s17
	s_or_b32 s30, s29, 0x80
	s_add_i32 s28, s28, s11
	ds_read_b128 v[106:109], v73
	ds_read_b128 v[110:113], v73 offset:1024
	ds_read_b128 v[114:117], v73 offset:2048
	ds_read_b128 v[118:121], v73 offset:3072
	ds_read_b128 v[122:125], v73 offset:4096
	ds_read_b128 v[126:129], v73 offset:5120
	ds_read_b128 v[130:133], v73 offset:6144
	ds_read_b128 v[134:137], v73 offset:7168
	s_waitcnt lgkmcnt(0)
	s_setprio 1
	s_barrier
	v_mfma_f32_16x16x32_bf16 v[62:65], v[74:77], v[106:109], v[62:65]
	v_mfma_f32_16x16x32_bf16 v[62:65], v[78:81], v[110:113], v[62:65]
	v_mfma_f32_16x16x32_bf16 v[58:61], v[82:85], v[106:109], v[58:61]
	v_mfma_f32_16x16x32_bf16 v[58:61], v[86:89], v[110:113], v[58:61]
	v_mfma_f32_16x16x32_bf16 v[38:41], v[82:85], v[114:117], v[38:41]
	v_mfma_f32_16x16x32_bf16 v[38:41], v[86:89], v[118:121], v[38:41]
	v_mfma_f32_16x16x32_bf16 v[54:57], v[74:77], v[114:117], v[54:57]
	v_mfma_f32_16x16x32_bf16 v[54:57], v[78:81], v[118:121], v[54:57]
	v_mfma_f32_16x16x32_bf16 v[30:33], v[74:77], v[122:125], v[30:33]
	v_mfma_f32_16x16x32_bf16 v[30:33], v[78:81], v[126:129], v[30:33]
	v_mfma_f32_16x16x32_bf16 v[22:25], v[82:85], v[122:125], v[22:25]
	v_mfma_f32_16x16x32_bf16 v[22:25], v[86:89], v[126:129], v[22:25]
	v_mfma_f32_16x16x32_bf16 v[6:9], v[82:85], v[130:133], v[6:9]
	v_mfma_f32_16x16x32_bf16 v[6:9], v[86:89], v[134:137], v[6:9]
	v_mfma_f32_16x16x32_bf16 v[14:17], v[74:77], v[130:133], v[14:17]
	v_mfma_f32_16x16x32_bf16 v[14:17], v[78:81], v[134:137], v[14:17]
	v_mfma_f32_16x16x32_bf16 v[50:53], v[90:93], v[106:109], v[50:53]
	v_mfma_f32_16x16x32_bf16 v[50:53], v[94:97], v[110:113], v[50:53]
	v_mfma_f32_16x16x32_bf16 v[46:49], v[98:101], v[106:109], v[46:49]
	v_mfma_f32_16x16x32_bf16 v[46:49], v[102:105], v[110:113], v[46:49]
	v_mfma_f32_16x16x32_bf16 v[34:37], v[98:101], v[114:117], v[34:37]
	v_mfma_f32_16x16x32_bf16 v[34:37], v[102:105], v[118:121], v[34:37]
	v_mfma_f32_16x16x32_bf16 v[42:45], v[90:93], v[114:117], v[42:45]
	v_mfma_f32_16x16x32_bf16 v[42:45], v[94:97], v[118:121], v[42:45]
	v_mfma_f32_16x16x32_bf16 v[26:29], v[90:93], v[122:125], v[26:29]
	v_mfma_f32_16x16x32_bf16 v[26:29], v[94:97], v[126:129], v[26:29]
	v_mfma_f32_16x16x32_bf16 v[18:21], v[98:101], v[122:125], v[18:21]
	v_mfma_f32_16x16x32_bf16 v[18:21], v[102:105], v[126:129], v[18:21]
	v_mfma_f32_16x16x32_bf16 v[2:5], v[98:101], v[130:133], v[2:5]
	v_mfma_f32_16x16x32_bf16 v[2:5], v[102:105], v[134:137], v[2:5]
	v_mfma_f32_16x16x32_bf16 v[10:13], v[90:93], v[130:133], v[10:13]
	v_mfma_f32_16x16x32_bf16 v[10:13], v[94:97], v[134:137], v[10:13]
	s_barrier
	s_setprio 0
	s_mov_b32 m0, s13
	s_mov_b32 s42, s78
	s_mov_b32 s43, s79
	buffer_load_dwordx4 v67, s[40:43], s28 offen lds
	s_mov_b32 m0, s14
	s_add_i32 s31, s28, 0x80000
	buffer_load_dwordx4 v69, s[40:43], s28 offen lds
	s_mov_b32 m0, s15
	s_nop 0
	buffer_load_dwordx4 v67, s[40:43], s31 offen lds
	s_mov_b32 m0, s16
	s_nop 0
	buffer_load_dwordx4 v69, s[40:43], s31 offen lds
	s_mov_b32 m0, s12
	s_nop 0
	buffer_load_dwordx4 v66, s[76:79], s29 offen lds
	s_mov_b32 m0, s18
	s_nop 0
	buffer_load_dwordx4 v68, s[76:79], s29 offen lds
	s_waitcnt vmcnt(6)
	s_barrier
	s_barrier
; #define PG8_STAGEX(rs, bufoff, soff, voff) do { _Pragma("unroll") for (int _i = 0; _i < 2; ++_i) \
;         __builtin_amdgcn_raw_ptr_buffer_load_lds(rs, (LAS unsigned*)(lds + (bufoff) + ldsw + _i * 8192), 16, (voff)[_i], (soff), 0, 0); } while (0)
; #define PG8_LDA(dst, b, h) do { _Pragma("unroll") for (int m = 0; m < 4; ++m) _Pragma("unroll") for (int k = 0; k < 2; ++k) dst[m][k] = *(const LAS bf16x8*)(lds + PG8_SA(b, h) + aoff + m * 2048 + k * 1024); } while (0)
; #define PG8_LDB(dst, b, h) do { _Pragma("unroll") for (int n = 0; n < 2; ++n) _Pragma("unroll") for (int k = 0; k < 2; ++k) dst[n][k] = *(const LAS bf16x8*)(lds + PG8_SB(b, h) + boff + n * 2048 + k * 1024); } while (0)
; #define PG8_WAIT_V(n) asm volatile("s_waitcnt vmcnt(" #n ")" ::: "memory")
; #define PG8_WAIT_L(n) asm volatile("s_waitcnt lgkmcnt(" #n ")" ::: "memory")
; #define PG8_BAR __builtin_amdgcn_s_barrier()
; #define PG8_SCHED __builtin_amdgcn_sched_barrier(0)
;     ...
;                 if (w0) { PG8_LDB(B0, 1, 0); PG8_LDB(B1, 1, 1); PG8_SCHED; PG8_LDA(At, 1, 0); }
;                 PG8_WAIT_L(0); PG8_BAR; if (w0) { PG8_MMA(0, 0, At, B0); PG8_MMA(0, 1, At, B1); } PG8_BAR; PG8_SCHED;
;                 PG8_STAGEX(rsB, PG8_SB(1, 0), b3, voffB); PG8_STAGEX(rsB, PG8_SB(1, 1), b3 + hstepB, voffB); PG8_STAGEX(rsA, PG8_SA(1, 0), a3, voffA);
;                 PG8_WAIT_V(6); PG8_BAR; PG8_BAR; PG8_SCHED;
;             }
;         }
;         if (wr == 0) PG8_BAR;
	v_add_u32_e32 v86, 0x18000, v72
	v_add_u32_e32 v102, 0x1c000, v72
	ds_read_b128 v[74:77], v86
	ds_read_b128 v[78:81], v86 offset:1024
	ds_read_b128 v[82:85], v86 offset:2048
	ds_read_b128 v[86:89], v86 offset:3072
	ds_read_b128 v[90:93], v102
	ds_read_b128 v[94:97], v102 offset:1024
	ds_read_b128 v[98:101], v102 offset:2048
	ds_read_b128 v[102:105], v102 offset:3072
	ds_read_b128 v[106:109], v73 offset:32768
	ds_read_b128 v[110:113], v73 offset:33792
	ds_read_b128 v[114:117], v73 offset:34816
	ds_read_b128 v[118:121], v73 offset:35840
	ds_read_b128 v[122:125], v73 offset:36864
	ds_read_b128 v[126:129], v73 offset:37888
	ds_read_b128 v[130:133], v73 offset:38912
	ds_read_b128 v[134:137], v73 offset:39936
	s_waitcnt lgkmcnt(0)
	s_setprio 1
	s_barrier
	v_mfma_f32_16x16x32_bf16 v[62:65], v[74:77], v[106:109], v[62:65]
	v_mfma_f32_16x16x32_bf16 v[58:61], v[82:85], v[106:109], v[58:61]
	v_mfma_f32_16x16x32_bf16 v[54:57], v[74:77], v[114:117], v[54:57]
	v_mfma_f32_16x16x32_bf16 v[38:41], v[82:85], v[114:117], v[38:41]
	v_mfma_f32_16x16x32_bf16 v[30:33], v[74:77], v[122:125], v[30:33]
	v_mfma_f32_16x16x32_bf16 v[22:25], v[82:85], v[122:125], v[22:25]
	v_mfma_f32_16x16x32_bf16 v[14:17], v[74:77], v[130:133], v[14:17]
	v_mfma_f32_16x16x32_bf16 v[6:9], v[82:85], v[130:133], v[6:9]
	v_mfma_f32_16x16x32_bf16 v[62:65], v[78:81], v[110:113], v[62:65]
	v_mfma_f32_16x16x32_bf16 v[58:61], v[86:89], v[110:113], v[58:61]
	v_mfma_f32_16x16x32_bf16 v[54:57], v[78:81], v[118:121], v[54:57]
	v_mfma_f32_16x16x32_bf16 v[38:41], v[86:89], v[118:121], v[38:41]
	v_mfma_f32_16x16x32_bf16 v[30:33], v[78:81], v[126:129], v[30:33]
	v_mfma_f32_16x16x32_bf16 v[22:25], v[86:89], v[126:129], v[22:25]
	v_mfma_f32_16x16x32_bf16 v[14:17], v[78:81], v[134:137], v[14:17]
	v_mfma_f32_16x16x32_bf16 v[6:9], v[86:89], v[134:137], v[6:9]
	v_mfma_f32_16x16x32_bf16 v[50:53], v[90:93], v[106:109], v[50:53]
	s_or_b32 s29, s28, 0x80
	v_mfma_f32_16x16x32_bf16 v[46:49], v[98:101], v[106:109], v[46:49]
	v_mfma_f32_16x16x32_bf16 v[42:45], v[90:93], v[114:117], v[42:45]
	v_mfma_f32_16x16x32_bf16 v[34:37], v[98:101], v[114:117], v[34:37]
	v_mfma_f32_16x16x32_bf16 v[26:29], v[90:93], v[122:125], v[26:29]
	v_mfma_f32_16x16x32_bf16 v[18:21], v[98:101], v[122:125], v[18:21]
	v_mfma_f32_16x16x32_bf16 v[10:13], v[90:93], v[130:133], v[10:13]
	v_mfma_f32_16x16x32_bf16 v[2:5], v[98:101], v[130:133], v[2:5]
	v_mfma_f32_16x16x32_bf16 v[50:53], v[94:97], v[110:113], v[50:53]
	v_mfma_f32_16x16x32_bf16 v[46:49], v[102:105], v[110:113], v[46:49]
	v_mfma_f32_16x16x32_bf16 v[42:45], v[94:97], v[118:121], v[42:45]
	v_mfma_f32_16x16x32_bf16 v[34:37], v[102:105], v[118:121], v[34:37]
	v_mfma_f32_16x16x32_bf16 v[26:29], v[94:97], v[126:129], v[26:29]
	v_mfma_f32_16x16x32_bf16 v[18:21], v[102:105], v[126:129], v[18:21]
	v_mfma_f32_16x16x32_bf16 v[10:13], v[94:97], v[134:137], v[10:13]
	v_mfma_f32_16x16x32_bf16 v[2:5], v[102:105], v[134:137], v[2:5]
	s_barrier
	s_setprio 0
	s_mov_b32 m0, s20
	s_add_i32 s28, s28, 0x80080
	buffer_load_dwordx4 v67, s[40:43], s29 offen lds
	s_mov_b32 m0, s21
	s_nop 0
	buffer_load_dwordx4 v69, s[40:43], s29 offen lds
	s_mov_b32 m0, s24
	s_nop 0
	buffer_load_dwordx4 v67, s[40:43], s28 offen lds
	s_mov_b32 m0, s25
	s_nop 0
	buffer_load_dwordx4 v69, s[40:43], s28 offen lds
	s_mov_b32 m0, s22
	s_nop 0
	buffer_load_dwordx4 v66, s[76:79], s30 offen lds
	s_mov_b32 m0, s23
	s_nop 0
	buffer_load_dwordx4 v68, s[76:79], s30 offen lds
	s_waitcnt vmcnt(6)
	s_barrier
	s_barrier
	s_addk_i32 s26, 0x100
	s_add_i32 s27, s27, 2
	s_cmp_gt_u32 s27, 29
	s_cbranch_scc0 .LBB0_240
	s_cmpk_lt_u32 s8, 0x100
	s_cbranch_scc0 .LBB0_243
	s_barrier

; #define PG8_STAGEX(rs, bufoff, soff, voff) do { _Pragma("unroll") for (int _i = 0; _i < 2; ++_i) \
;         __builtin_amdgcn_raw_ptr_buffer_load_lds(rs, (LAS unsigned*)(lds + (bufoff) + ldsw + _i * 8192), 16, (voff)[_i], (soff), 0, 0); } while (0)
; #define PG8_LDA(dst, b, h) do { _Pragma("unroll") for (int m = 0; m < 4; ++m) _Pragma("unroll") for (int k = 0; k < 2; ++k) dst[m][k] = *(const LAS bf16x8*)(lds + PG8_SA(b, h) + aoff + m * 2048 + k * 1024); } while (0)
; #define PG8_LDB(dst, b, h) do { _Pragma("unroll") for (int n = 0; n < 2; ++n) _Pragma("unroll") for (int k = 0; k < 2; ++k) dst[n][k] = *(const LAS bf16x8*)(lds + PG8_SB(b, h) + boff + n * 2048 + k * 1024); } while (0)
; #define PG8_WAIT_V(n) asm volatile("s_waitcnt vmcnt(" #n ")" ::: "memory")
; #define PG8_WAIT_L(n) asm volatile("s_waitcnt lgkmcnt(" #n ")" ::: "memory")
; #define PG8_BAR __builtin_amdgcn_s_barrier()
; #define PG8_SCHED __builtin_amdgcn_sched_barrier(0)
;     ...
;         for (int t = 0; t < nt; t += 2) {
;             const bool last = (t == nt - 2);
;             const unsigned a1 = cA + (unsigned)(t + 1) * kstep;
;             const unsigned a2 = last ? nA : cA + (unsigned)(t + 2) * kstep, b2 = last ? nB : cB + (unsigned)(t + 2) * kstep;
;             const unsigned a3 = a2 + kstep, b3 = b2 + kstep;
;             PG8_LDB(B0, 0, 0); PG8_LDB(B1, 0, 1); PG8_SCHED; PG8_LDA(At, 0, 0); PG8_STAGEX(rsA, PG8_SA(1, 1), a1 + hstepA, voffA);
;             PG8_WAIT_V(8); PG8_WAIT_L(0); PG8_BAR; PG8_MMA(0, 0, At, B0); PG8_MMA(0, 1, At, B1); PG8_BAR; PG8_SCHED;
;             PG8_LDA(At, 0, 1); PG8_STAGEX(rsB, PG8_SB(0, 0), b2, voffB); PG8_STAGEX(rsB, PG8_SB(0, 1), b2 + hstepB, voffB); PG8_STAGEX(rsA, PG8_SA(0, 0), a2, voffA);
;             PG8_WAIT_V(8); PG8_WAIT_L(0); PG8_BAR; PG8_MMA(1, 0, At, B0); PG8_MMA(1, 1, At, B1); PG8_BAR; PG8_SCHED;
.LBB0_323:
	v_add_u32_e32 v118, 0x10000, v210
	v_add_u32_e32 v160, 0x14000, v210
	ds_read_b128 v[106:109], v118
	ds_read_b128 v[110:113], v118 offset:1024
	ds_read_b128 v[114:117], v118 offset:2048
	ds_read_b128 v[118:121], v118 offset:3072
	ds_read_b128 v[122:125], v160
	ds_read_b128 v[134:137], v160 offset:1024
	ds_read_b128 v[156:159], v160 offset:2048
	ds_read_b128 v[160:163], v160 offset:3072
	s_add_i32 s42, s51, 0xffea8080
	s_cmpk_eq_i32 s58, 0x52
	s_cselect_b32 s61, s30, s42
	s_cselect_b32 s60, s31, s57
	s_or_b32 s59, s61, 0x80
	s_mov_b32 m0, s68
	ds_read_b128 v[164:167], v211
	ds_read_b128 v[168:171], v211 offset:1024
	ds_read_b128 v[182:185], v211 offset:2048
	ds_read_b128 v[186:189], v211 offset:3072
	ds_read_b128 v[190:193], v211 offset:4096
	ds_read_b128 v[194:197], v211 offset:5120
	ds_read_b128 v[198:201], v211 offset:6144
	ds_read_b128 v[202:205], v211 offset:7168
	buffer_load_dwordx4 v178, s[76:79], s51 offen lds
	s_mov_b32 m0, s69
	s_nop 0
	buffer_load_dwordx4 v206, s[76:79], s51 offen lds
	s_waitcnt vmcnt(8)
	s_waitcnt lgkmcnt(0)
	s_setprio 1
	s_barrier
	v_mfma_f32_16x16x32_bf16 v[150:153], v[106:109], v[164:167], v[150:153]
	v_mfma_f32_16x16x32_bf16 v[150:153], v[110:113], v[168:171], v[150:153]
	v_mfma_f32_16x16x32_bf16 v[146:149], v[114:117], v[164:167], v[146:149]
	v_mfma_f32_16x16x32_bf16 v[146:149], v[118:121], v[168:171], v[146:149]
	v_mfma_f32_16x16x32_bf16 v[138:141], v[114:117], v[182:185], v[138:141]
	v_mfma_f32_16x16x32_bf16 v[138:141], v[118:121], v[186:189], v[138:141]
	v_mfma_f32_16x16x32_bf16 v[142:145], v[106:109], v[182:185], v[142:145]
	v_mfma_f32_16x16x32_bf16 v[142:145], v[110:113], v[186:189], v[142:145]
	v_mfma_f32_16x16x32_bf16 v[130:133], v[106:109], v[190:193], v[130:133]
	v_mfma_f32_16x16x32_bf16 v[130:133], v[110:113], v[194:197], v[130:133]
	v_mfma_f32_16x16x32_bf16 v[126:129], v[114:117], v[190:193], v[126:129]
	v_mfma_f32_16x16x32_bf16 v[126:129], v[118:121], v[194:197], v[126:129]
	v_mfma_f32_16x16x32_bf16 v[98:101], v[114:117], v[198:201], v[98:101]
	v_mfma_f32_16x16x32_bf16 v[98:101], v[118:121], v[202:205], v[98:101]
	v_mfma_f32_16x16x32_bf16 v[102:105], v[106:109], v[198:201], v[102:105]
	v_mfma_f32_16x16x32_bf16 v[102:105], v[110:113], v[202:205], v[102:105]
	v_mfma_f32_16x16x32_bf16 v[62:65], v[122:125], v[164:167], v[62:65]
	v_mfma_f32_16x16x32_bf16 v[62:65], v[134:137], v[168:171], v[62:65]
	v_mfma_f32_16x16x32_bf16 v[58:61], v[156:159], v[164:167], v[58:61]
	v_mfma_f32_16x16x32_bf16 v[58:61], v[160:163], v[168:171], v[58:61]
	v_mfma_f32_16x16x32_bf16 v[50:53], v[156:159], v[182:185], v[50:53]
	v_mfma_f32_16x16x32_bf16 v[50:53], v[160:163], v[186:189], v[50:53]
	v_mfma_f32_16x16x32_bf16 v[54:57], v[122:125], v[182:185], v[54:57]
	v_mfma_f32_16x16x32_bf16 v[54:57], v[134:137], v[186:189], v[54:57]
	v_mfma_f32_16x16x32_bf16 v[46:49], v[122:125], v[190:193], v[46:49]
	v_mfma_f32_16x16x32_bf16 v[46:49], v[134:137], v[194:197], v[46:49]
	v_mfma_f32_16x16x32_bf16 v[42:45], v[156:159], v[190:193], v[42:45]
	v_mfma_f32_16x16x32_bf16 v[42:45], v[160:163], v[194:197], v[42:45]
	v_mfma_f32_16x16x32_bf16 v[34:37], v[156:159], v[198:201], v[34:37]
	v_mfma_f32_16x16x32_bf16 v[34:37], v[160:163], v[202:205], v[34:37]
	v_mfma_f32_16x16x32_bf16 v[38:41], v[122:125], v[198:201], v[38:41]
	v_mfma_f32_16x16x32_bf16 v[38:41], v[134:137], v[202:205], v[38:41]
	s_barrier
	s_setprio 0
	s_mov_b32 m0, s15
	s_mov_b32 s42, s78
	s_mov_b32 s43, s79
	ds_read_b128 v[164:167], v211 offset:16384
	ds_read_b128 v[168:171], v211 offset:17408
	ds_read_b128 v[182:185], v211 offset:18432
	ds_read_b128 v[186:189], v211 offset:19456
	ds_read_b128 v[190:193], v211 offset:20480
	ds_read_b128 v[194:197], v211 offset:21504
	ds_read_b128 v[198:201], v211 offset:22528
	ds_read_b128 v[202:205], v211 offset:23552
	buffer_load_dwordx4 v179, s[40:43], s60 offen lds
	s_mov_b32 m0, s16
	s_add_i32 s62, s60, 0x158000
	buffer_load_dwordx4 v207, s[40:43], s60 offen lds
	s_mov_b32 m0, s17
	s_nop 0
	buffer_load_dwordx4 v179, s[40:43], s62 offen lds
	s_mov_b32 m0, s18
	s_nop 0
	buffer_load_dwordx4 v207, s[40:43], s62 offen lds
	s_mov_b32 m0, s14
	s_nop 0
	buffer_load_dwordx4 v178, s[76:79], s61 offen lds
	s_mov_b32 m0, s19
	s_nop 0
	buffer_load_dwordx4 v206, s[76:79], s61 offen lds
	s_waitcnt vmcnt(8)
	s_waitcnt lgkmcnt(0)
	s_setprio 1
	s_barrier
	v_mfma_f32_16x16x32_bf16 v[94:97], v[106:109], v[164:167], v[94:97]
	v_mfma_f32_16x16x32_bf16 v[94:97], v[110:113], v[168:171], v[94:97]
	v_mfma_f32_16x16x32_bf16 v[90:93], v[114:117], v[164:167], v[90:93]
	v_mfma_f32_16x16x32_bf16 v[90:93], v[118:121], v[168:171], v[90:93]
	v_mfma_f32_16x16x32_bf16 v[82:85], v[114:117], v[182:185], v[82:85]
	v_mfma_f32_16x16x32_bf16 v[82:85], v[118:121], v[186:189], v[82:85]
	v_mfma_f32_16x16x32_bf16 v[86:89], v[106:109], v[182:185], v[86:89]
	v_mfma_f32_16x16x32_bf16 v[86:89], v[110:113], v[186:189], v[86:89]
	v_mfma_f32_16x16x32_bf16 v[78:81], v[106:109], v[190:193], v[78:81]
	v_mfma_f32_16x16x32_bf16 v[78:81], v[110:113], v[194:197], v[78:81]
	v_mfma_f32_16x16x32_bf16 v[74:77], v[114:117], v[190:193], v[74:77]
	v_mfma_f32_16x16x32_bf16 v[74:77], v[118:121], v[194:197], v[74:77]
	v_mfma_f32_16x16x32_bf16 v[66:69], v[114:117], v[198:201], v[66:69]
	v_mfma_f32_16x16x32_bf16 v[66:69], v[118:121], v[202:205], v[66:69]
	v_mfma_f32_16x16x32_bf16 v[70:73], v[106:109], v[198:201], v[70:73]
	v_mfma_f32_16x16x32_bf16 v[70:73], v[110:113], v[202:205], v[70:73]
	v_mfma_f32_16x16x32_bf16 v[30:33], v[122:125], v[164:167], v[30:33]
	v_mfma_f32_16x16x32_bf16 v[30:33], v[134:137], v[168:171], v[30:33]
	v_mfma_f32_16x16x32_bf16 v[26:29], v[156:159], v[164:167], v[26:29]
	v_mfma_f32_16x16x32_bf16 v[26:29], v[160:163], v[168:171], v[26:29]
	v_mfma_f32_16x16x32_bf16 v[18:21], v[156:159], v[182:185], v[18:21]
	v_mfma_f32_16x16x32_bf16 v[18:21], v[160:163], v[186:189], v[18:21]
	v_mfma_f32_16x16x32_bf16 v[22:25], v[122:125], v[182:185], v[22:25]
	v_mfma_f32_16x16x32_bf16 v[22:25], v[134:137], v[186:189], v[22:25]
	v_mfma_f32_16x16x32_bf16 v[14:17], v[122:125], v[190:193], v[14:17]
	v_mfma_f32_16x16x32_bf16 v[14:17], v[134:137], v[194:197], v[14:17]
	v_mfma_f32_16x16x32_bf16 v[10:13], v[156:159], v[190:193], v[10:13]
	v_mfma_f32_16x16x32_bf16 v[10:13], v[160:163], v[194:197], v[10:13]
	v_mfma_f32_16x16x32_bf16 v[2:5], v[156:159], v[198:201], v[2:5]
	v_mfma_f32_16x16x32_bf16 v[2:5], v[160:163], v[202:205], v[2:5]
	v_mfma_f32_16x16x32_bf16 v[6:9], v[122:125], v[198:201], v[6:9]
	v_mfma_f32_16x16x32_bf16 v[6:9], v[134:137], v[202:205], v[6:9]
	s_barrier
; #define PG8_STAGEX(rs, bufoff, soff, voff) do { _Pragma("unroll") for (int _i = 0; _i < 2; ++_i) \
;         __builtin_amdgcn_raw_ptr_buffer_load_lds(rs, (LAS unsigned*)(lds + (bufoff) + ldsw + _i * 8192), 16, (voff)[_i], (soff), 0, 0); } while (0)
; #define PG8_LDA(dst, b, h) do { _Pragma("unroll") for (int m = 0; m < 4; ++m) _Pragma("unroll") for (int k = 0; k < 2; ++k) dst[m][k] = *(const LAS bf16x8*)(lds + PG8_SA(b, h) + aoff + m * 2048 + k * 1024); } while (0)
; #define PG8_LDB(dst, b, h) do { _Pragma("unroll") for (int n = 0; n < 2; ++n) _Pragma("unroll") for (int k = 0; k < 2; ++k) dst[n][k] = *(const LAS bf16x8*)(lds + PG8_SB(b, h) + boff + n * 2048 + k * 1024); } while (0)
; #define PG8_WAIT_V(n) asm volatile("s_waitcnt vmcnt(" #n ")" ::: "memory")
; #define PG8_WAIT_L(n) asm volatile("s_waitcnt lgkmcnt(" #n ")" ::: "memory")
; #define PG8_BAR __builtin_amdgcn_s_barrier()
; #define PG8_SCHED __builtin_amdgcn_sched_barrier(0)
;     ...
;             PG8_LDB(B0, 1, 0); PG8_LDB(B1, 1, 1); PG8_SCHED; PG8_LDA(At, 1, 0); PG8_STAGEX(rsA, PG8_SA(0, 1), a2 + hstepA, voffA);
;             PG8_WAIT_V(8); PG8_WAIT_L(0); PG8_BAR; PG8_MMA(0, 0, At, B0); PG8_MMA(0, 1, At, B1); PG8_BAR; PG8_SCHED;
;             PG8_LDA(At, 1, 1); PG8_STAGEX(rsB, PG8_SB(1, 0), b3, voffB); PG8_STAGEX(rsB, PG8_SB(1, 1), b3 + hstepB, voffB); PG8_STAGEX(rsA, PG8_SA(1, 0), a3, voffA);
;             PG8_WAIT_V(8); PG8_WAIT_L(0); PG8_BAR; PG8_MMA(1, 0, At, B0); PG8_MMA(1, 1, At, B1); PG8_BAR; PG8_SCHED;
;         }
	s_setprio 0
	v_add_u32_e32 v118, 0x18000, v210
	v_add_u32_e32 v160, 0x1c000, v210
	ds_read_b128 v[106:109], v118
	ds_read_b128 v[110:113], v118 offset:1024
	ds_read_b128 v[114:117], v118 offset:2048
	ds_read_b128 v[118:121], v118 offset:3072
	ds_read_b128 v[122:125], v160
	ds_read_b128 v[134:137], v160 offset:1024
	ds_read_b128 v[156:159], v160 offset:2048
	ds_read_b128 v[160:163], v160 offset:3072
	s_add_i32 s61, s61, 0x158000
	s_mov_b32 m0, s20
	ds_read_b128 v[164:167], v211 offset:32768
	ds_read_b128 v[168:171], v211 offset:33792
	ds_read_b128 v[182:185], v211 offset:34816
	ds_read_b128 v[186:189], v211 offset:35840
	ds_read_b128 v[190:193], v211 offset:36864
	ds_read_b128 v[194:197], v211 offset:37888
	ds_read_b128 v[198:201], v211 offset:38912
	ds_read_b128 v[202:205], v211 offset:39936
	buffer_load_dwordx4 v178, s[76:79], s61 offen lds
	s_mov_b32 m0, s21
	s_nop 0
	buffer_load_dwordx4 v206, s[76:79], s61 offen lds
	s_waitcnt vmcnt(8)
	s_waitcnt lgkmcnt(0)
	s_setprio 1
	s_barrier
	v_mfma_f32_16x16x32_bf16 v[150:153], v[106:109], v[164:167], v[150:153]
	v_mfma_f32_16x16x32_bf16 v[150:153], v[110:113], v[168:171], v[150:153]
	v_mfma_f32_16x16x32_bf16 v[146:149], v[114:117], v[164:167], v[146:149]
	v_mfma_f32_16x16x32_bf16 v[146:149], v[118:121], v[168:171], v[146:149]
	v_mfma_f32_16x16x32_bf16 v[138:141], v[114:117], v[182:185], v[138:141]
	v_mfma_f32_16x16x32_bf16 v[138:141], v[118:121], v[186:189], v[138:141]
	v_mfma_f32_16x16x32_bf16 v[142:145], v[106:109], v[182:185], v[142:145]
	v_mfma_f32_16x16x32_bf16 v[142:145], v[110:113], v[186:189], v[142:145]
	v_mfma_f32_16x16x32_bf16 v[130:133], v[106:109], v[190:193], v[130:133]
	v_mfma_f32_16x16x32_bf16 v[130:133], v[110:113], v[194:197], v[130:133]
	v_mfma_f32_16x16x32_bf16 v[126:129], v[114:117], v[190:193], v[126:129]
	v_mfma_f32_16x16x32_bf16 v[126:129], v[118:121], v[194:197], v[126:129]
	v_mfma_f32_16x16x32_bf16 v[98:101], v[114:117], v[198:201], v[98:101]
	v_mfma_f32_16x16x32_bf16 v[98:101], v[118:121], v[202:205], v[98:101]
	v_mfma_f32_16x16x32_bf16 v[102:105], v[106:109], v[198:201], v[102:105]
	v_mfma_f32_16x16x32_bf16 v[102:105], v[110:113], v[202:205], v[102:105]
	v_mfma_f32_16x16x32_bf16 v[62:65], v[122:125], v[164:167], v[62:65]
	v_mfma_f32_16x16x32_bf16 v[62:65], v[134:137], v[168:171], v[62:65]
	v_mfma_f32_16x16x32_bf16 v[58:61], v[156:159], v[164:167], v[58:61]
	v_mfma_f32_16x16x32_bf16 v[58:61], v[160:163], v[168:171], v[58:61]
	v_mfma_f32_16x16x32_bf16 v[50:53], v[156:159], v[182:185], v[50:53]
	v_mfma_f32_16x16x32_bf16 v[50:53], v[160:163], v[186:189], v[50:53]
	v_mfma_f32_16x16x32_bf16 v[54:57], v[122:125], v[182:185], v[54:57]
	v_mfma_f32_16x16x32_bf16 v[54:57], v[134:137], v[186:189], v[54:57]
	v_mfma_f32_16x16x32_bf16 v[46:49], v[122:125], v[190:193], v[46:49]
	v_mfma_f32_16x16x32_bf16 v[46:49], v[134:137], v[194:197], v[46:49]
	v_mfma_f32_16x16x32_bf16 v[42:45], v[156:159], v[190:193], v[42:45]
	v_mfma_f32_16x16x32_bf16 v[42:45], v[160:163], v[194:197], v[42:45]
	v_mfma_f32_16x16x32_bf16 v[34:37], v[156:159], v[198:201], v[34:37]
	v_mfma_f32_16x16x32_bf16 v[34:37], v[160:163], v[202:205], v[34:37]
	v_mfma_f32_16x16x32_bf16 v[38:41], v[122:125], v[198:201], v[38:41]
	v_mfma_f32_16x16x32_bf16 v[38:41], v[134:137], v[202:205], v[38:41]
	s_barrier
	s_setprio 0
	s_mov_b32 m0, s28
	s_or_b32 s61, s60, 0x80
	ds_read_b128 v[164:167], v211 offset:49152
	ds_read_b128 v[168:171], v211 offset:50176
	ds_read_b128 v[182:185], v211 offset:51200
	ds_read_b128 v[186:189], v211 offset:52224
	ds_read_b128 v[190:193], v211 offset:53248
	ds_read_b128 v[194:197], v211 offset:54272
	ds_read_b128 v[198:201], v211 offset:55296
	ds_read_b128 v[202:205], v211 offset:56320
	buffer_load_dwordx4 v179, s[40:43], s61 offen lds
	s_mov_b32 m0, s29
	s_add_i32 s60, s60, 0x158080
	buffer_load_dwordx4 v207, s[40:43], s61 offen lds
	s_mov_b32 m0, s66
	s_nop 0
	buffer_load_dwordx4 v179, s[40:43], s60 offen lds
	s_mov_b32 m0, s67
	s_nop 0
	buffer_load_dwordx4 v207, s[40:43], s60 offen lds
	s_mov_b32 m0, s54
	s_nop 0
	buffer_load_dwordx4 v178, s[76:79], s59 offen lds
	s_mov_b32 m0, s55
	s_nop 0
	buffer_load_dwordx4 v206, s[76:79], s59 offen lds
	s_waitcnt vmcnt(8)
	s_waitcnt lgkmcnt(0)
	s_setprio 1
	s_barrier
	v_mfma_f32_16x16x32_bf16 v[94:97], v[106:109], v[164:167], v[94:97]
	v_mfma_f32_16x16x32_bf16 v[94:97], v[110:113], v[168:171], v[94:97]
	v_mfma_f32_16x16x32_bf16 v[90:93], v[114:117], v[164:167], v[90:93]
	v_mfma_f32_16x16x32_bf16 v[90:93], v[118:121], v[168:171], v[90:93]
	v_mfma_f32_16x16x32_bf16 v[82:85], v[114:117], v[182:185], v[82:85]
	v_mfma_f32_16x16x32_bf16 v[82:85], v[118:121], v[186:189], v[82:85]
	v_mfma_f32_16x16x32_bf16 v[86:89], v[106:109], v[182:185], v[86:89]
	v_mfma_f32_16x16x32_bf16 v[86:89], v[110:113], v[186:189], v[86:89]
	v_mfma_f32_16x16x32_bf16 v[78:81], v[106:109], v[190:193], v[78:81]
	v_mfma_f32_16x16x32_bf16 v[78:81], v[110:113], v[194:197], v[78:81]
	v_mfma_f32_16x16x32_bf16 v[74:77], v[114:117], v[190:193], v[74:77]
	v_mfma_f32_16x16x32_bf16 v[74:77], v[118:121], v[194:197], v[74:77]
	v_mfma_f32_16x16x32_bf16 v[66:69], v[114:117], v[198:201], v[66:69]
	v_mfma_f32_16x16x32_bf16 v[66:69], v[118:121], v[202:205], v[66:69]
	v_mfma_f32_16x16x32_bf16 v[70:73], v[106:109], v[198:201], v[70:73]
	v_mfma_f32_16x16x32_bf16 v[70:73], v[110:113], v[202:205], v[70:73]
	v_mfma_f32_16x16x32_bf16 v[30:33], v[122:125], v[164:167], v[30:33]
	v_mfma_f32_16x16x32_bf16 v[30:33], v[134:137], v[168:171], v[30:33]
	v_mfma_f32_16x16x32_bf16 v[26:29], v[156:159], v[164:167], v[26:29]
	v_mfma_f32_16x16x32_bf16 v[26:29], v[160:163], v[168:171], v[26:29]
	v_mfma_f32_16x16x32_bf16 v[18:21], v[156:159], v[182:185], v[18:21]
	v_mfma_f32_16x16x32_bf16 v[18:21], v[160:163], v[186:189], v[18:21]
	v_mfma_f32_16x16x32_bf16 v[22:25], v[122:125], v[182:185], v[22:25]
	v_mfma_f32_16x16x32_bf16 v[22:25], v[134:137], v[186:189], v[22:25]
	v_mfma_f32_16x16x32_bf16 v[14:17], v[122:125], v[190:193], v[14:17]
	v_mfma_f32_16x16x32_bf16 v[14:17], v[134:137], v[194:197], v[14:17]
	v_mfma_f32_16x16x32_bf16 v[10:13], v[156:159], v[190:193], v[10:13]
	v_mfma_f32_16x16x32_bf16 v[10:13], v[160:163], v[194:197], v[10:13]
	v_mfma_f32_16x16x32_bf16 v[2:5], v[156:159], v[198:201], v[2:5]
	v_mfma_f32_16x16x32_bf16 v[2:5], v[160:163], v[202:205], v[2:5]
	v_mfma_f32_16x16x32_bf16 v[6:9], v[122:125], v[198:201], v[6:9]
	v_mfma_f32_16x16x32_bf16 v[6:9], v[134:137], v[202:205], v[6:9]
	s_barrier
	s_setprio 0
	s_add_i32 s58, s58, 2
	s_addk_i32 s51, 0x100
	s_addk_i32 s57, 0x100
	s_cmpk_gt_u32 s58, 0x53
	s_cbranch_scc0 .LBB0_323
	s_and_b64 vcc, exec, s[48:49]
	s_cbranch_vccz .LBB0_326
	s_barrier

; #define PG8_WAIT_L(n) asm volatile("s_waitcnt lgkmcnt(" #n ")" ::: "memory")
; #define PG8_BAR __builtin_amdgcn_s_barrier()
; #define PG8_SCHED __builtin_amdgcn_sched_barrier(0)
;     ...
;                 PG8_WAIT_L(0); PG8_BAR; if (w0) { PG8_MMA(0, 0, At, B0); PG8_MMA(0, 1, At, B1); } PG8_BAR; PG8_SCHED;
.LBB0_355:
	s_waitcnt lgkmcnt(0)
	s_and_b64 vcc, exec, s[38:39]
	s_barrier
	s_cbranch_vccnz .LBB0_357
	s_setprio 1
	s_waitcnt lgkmcnt(7)
	v_mfma_f32_16x16x32_bf16 v[62:65], v[66:69], v[98:101], v[62:65]
	v_mfma_f32_16x16x32_bf16 v[62:65], v[70:73], v[102:105], v[62:65]
	v_mfma_f32_16x16x32_bf16 v[58:61], v[74:77], v[98:101], v[58:61]
	v_mfma_f32_16x16x32_bf16 v[58:61], v[78:81], v[102:105], v[58:61]
	v_mfma_f32_16x16x32_bf16 v[50:53], v[74:77], v[106:109], v[50:53]
	v_mfma_f32_16x16x32_bf16 v[50:53], v[78:81], v[110:113], v[50:53]
	v_mfma_f32_16x16x32_bf16 v[54:57], v[66:69], v[106:109], v[54:57]
	v_mfma_f32_16x16x32_bf16 v[54:57], v[70:73], v[110:113], v[54:57]
	v_mfma_f32_16x16x32_bf16 v[46:49], v[66:69], v[114:117], v[46:49]
	v_mfma_f32_16x16x32_bf16 v[46:49], v[70:73], v[118:121], v[46:49]
	v_mfma_f32_16x16x32_bf16 v[42:45], v[74:77], v[114:117], v[42:45]
	v_mfma_f32_16x16x32_bf16 v[42:45], v[78:81], v[118:121], v[42:45]
	v_mfma_f32_16x16x32_bf16 v[34:37], v[74:77], v[122:125], v[34:37]
	v_mfma_f32_16x16x32_bf16 v[34:37], v[78:81], v[126:129], v[34:37]
	v_mfma_f32_16x16x32_bf16 v[38:41], v[66:69], v[122:125], v[38:41]
	v_mfma_f32_16x16x32_bf16 v[38:41], v[70:73], v[126:129], v[38:41]
	v_mfma_f32_16x16x32_bf16 v[30:33], v[82:85], v[98:101], v[30:33]
	v_mfma_f32_16x16x32_bf16 v[30:33], v[86:89], v[102:105], v[30:33]
	v_mfma_f32_16x16x32_bf16 v[26:29], v[90:93], v[98:101], v[26:29]
	v_mfma_f32_16x16x32_bf16 v[26:29], v[94:97], v[102:105], v[26:29]
	v_mfma_f32_16x16x32_bf16 v[18:21], v[90:93], v[106:109], v[18:21]
	v_mfma_f32_16x16x32_bf16 v[18:21], v[94:97], v[110:113], v[18:21]
	v_mfma_f32_16x16x32_bf16 v[22:25], v[82:85], v[106:109], v[22:25]
	v_mfma_f32_16x16x32_bf16 v[22:25], v[86:89], v[110:113], v[22:25]
	v_mfma_f32_16x16x32_bf16 v[14:17], v[82:85], v[114:117], v[14:17]
	v_mfma_f32_16x16x32_bf16 v[14:17], v[86:89], v[118:121], v[14:17]
	v_mfma_f32_16x16x32_bf16 v[10:13], v[90:93], v[114:117], v[10:13]
	v_mfma_f32_16x16x32_bf16 v[10:13], v[94:97], v[118:121], v[10:13]
	v_mfma_f32_16x16x32_bf16 v[2:5], v[90:93], v[122:125], v[2:5]
	v_mfma_f32_16x16x32_bf16 v[2:5], v[94:97], v[126:129], v[2:5]
	v_mfma_f32_16x16x32_bf16 v[6:9], v[82:85], v[122:125], v[6:9]
	v_mfma_f32_16x16x32_bf16 v[6:9], v[86:89], v[126:129], v[6:9]
	s_setprio 0

; #define PG8_WAIT_L(n) asm volatile("s_waitcnt lgkmcnt(" #n ")" ::: "memory")
; #define PG8_BAR __builtin_amdgcn_s_barrier()
; #define PG8_SCHED __builtin_amdgcn_sched_barrier(0)
;     ...
;                 PG8_WAIT_L(0); PG8_BAR; if (w0) { PG8_MMA(0, 0, At, B0); PG8_MMA(0, 1, At, B1); } PG8_BAR; PG8_SCHED;
.LBB0_359:
	s_waitcnt lgkmcnt(0)
	s_and_b64 vcc, exec, s[38:39]
	s_barrier
	s_cbranch_vccnz .LBB0_352
	s_setprio 1
	s_waitcnt lgkmcnt(7)
	v_mfma_f32_16x16x32_bf16 v[62:65], v[66:69], v[98:101], v[62:65]
	v_mfma_f32_16x16x32_bf16 v[62:65], v[70:73], v[102:105], v[62:65]
	v_mfma_f32_16x16x32_bf16 v[58:61], v[74:77], v[98:101], v[58:61]
	v_mfma_f32_16x16x32_bf16 v[58:61], v[78:81], v[102:105], v[58:61]
	v_mfma_f32_16x16x32_bf16 v[50:53], v[74:77], v[106:109], v[50:53]
	v_mfma_f32_16x16x32_bf16 v[50:53], v[78:81], v[110:113], v[50:53]
	v_mfma_f32_16x16x32_bf16 v[54:57], v[66:69], v[106:109], v[54:57]
	v_mfma_f32_16x16x32_bf16 v[54:57], v[70:73], v[110:113], v[54:57]
	v_mfma_f32_16x16x32_bf16 v[46:49], v[66:69], v[114:117], v[46:49]
	v_mfma_f32_16x16x32_bf16 v[46:49], v[70:73], v[118:121], v[46:49]
	v_mfma_f32_16x16x32_bf16 v[42:45], v[74:77], v[114:117], v[42:45]
	v_mfma_f32_16x16x32_bf16 v[42:45], v[78:81], v[118:121], v[42:45]
	v_mfma_f32_16x16x32_bf16 v[34:37], v[74:77], v[122:125], v[34:37]
	v_mfma_f32_16x16x32_bf16 v[34:37], v[78:81], v[126:129], v[34:37]
	v_mfma_f32_16x16x32_bf16 v[38:41], v[66:69], v[122:125], v[38:41]
	v_mfma_f32_16x16x32_bf16 v[38:41], v[70:73], v[126:129], v[38:41]
	v_mfma_f32_16x16x32_bf16 v[30:33], v[82:85], v[98:101], v[30:33]
	v_mfma_f32_16x16x32_bf16 v[30:33], v[86:89], v[102:105], v[30:33]
	v_mfma_f32_16x16x32_bf16 v[26:29], v[90:93], v[98:101], v[26:29]
	v_mfma_f32_16x16x32_bf16 v[26:29], v[94:97], v[102:105], v[26:29]
	v_mfma_f32_16x16x32_bf16 v[18:21], v[90:93], v[106:109], v[18:21]
	v_mfma_f32_16x16x32_bf16 v[18:21], v[94:97], v[110:113], v[18:21]
	v_mfma_f32_16x16x32_bf16 v[22:25], v[82:85], v[106:109], v[22:25]
	v_mfma_f32_16x16x32_bf16 v[22:25], v[86:89], v[110:113], v[22:25]
	v_mfma_f32_16x16x32_bf16 v[14:17], v[82:85], v[114:117], v[14:17]
	v_mfma_f32_16x16x32_bf16 v[14:17], v[86:89], v[118:121], v[14:17]
	v_mfma_f32_16x16x32_bf16 v[10:13], v[90:93], v[114:117], v[10:13]
	v_mfma_f32_16x16x32_bf16 v[10:13], v[94:97], v[118:121], v[10:13]
	v_mfma_f32_16x16x32_bf16 v[2:5], v[90:93], v[122:125], v[2:5]
	v_mfma_f32_16x16x32_bf16 v[2:5], v[94:97], v[126:129], v[2:5]
	v_mfma_f32_16x16x32_bf16 v[6:9], v[82:85], v[122:125], v[6:9]
	v_mfma_f32_16x16x32_bf16 v[6:9], v[86:89], v[126:129], v[6:9]
	s_setprio 0
	s_branch .LBB0_352

; #define PG8_STAGEX(rs, bufoff, soff, voff) do { _Pragma("unroll") for (int _i = 0; _i < 2; ++_i) \
;         __builtin_amdgcn_raw_ptr_buffer_load_lds(rs, (LAS unsigned*)(lds + (bufoff) + ldsw + _i * 8192), 16, (voff)[_i], (soff), 0, 0); } while (0)
; #define PG8_LDA(dst, b, h) do { _Pragma("unroll") for (int m = 0; m < 4; ++m) _Pragma("unroll") for (int k = 0; k < 2; ++k) dst[m][k] = *(const LAS bf16x8*)(lds + PG8_SA(b, h) + aoff + m * 2048 + k * 1024); } while (0)
; #define PG8_LDB(dst, b, h) do { _Pragma("unroll") for (int n = 0; n < 2; ++n) _Pragma("unroll") for (int k = 0; k < 2; ++k) dst[n][k] = *(const LAS bf16x8*)(lds + PG8_SB(b, h) + boff + n * 2048 + k * 1024); } while (0)
; #define PG8_WAIT_V(n) asm volatile("s_waitcnt vmcnt(" #n ")" ::: "memory")
; #define PG8_WAIT_L(n) asm volatile("s_waitcnt lgkmcnt(" #n ")" ::: "memory")
; #define PG8_BAR __builtin_amdgcn_s_barrier()
; #define PG8_SCHED __builtin_amdgcn_sched_barrier(0)
;     ...
;         for (int t = 0; t < nt; t += 2) {
;             const bool last = (t == nt - 2);
;             const unsigned a1 = cA + (unsigned)(t + 1) * kstep;
;             const unsigned a2 = last ? nA : cA + (unsigned)(t + 2) * kstep, b2 = last ? nB : cB + (unsigned)(t + 2) * kstep;
;             const unsigned a3 = a2 + kstep, b3 = b2 + kstep;
;             PG8_LDB(B0, 0, 0); PG8_LDB(B1, 0, 1); PG8_SCHED; PG8_LDA(At, 0, 0); PG8_STAGEX(rsA, PG8_SA(1, 1), a1 + hstepA, voffA);
;             PG8_WAIT_V(8); PG8_WAIT_L(0); PG8_BAR; PG8_MMA(0, 0, At, B0); PG8_MMA(0, 1, At, B1); PG8_BAR; PG8_SCHED;
;             PG8_LDA(At, 0, 1); PG8_STAGEX(rsB, PG8_SB(0, 0), b2, voffB); PG8_STAGEX(rsB, PG8_SB(0, 1), b2 + hstepB, voffB); PG8_STAGEX(rsA, PG8_SA(0, 0), a2, voffA);
;             PG8_WAIT_V(8); PG8_WAIT_L(0); PG8_BAR; PG8_MMA(1, 0, At, B0); PG8_MMA(1, 1, At, B1); PG8_BAR; PG8_SCHED;
.LBB0_437:
	v_add_u32_e32 v142, 0x10000, v220
	v_add_u32_e32 v158, 0x14000, v220
	ds_read_b128 v[130:133], v142
	ds_read_b128 v[134:137], v142 offset:1024
	ds_read_b128 v[138:141], v142 offset:2048
	ds_read_b128 v[142:145], v142 offset:3072
	ds_read_b128 v[146:149], v158
	ds_read_b128 v[150:153], v158 offset:1024
	ds_read_b128 v[154:157], v158 offset:2048
	ds_read_b128 v[158:161], v158 offset:3072
	s_add_i32 s30, s7, 0xfff80080
	s_cmp_eq_u32 s29, 28
	s_cselect_b32 s50, s2, s30
	s_cselect_b32 s31, s5, s28
	s_or_b32 s30, s50, 0x80
	s_mov_b32 m0, s20
	ds_read_b128 v[162:165], v221
	ds_read_b128 v[170:173], v221 offset:1024
	ds_read_b128 v[182:185], v221 offset:2048
	ds_read_b128 v[186:189], v221 offset:3072
	ds_read_b128 v[190:193], v221 offset:4096
	ds_read_b128 v[194:197], v221 offset:5120
	ds_read_b128 v[198:201], v221 offset:6144
	ds_read_b128 v[202:205], v221 offset:7168
	buffer_load_dwordx4 v178, s[76:79], s7 offen lds
	s_mov_b32 m0, s22
	s_nop 0
	buffer_load_dwordx4 v210, s[76:79], s7 offen lds
	s_waitcnt vmcnt(8)
	s_waitcnt lgkmcnt(0)
	s_setprio 1
	s_barrier
	v_mfma_f32_16x16x32_bf16 v[126:129], v[130:133], v[162:165], v[126:129]
	v_mfma_f32_16x16x32_bf16 v[126:129], v[134:137], v[170:173], v[126:129]
	v_mfma_f32_16x16x32_bf16 v[110:113], v[138:141], v[162:165], v[110:113]
	v_mfma_f32_16x16x32_bf16 v[110:113], v[142:145], v[170:173], v[110:113]
	v_mfma_f32_16x16x32_bf16 v[102:105], v[138:141], v[182:185], v[102:105]
	v_mfma_f32_16x16x32_bf16 v[102:105], v[142:145], v[186:189], v[102:105]
	v_mfma_f32_16x16x32_bf16 v[118:121], v[130:133], v[182:185], v[118:121]
	v_mfma_f32_16x16x32_bf16 v[118:121], v[134:137], v[186:189], v[118:121]
	v_mfma_f32_16x16x32_bf16 v[114:117], v[130:133], v[190:193], v[114:117]
	v_mfma_f32_16x16x32_bf16 v[114:117], v[134:137], v[194:197], v[114:117]
	v_mfma_f32_16x16x32_bf16 v[98:101], v[138:141], v[190:193], v[98:101]
	v_mfma_f32_16x16x32_bf16 v[98:101], v[142:145], v[194:197], v[98:101]
	v_mfma_f32_16x16x32_bf16 v[106:109], v[138:141], v[198:201], v[106:109]
	v_mfma_f32_16x16x32_bf16 v[106:109], v[142:145], v[202:205], v[106:109]
	v_mfma_f32_16x16x32_bf16 v[122:125], v[130:133], v[198:201], v[122:125]
	v_mfma_f32_16x16x32_bf16 v[122:125], v[134:137], v[202:205], v[122:125]
	v_mfma_f32_16x16x32_bf16 v[62:65], v[146:149], v[162:165], v[62:65]
	v_mfma_f32_16x16x32_bf16 v[62:65], v[150:153], v[170:173], v[62:65]
	v_mfma_f32_16x16x32_bf16 v[46:49], v[154:157], v[162:165], v[46:49]
	v_mfma_f32_16x16x32_bf16 v[46:49], v[158:161], v[170:173], v[46:49]
	v_mfma_f32_16x16x32_bf16 v[38:41], v[154:157], v[182:185], v[38:41]
	v_mfma_f32_16x16x32_bf16 v[38:41], v[158:161], v[186:189], v[38:41]
	v_mfma_f32_16x16x32_bf16 v[54:57], v[146:149], v[182:185], v[54:57]
	v_mfma_f32_16x16x32_bf16 v[54:57], v[150:153], v[186:189], v[54:57]
	v_mfma_f32_16x16x32_bf16 v[50:53], v[146:149], v[190:193], v[50:53]
	v_mfma_f32_16x16x32_bf16 v[50:53], v[150:153], v[194:197], v[50:53]
	v_mfma_f32_16x16x32_bf16 v[34:37], v[154:157], v[190:193], v[34:37]
	v_mfma_f32_16x16x32_bf16 v[34:37], v[158:161], v[194:197], v[34:37]
	v_mfma_f32_16x16x32_bf16 v[42:45], v[154:157], v[198:201], v[42:45]
	v_mfma_f32_16x16x32_bf16 v[42:45], v[158:161], v[202:205], v[42:45]
	v_mfma_f32_16x16x32_bf16 v[58:61], v[146:149], v[198:201], v[58:61]
	v_mfma_f32_16x16x32_bf16 v[58:61], v[150:153], v[202:205], v[58:61]
	s_barrier
	s_setprio 0
	s_mov_b32 m0, s90
	s_mov_b32 s58, s78
	s_mov_b32 s59, s79
	ds_read_b128 v[162:165], v221 offset:16384
	ds_read_b128 v[170:173], v221 offset:17408
	ds_read_b128 v[182:185], v221 offset:18432
	ds_read_b128 v[186:189], v221 offset:19456
	ds_read_b128 v[190:193], v221 offset:20480
	ds_read_b128 v[194:197], v221 offset:21504
	ds_read_b128 v[198:201], v221 offset:22528
	ds_read_b128 v[202:205], v221 offset:23552
	buffer_load_dwordx4 v179, s[56:59], s31 offen lds
	s_mov_b32 m0, s91
	s_add_i32 s51, s31, 0x80000
	buffer_load_dwordx4 v211, s[56:59], s31 offen lds
	s_mov_b32 m0, s9
	s_nop 0
	buffer_load_dwordx4 v179, s[56:59], s51 offen lds
	s_mov_b32 m0, s10
	s_nop 0
	buffer_load_dwordx4 v211, s[56:59], s51 offen lds
	s_mov_b32 m0, s89
	s_nop 0
	buffer_load_dwordx4 v178, s[76:79], s50 offen lds
	s_mov_b32 m0, s11
	s_nop 0
	buffer_load_dwordx4 v210, s[76:79], s50 offen lds
	s_waitcnt vmcnt(8)
	s_waitcnt lgkmcnt(0)
	s_setprio 1
	s_barrier
	v_mfma_f32_16x16x32_bf16 v[94:97], v[130:133], v[162:165], v[94:97]
	v_mfma_f32_16x16x32_bf16 v[94:97], v[134:137], v[170:173], v[94:97]
	v_mfma_f32_16x16x32_bf16 v[78:81], v[138:141], v[162:165], v[78:81]
	v_mfma_f32_16x16x32_bf16 v[78:81], v[142:145], v[170:173], v[78:81]
	v_mfma_f32_16x16x32_bf16 v[70:73], v[138:141], v[182:185], v[70:73]
	v_mfma_f32_16x16x32_bf16 v[70:73], v[142:145], v[186:189], v[70:73]
	v_mfma_f32_16x16x32_bf16 v[86:89], v[130:133], v[182:185], v[86:89]
	v_mfma_f32_16x16x32_bf16 v[86:89], v[134:137], v[186:189], v[86:89]
	v_mfma_f32_16x16x32_bf16 v[82:85], v[130:133], v[190:193], v[82:85]
	v_mfma_f32_16x16x32_bf16 v[82:85], v[134:137], v[194:197], v[82:85]
	v_mfma_f32_16x16x32_bf16 v[66:69], v[138:141], v[190:193], v[66:69]
	v_mfma_f32_16x16x32_bf16 v[66:69], v[142:145], v[194:197], v[66:69]
	v_mfma_f32_16x16x32_bf16 v[74:77], v[138:141], v[198:201], v[74:77]
	v_mfma_f32_16x16x32_bf16 v[74:77], v[142:145], v[202:205], v[74:77]
	v_mfma_f32_16x16x32_bf16 v[90:93], v[130:133], v[198:201], v[90:93]
	v_mfma_f32_16x16x32_bf16 v[90:93], v[134:137], v[202:205], v[90:93]
	v_mfma_f32_16x16x32_bf16 v[30:33], v[146:149], v[162:165], v[30:33]
	v_mfma_f32_16x16x32_bf16 v[30:33], v[150:153], v[170:173], v[30:33]
	v_mfma_f32_16x16x32_bf16 v[14:17], v[154:157], v[162:165], v[14:17]
	v_mfma_f32_16x16x32_bf16 v[14:17], v[158:161], v[170:173], v[14:17]
	v_mfma_f32_16x16x32_bf16 v[10:13], v[154:157], v[182:185], v[10:13]
	v_mfma_f32_16x16x32_bf16 v[10:13], v[158:161], v[186:189], v[10:13]
	v_mfma_f32_16x16x32_bf16 v[22:25], v[146:149], v[182:185], v[22:25]
	v_mfma_f32_16x16x32_bf16 v[22:25], v[150:153], v[186:189], v[22:25]
	v_mfma_f32_16x16x32_bf16 v[18:21], v[146:149], v[190:193], v[18:21]
	v_mfma_f32_16x16x32_bf16 v[18:21], v[150:153], v[194:197], v[18:21]
	v_mfma_f32_16x16x32_bf16 v[2:5], v[154:157], v[190:193], v[2:5]
	v_mfma_f32_16x16x32_bf16 v[2:5], v[158:161], v[194:197], v[2:5]
	v_mfma_f32_16x16x32_bf16 v[6:9], v[154:157], v[198:201], v[6:9]
	v_mfma_f32_16x16x32_bf16 v[6:9], v[158:161], v[202:205], v[6:9]
	v_mfma_f32_16x16x32_bf16 v[26:29], v[146:149], v[198:201], v[26:29]
	v_mfma_f32_16x16x32_bf16 v[26:29], v[150:153], v[202:205], v[26:29]
	s_barrier
; #define PG8_STAGEX(rs, bufoff, soff, voff) do { _Pragma("unroll") for (int _i = 0; _i < 2; ++_i) \
;         __builtin_amdgcn_raw_ptr_buffer_load_lds(rs, (LAS unsigned*)(lds + (bufoff) + ldsw + _i * 8192), 16, (voff)[_i], (soff), 0, 0); } while (0)
; #define PG8_LDA(dst, b, h) do { _Pragma("unroll") for (int m = 0; m < 4; ++m) _Pragma("unroll") for (int k = 0; k < 2; ++k) dst[m][k] = *(const LAS bf16x8*)(lds + PG8_SA(b, h) + aoff + m * 2048 + k * 1024); } while (0)
; #define PG8_LDB(dst, b, h) do { _Pragma("unroll") for (int n = 0; n < 2; ++n) _Pragma("unroll") for (int k = 0; k < 2; ++k) dst[n][k] = *(const LAS bf16x8*)(lds + PG8_SB(b, h) + boff + n * 2048 + k * 1024); } while (0)
; #define PG8_WAIT_V(n) asm volatile("s_waitcnt vmcnt(" #n ")" ::: "memory")
; #define PG8_WAIT_L(n) asm volatile("s_waitcnt lgkmcnt(" #n ")" ::: "memory")
; #define PG8_BAR __builtin_amdgcn_s_barrier()
; #define PG8_SCHED __builtin_amdgcn_sched_barrier(0)
;     ...
;             PG8_LDB(B0, 1, 0); PG8_LDB(B1, 1, 1); PG8_SCHED; PG8_LDA(At, 1, 0); PG8_STAGEX(rsA, PG8_SA(0, 1), a2 + hstepA, voffA);
;             PG8_WAIT_V(8); PG8_WAIT_L(0); PG8_BAR; PG8_MMA(0, 0, At, B0); PG8_MMA(0, 1, At, B1); PG8_BAR; PG8_SCHED;
;             PG8_LDA(At, 1, 1); PG8_STAGEX(rsB, PG8_SB(1, 0), b3, voffB); PG8_STAGEX(rsB, PG8_SB(1, 1), b3 + hstepB, voffB); PG8_STAGEX(rsA, PG8_SA(1, 0), a3, voffA);
;             PG8_WAIT_V(8); PG8_WAIT_L(0); PG8_BAR; PG8_MMA(1, 0, At, B0); PG8_MMA(1, 1, At, B1); PG8_BAR; PG8_SCHED;
;         }
	s_setprio 0
	v_add_u32_e32 v142, 0x18000, v220
	v_add_u32_e32 v158, 0x1c000, v220
	ds_read_b128 v[130:133], v142
	ds_read_b128 v[134:137], v142 offset:1024
	ds_read_b128 v[138:141], v142 offset:2048
	ds_read_b128 v[142:145], v142 offset:3072
	ds_read_b128 v[146:149], v158
	ds_read_b128 v[150:153], v158 offset:1024
	ds_read_b128 v[154:157], v158 offset:2048
	ds_read_b128 v[158:161], v158 offset:3072
	s_add_i32 s50, s50, 0x80000
	s_mov_b32 m0, s74
	ds_read_b128 v[162:165], v221 offset:32768
	ds_read_b128 v[170:173], v221 offset:33792
	ds_read_b128 v[182:185], v221 offset:34816
	ds_read_b128 v[186:189], v221 offset:35840
	ds_read_b128 v[190:193], v221 offset:36864
	ds_read_b128 v[194:197], v221 offset:37888
	ds_read_b128 v[198:201], v221 offset:38912
	ds_read_b128 v[202:205], v221 offset:39936
	buffer_load_dwordx4 v178, s[76:79], s50 offen lds
	s_mov_b32 m0, s12
	s_nop 0
	buffer_load_dwordx4 v210, s[76:79], s50 offen lds
	s_waitcnt vmcnt(8)
	s_waitcnt lgkmcnt(0)
	s_setprio 1
	s_barrier
	v_mfma_f32_16x16x32_bf16 v[126:129], v[130:133], v[162:165], v[126:129]
	v_mfma_f32_16x16x32_bf16 v[126:129], v[134:137], v[170:173], v[126:129]
	v_mfma_f32_16x16x32_bf16 v[110:113], v[138:141], v[162:165], v[110:113]
	v_mfma_f32_16x16x32_bf16 v[110:113], v[142:145], v[170:173], v[110:113]
	v_mfma_f32_16x16x32_bf16 v[102:105], v[138:141], v[182:185], v[102:105]
	v_mfma_f32_16x16x32_bf16 v[102:105], v[142:145], v[186:189], v[102:105]
	v_mfma_f32_16x16x32_bf16 v[118:121], v[130:133], v[182:185], v[118:121]
	v_mfma_f32_16x16x32_bf16 v[118:121], v[134:137], v[186:189], v[118:121]
	v_mfma_f32_16x16x32_bf16 v[114:117], v[130:133], v[190:193], v[114:117]
	v_mfma_f32_16x16x32_bf16 v[114:117], v[134:137], v[194:197], v[114:117]
	v_mfma_f32_16x16x32_bf16 v[98:101], v[138:141], v[190:193], v[98:101]
	v_mfma_f32_16x16x32_bf16 v[98:101], v[142:145], v[194:197], v[98:101]
	v_mfma_f32_16x16x32_bf16 v[106:109], v[138:141], v[198:201], v[106:109]
	v_mfma_f32_16x16x32_bf16 v[106:109], v[142:145], v[202:205], v[106:109]
	v_mfma_f32_16x16x32_bf16 v[122:125], v[130:133], v[198:201], v[122:125]
	v_mfma_f32_16x16x32_bf16 v[122:125], v[134:137], v[202:205], v[122:125]
	v_mfma_f32_16x16x32_bf16 v[62:65], v[146:149], v[162:165], v[62:65]
	v_mfma_f32_16x16x32_bf16 v[62:65], v[150:153], v[170:173], v[62:65]
	v_mfma_f32_16x16x32_bf16 v[46:49], v[154:157], v[162:165], v[46:49]
	v_mfma_f32_16x16x32_bf16 v[46:49], v[158:161], v[170:173], v[46:49]
	v_mfma_f32_16x16x32_bf16 v[38:41], v[154:157], v[182:185], v[38:41]
	v_mfma_f32_16x16x32_bf16 v[38:41], v[158:161], v[186:189], v[38:41]
	v_mfma_f32_16x16x32_bf16 v[54:57], v[146:149], v[182:185], v[54:57]
	v_mfma_f32_16x16x32_bf16 v[54:57], v[150:153], v[186:189], v[54:57]
	v_mfma_f32_16x16x32_bf16 v[50:53], v[146:149], v[190:193], v[50:53]
	v_mfma_f32_16x16x32_bf16 v[50:53], v[150:153], v[194:197], v[50:53]
	v_mfma_f32_16x16x32_bf16 v[34:37], v[154:157], v[190:193], v[34:37]
	v_mfma_f32_16x16x32_bf16 v[34:37], v[158:161], v[194:197], v[34:37]
	v_mfma_f32_16x16x32_bf16 v[42:45], v[154:157], v[198:201], v[42:45]
	v_mfma_f32_16x16x32_bf16 v[42:45], v[158:161], v[202:205], v[42:45]
	v_mfma_f32_16x16x32_bf16 v[58:61], v[146:149], v[198:201], v[58:61]
	v_mfma_f32_16x16x32_bf16 v[58:61], v[150:153], v[202:205], v[58:61]
	s_barrier
	s_setprio 0
	s_mov_b32 m0, s13
	s_or_b32 s50, s31, 0x80
	ds_read_b128 v[162:165], v221 offset:49152
	ds_read_b128 v[170:173], v221 offset:50176
	ds_read_b128 v[182:185], v221 offset:51200
	ds_read_b128 v[186:189], v221 offset:52224
	ds_read_b128 v[190:193], v221 offset:53248
	ds_read_b128 v[194:197], v221 offset:54272
	ds_read_b128 v[198:201], v221 offset:55296
	ds_read_b128 v[202:205], v221 offset:56320
	buffer_load_dwordx4 v179, s[56:59], s50 offen lds
	s_mov_b32 m0, s14
	s_add_i32 s31, s31, 0x80080
	buffer_load_dwordx4 v211, s[56:59], s50 offen lds
	s_mov_b32 m0, s17
	s_nop 0
	buffer_load_dwordx4 v179, s[56:59], s31 offen lds
	s_mov_b32 m0, s18
	s_nop 0
	buffer_load_dwordx4 v211, s[56:59], s31 offen lds
	s_mov_b32 m0, s15
	s_nop 0
	buffer_load_dwordx4 v178, s[76:79], s30 offen lds
	s_mov_b32 m0, s16
	s_nop 0
	buffer_load_dwordx4 v210, s[76:79], s30 offen lds
	s_waitcnt vmcnt(8)
	s_waitcnt lgkmcnt(0)
	s_setprio 1
	s_barrier
	v_mfma_f32_16x16x32_bf16 v[94:97], v[130:133], v[162:165], v[94:97]
	v_mfma_f32_16x16x32_bf16 v[94:97], v[134:137], v[170:173], v[94:97]
	v_mfma_f32_16x16x32_bf16 v[78:81], v[138:141], v[162:165], v[78:81]
	v_mfma_f32_16x16x32_bf16 v[78:81], v[142:145], v[170:173], v[78:81]
	v_mfma_f32_16x16x32_bf16 v[70:73], v[138:141], v[182:185], v[70:73]
	v_mfma_f32_16x16x32_bf16 v[70:73], v[142:145], v[186:189], v[70:73]
	v_mfma_f32_16x16x32_bf16 v[86:89], v[130:133], v[182:185], v[86:89]
	v_mfma_f32_16x16x32_bf16 v[86:89], v[134:137], v[186:189], v[86:89]
	v_mfma_f32_16x16x32_bf16 v[82:85], v[130:133], v[190:193], v[82:85]
	v_mfma_f32_16x16x32_bf16 v[82:85], v[134:137], v[194:197], v[82:85]
	v_mfma_f32_16x16x32_bf16 v[66:69], v[138:141], v[190:193], v[66:69]
	v_mfma_f32_16x16x32_bf16 v[66:69], v[142:145], v[194:197], v[66:69]
	v_mfma_f32_16x16x32_bf16 v[74:77], v[138:141], v[198:201], v[74:77]
	v_mfma_f32_16x16x32_bf16 v[74:77], v[142:145], v[202:205], v[74:77]
	v_mfma_f32_16x16x32_bf16 v[90:93], v[130:133], v[198:201], v[90:93]
	v_mfma_f32_16x16x32_bf16 v[90:93], v[134:137], v[202:205], v[90:93]
	v_mfma_f32_16x16x32_bf16 v[30:33], v[146:149], v[162:165], v[30:33]
	v_mfma_f32_16x16x32_bf16 v[30:33], v[150:153], v[170:173], v[30:33]
	v_mfma_f32_16x16x32_bf16 v[14:17], v[154:157], v[162:165], v[14:17]
	v_mfma_f32_16x16x32_bf16 v[14:17], v[158:161], v[170:173], v[14:17]
	v_mfma_f32_16x16x32_bf16 v[10:13], v[154:157], v[182:185], v[10:13]
	v_mfma_f32_16x16x32_bf16 v[10:13], v[158:161], v[186:189], v[10:13]
	v_mfma_f32_16x16x32_bf16 v[22:25], v[146:149], v[182:185], v[22:25]
	v_mfma_f32_16x16x32_bf16 v[22:25], v[150:153], v[186:189], v[22:25]
	v_mfma_f32_16x16x32_bf16 v[18:21], v[146:149], v[190:193], v[18:21]
	v_mfma_f32_16x16x32_bf16 v[18:21], v[150:153], v[194:197], v[18:21]
	v_mfma_f32_16x16x32_bf16 v[2:5], v[154:157], v[190:193], v[2:5]
	v_mfma_f32_16x16x32_bf16 v[2:5], v[158:161], v[194:197], v[2:5]
	v_mfma_f32_16x16x32_bf16 v[6:9], v[154:157], v[198:201], v[6:9]
	v_mfma_f32_16x16x32_bf16 v[6:9], v[158:161], v[202:205], v[6:9]
	v_mfma_f32_16x16x32_bf16 v[26:29], v[146:149], v[198:201], v[26:29]
	v_mfma_f32_16x16x32_bf16 v[26:29], v[150:153], v[202:205], v[26:29]
	s_barrier
	s_setprio 0
	s_add_i32 s29, s29, 2
	s_addk_i32 s7, 0x100
	s_addk_i32 s28, 0x100
	s_cmp_gt_u32 s29, 29
	s_cbranch_scc0 .LBB0_437
	s_and_b64 vcc, exec, s[84:85]
	s_cbranch_vccz .LBB0_440
	s_barrier

; #define PG8_STAGEX(rs, bufoff, soff, voff) do { _Pragma("unroll") for (int _i = 0; _i < 2; ++_i) \
;         __builtin_amdgcn_raw_ptr_buffer_load_lds(rs, (LAS unsigned*)(lds + (bufoff) + ldsw + _i * 8192), 16, (voff)[_i], (soff), 0, 0); } while (0)
; #define PG8_LDA(dst, b, h) do { _Pragma("unroll") for (int m = 0; m < 4; ++m) _Pragma("unroll") for (int k = 0; k < 2; ++k) dst[m][k] = *(const LAS bf16x8*)(lds + PG8_SA(b, h) + aoff + m * 2048 + k * 1024); } while (0)
; #define PG8_LDB(dst, b, h) do { _Pragma("unroll") for (int n = 0; n < 2; ++n) _Pragma("unroll") for (int k = 0; k < 2; ++k) dst[n][k] = *(const LAS bf16x8*)(lds + PG8_SB(b, h) + boff + n * 2048 + k * 1024); } while (0)
; #define PG8_WAIT_V(n) asm volatile("s_waitcnt vmcnt(" #n ")" ::: "memory")
; #define PG8_WAIT_L(n) asm volatile("s_waitcnt lgkmcnt(" #n ")" ::: "memory")
; #define PG8_BAR __builtin_amdgcn_s_barrier()
; #define PG8_SCHED __builtin_amdgcn_sched_barrier(0)
;     ...
;             for (int t = 0; t < nt; t += 2) {
;                 const bool last = (t == nt - 2);
;                 const unsigned a1 = cA + (unsigned)(t + 1) * kstep;
;                 const unsigned a2 = last ? nA : cA + (unsigned)(t + 2) * kstep, b2 = last ? nB : cB + (unsigned)(t + 2) * kstep;
;                 const unsigned a3 = a2 + kstep, b3 = b2 + kstep;
;                 if (w0) { PG8_LDB(B0, 0, 0); PG8_LDB(B1, 0, 1); PG8_SCHED; PG8_LDA(At, 0, 0); }
;                 PG8_WAIT_L(0); PG8_BAR; if (w0) { PG8_MMA(0, 0, At, B0); PG8_MMA(0, 1, At, B1); } PG8_BAR; PG8_SCHED;
;                 PG8_STAGEX(rsB, PG8_SB(0, 0), b2, voffB); PG8_STAGEX(rsB, PG8_SB(0, 1), b2 + hstepB, voffB); PG8_STAGEX(rsA, PG8_SA(0, 0), a2, voffA);
;                 PG8_WAIT_V(6); PG8_BAR; PG8_BAR; PG8_SCHED;
.LBB0_542:
	v_add_u32_e32 v73, 0x10000, v71
	ds_read_b128 v[74:77], v73
	ds_read_b128 v[78:81], v73 offset:1024
	ds_read_b128 v[82:85], v73 offset:2048
	ds_read_b128 v[86:89], v73 offset:3072
	v_add_u32_e32 v73, 0x14000, v71
	ds_read_b128 v[90:93], v73
	ds_read_b128 v[94:97], v73 offset:1024
	ds_read_b128 v[98:101], v73 offset:2048
	ds_read_b128 v[110:113], v73 offset:3072
	s_cmp_lg_u32 s26, 28
	s_cselect_b32 s27, s25, 0
	s_add_i32 s28, s27, s17
	s_or_b32 s29, s28, 0x80
	s_add_i32 s27, s27, s10
	ds_read_b128 v[114:117], v72
	ds_read_b128 v[118:121], v72 offset:1024
	ds_read_b128 v[122:125], v72 offset:2048
	ds_read_b128 v[126:129], v72 offset:3072
	ds_read_b128 v[130:133], v72 offset:4096
	ds_read_b128 v[134:137], v72 offset:5120
	ds_read_b128 v[138:141], v72 offset:6144
	ds_read_b128 v[142:145], v72 offset:7168
	s_waitcnt lgkmcnt(0)
	s_setprio 1
	s_barrier
	v_mfma_f32_16x16x32_bf16 v[62:65], v[74:77], v[114:117], v[62:65]
	v_mfma_f32_16x16x32_bf16 v[62:65], v[78:81], v[118:121], v[62:65]
	v_mfma_f32_16x16x32_bf16 v[46:49], v[82:85], v[114:117], v[46:49]
	v_mfma_f32_16x16x32_bf16 v[46:49], v[86:89], v[118:121], v[46:49]
	v_mfma_f32_16x16x32_bf16 v[38:41], v[82:85], v[122:125], v[38:41]
	v_mfma_f32_16x16x32_bf16 v[38:41], v[86:89], v[126:129], v[38:41]
	v_mfma_f32_16x16x32_bf16 v[54:57], v[74:77], v[122:125], v[54:57]
	v_mfma_f32_16x16x32_bf16 v[54:57], v[78:81], v[126:129], v[54:57]
	v_mfma_f32_16x16x32_bf16 v[50:53], v[74:77], v[130:133], v[50:53]
	v_mfma_f32_16x16x32_bf16 v[50:53], v[78:81], v[134:137], v[50:53]
	v_mfma_f32_16x16x32_bf16 v[34:37], v[82:85], v[130:133], v[34:37]
	v_mfma_f32_16x16x32_bf16 v[34:37], v[86:89], v[134:137], v[34:37]
	v_mfma_f32_16x16x32_bf16 v[42:45], v[82:85], v[138:141], v[42:45]
	v_mfma_f32_16x16x32_bf16 v[42:45], v[86:89], v[142:145], v[42:45]
	v_mfma_f32_16x16x32_bf16 v[58:61], v[74:77], v[138:141], v[58:61]
	v_mfma_f32_16x16x32_bf16 v[58:61], v[78:81], v[142:145], v[58:61]
	v_mfma_f32_16x16x32_bf16 v[30:33], v[90:93], v[114:117], v[30:33]
	v_mfma_f32_16x16x32_bf16 v[30:33], v[94:97], v[118:121], v[30:33]
	v_mfma_f32_16x16x32_bf16 v[14:17], v[98:101], v[114:117], v[14:17]
	v_mfma_f32_16x16x32_bf16 v[14:17], v[110:113], v[118:121], v[14:17]
	v_mfma_f32_16x16x32_bf16 v[10:13], v[98:101], v[122:125], v[10:13]
	v_mfma_f32_16x16x32_bf16 v[10:13], v[110:113], v[126:129], v[10:13]
	v_mfma_f32_16x16x32_bf16 v[22:25], v[90:93], v[122:125], v[22:25]
	v_mfma_f32_16x16x32_bf16 v[22:25], v[94:97], v[126:129], v[22:25]
	v_mfma_f32_16x16x32_bf16 v[18:21], v[90:93], v[130:133], v[18:21]
	v_mfma_f32_16x16x32_bf16 v[18:21], v[94:97], v[134:137], v[18:21]
	v_mfma_f32_16x16x32_bf16 v[2:5], v[98:101], v[130:133], v[2:5]
	v_mfma_f32_16x16x32_bf16 v[2:5], v[110:113], v[134:137], v[2:5]
	v_mfma_f32_16x16x32_bf16 v[6:9], v[98:101], v[138:141], v[6:9]
	v_mfma_f32_16x16x32_bf16 v[6:9], v[110:113], v[142:145], v[6:9]
	v_mfma_f32_16x16x32_bf16 v[26:29], v[90:93], v[138:141], v[26:29]
	v_mfma_f32_16x16x32_bf16 v[26:29], v[94:97], v[142:145], v[26:29]
	s_barrier
	s_setprio 0
	s_mov_b32 m0, s12
	s_mov_b32 s58, s78
	s_mov_b32 s59, s79
	buffer_load_dwordx4 v67, s[56:59], s27 offen lds
	s_mov_b32 m0, s13
	s_add_i32 s30, s27, 0x80000
	buffer_load_dwordx4 v69, s[56:59], s27 offen lds
	s_mov_b32 m0, s14
	s_nop 0
	buffer_load_dwordx4 v67, s[56:59], s30 offen lds
	s_mov_b32 m0, s15
	s_nop 0
	buffer_load_dwordx4 v69, s[56:59], s30 offen lds
	s_mov_b32 m0, s11
	s_nop 0
	buffer_load_dwordx4 v66, s[76:79], s28 offen lds
	s_mov_b32 m0, s18
	s_nop 0
	buffer_load_dwordx4 v68, s[76:79], s28 offen lds
	s_waitcnt vmcnt(6)
	s_barrier
	s_barrier
; #define PG8_STAGEX(rs, bufoff, soff, voff) do { _Pragma("unroll") for (int _i = 0; _i < 2; ++_i) \
;         __builtin_amdgcn_raw_ptr_buffer_load_lds(rs, (LAS unsigned*)(lds + (bufoff) + ldsw + _i * 8192), 16, (voff)[_i], (soff), 0, 0); } while (0)
; #define PG8_LDA(dst, b, h) do { _Pragma("unroll") for (int m = 0; m < 4; ++m) _Pragma("unroll") for (int k = 0; k < 2; ++k) dst[m][k] = *(const LAS bf16x8*)(lds + PG8_SA(b, h) + aoff + m * 2048 + k * 1024); } while (0)
; #define PG8_LDB(dst, b, h) do { _Pragma("unroll") for (int n = 0; n < 2; ++n) _Pragma("unroll") for (int k = 0; k < 2; ++k) dst[n][k] = *(const LAS bf16x8*)(lds + PG8_SB(b, h) + boff + n * 2048 + k * 1024); } while (0)
; #define PG8_WAIT_V(n) asm volatile("s_waitcnt vmcnt(" #n ")" ::: "memory")
; #define PG8_WAIT_L(n) asm volatile("s_waitcnt lgkmcnt(" #n ")" ::: "memory")
; #define PG8_BAR __builtin_amdgcn_s_barrier()
; #define PG8_SCHED __builtin_amdgcn_sched_barrier(0)
;     ...
;                 if (w0) { PG8_LDB(B0, 1, 0); PG8_LDB(B1, 1, 1); PG8_SCHED; PG8_LDA(At, 1, 0); }
;                 PG8_WAIT_L(0); PG8_BAR; if (w0) { PG8_MMA(0, 0, At, B0); PG8_MMA(0, 1, At, B1); } PG8_BAR; PG8_SCHED;
;                 PG8_STAGEX(rsB, PG8_SB(1, 0), b3, voffB); PG8_STAGEX(rsB, PG8_SB(1, 1), b3 + hstepB, voffB); PG8_STAGEX(rsA, PG8_SA(1, 0), a3, voffA);
;                 PG8_WAIT_V(6); PG8_BAR; PG8_BAR; PG8_SCHED;
;             }
;         }
;         if (wr == 0) PG8_BAR;
	v_add_u32_e32 v73, 0x18000, v71
	ds_read_b128 v[74:77], v73
	ds_read_b128 v[78:81], v73 offset:1024
	ds_read_b128 v[82:85], v73 offset:2048
	ds_read_b128 v[86:89], v73 offset:3072
	v_add_u32_e32 v73, 0x1c000, v71
	ds_read_b128 v[90:93], v73
	ds_read_b128 v[94:97], v73 offset:1024
	ds_read_b128 v[98:101], v73 offset:2048
	ds_read_b128 v[110:113], v73 offset:3072
	ds_read_b128 v[114:117], v72 offset:32768
	ds_read_b128 v[118:121], v72 offset:33792
	ds_read_b128 v[122:125], v72 offset:34816
	ds_read_b128 v[126:129], v72 offset:35840
	ds_read_b128 v[130:133], v72 offset:36864
	ds_read_b128 v[134:137], v72 offset:37888
	ds_read_b128 v[138:141], v72 offset:38912
	ds_read_b128 v[142:145], v72 offset:39936
	s_waitcnt lgkmcnt(0)
	s_setprio 1
	s_barrier
	v_mfma_f32_16x16x32_bf16 v[62:65], v[74:77], v[114:117], v[62:65]
	v_mfma_f32_16x16x32_bf16 v[46:49], v[82:85], v[114:117], v[46:49]
	v_mfma_f32_16x16x32_bf16 v[54:57], v[74:77], v[122:125], v[54:57]
	v_mfma_f32_16x16x32_bf16 v[38:41], v[82:85], v[122:125], v[38:41]
	v_mfma_f32_16x16x32_bf16 v[50:53], v[74:77], v[130:133], v[50:53]
	v_mfma_f32_16x16x32_bf16 v[34:37], v[82:85], v[130:133], v[34:37]
	v_mfma_f32_16x16x32_bf16 v[58:61], v[74:77], v[138:141], v[58:61]
	v_mfma_f32_16x16x32_bf16 v[42:45], v[82:85], v[138:141], v[42:45]
	v_mfma_f32_16x16x32_bf16 v[62:65], v[78:81], v[118:121], v[62:65]
	v_mfma_f32_16x16x32_bf16 v[46:49], v[86:89], v[118:121], v[46:49]
	v_mfma_f32_16x16x32_bf16 v[54:57], v[78:81], v[126:129], v[54:57]
	v_mfma_f32_16x16x32_bf16 v[38:41], v[86:89], v[126:129], v[38:41]
	v_mfma_f32_16x16x32_bf16 v[50:53], v[78:81], v[134:137], v[50:53]
	v_mfma_f32_16x16x32_bf16 v[34:37], v[86:89], v[134:137], v[34:37]
	v_mfma_f32_16x16x32_bf16 v[58:61], v[78:81], v[142:145], v[58:61]
	v_mfma_f32_16x16x32_bf16 v[42:45], v[86:89], v[142:145], v[42:45]
	v_mfma_f32_16x16x32_bf16 v[30:33], v[90:93], v[114:117], v[30:33]
	s_or_b32 s28, s27, 0x80
	v_mfma_f32_16x16x32_bf16 v[14:17], v[98:101], v[114:117], v[14:17]
	v_mfma_f32_16x16x32_bf16 v[22:25], v[90:93], v[122:125], v[22:25]
	v_mfma_f32_16x16x32_bf16 v[10:13], v[98:101], v[122:125], v[10:13]
	v_mfma_f32_16x16x32_bf16 v[18:21], v[90:93], v[130:133], v[18:21]
	v_mfma_f32_16x16x32_bf16 v[2:5], v[98:101], v[130:133], v[2:5]
	v_mfma_f32_16x16x32_bf16 v[26:29], v[90:93], v[138:141], v[26:29]
	v_mfma_f32_16x16x32_bf16 v[6:9], v[98:101], v[138:141], v[6:9]
	v_mfma_f32_16x16x32_bf16 v[30:33], v[94:97], v[118:121], v[30:33]
	v_mfma_f32_16x16x32_bf16 v[14:17], v[110:113], v[118:121], v[14:17]
	v_mfma_f32_16x16x32_bf16 v[22:25], v[94:97], v[126:129], v[22:25]
	v_mfma_f32_16x16x32_bf16 v[10:13], v[110:113], v[126:129], v[10:13]
	v_mfma_f32_16x16x32_bf16 v[18:21], v[94:97], v[134:137], v[18:21]
	v_mfma_f32_16x16x32_bf16 v[2:5], v[110:113], v[134:137], v[2:5]
	v_mfma_f32_16x16x32_bf16 v[26:29], v[94:97], v[142:145], v[26:29]
	v_mfma_f32_16x16x32_bf16 v[6:9], v[110:113], v[142:145], v[6:9]
	s_barrier
	s_setprio 0
	s_mov_b32 m0, s19
	s_add_i32 s27, s27, 0x80080
	buffer_load_dwordx4 v67, s[56:59], s28 offen lds
	s_mov_b32 m0, s20
	s_nop 0
	buffer_load_dwordx4 v69, s[56:59], s28 offen lds
	s_mov_b32 m0, s23
	s_nop 0
	buffer_load_dwordx4 v67, s[56:59], s27 offen lds
	s_mov_b32 m0, s24
	s_nop 0
	buffer_load_dwordx4 v69, s[56:59], s27 offen lds
	s_mov_b32 m0, s21
	s_nop 0
	buffer_load_dwordx4 v66, s[76:79], s29 offen lds
	s_mov_b32 m0, s22
	s_nop 0
	buffer_load_dwordx4 v68, s[76:79], s29 offen lds
	s_waitcnt vmcnt(6)
	s_barrier
	s_barrier
	s_addk_i32 s25, 0x100
	s_add_i32 s26, s26, 2
	s_cmp_gt_u32 s26, 29
	s_cbranch_scc0 .LBB0_542
	s_cmpk_lt_u32 s1, 0x100
	s_cbranch_scc0 .LBB0_545
	s_barrier

; #define PG8_STAGEX(rs, bufoff, soff, voff) do { _Pragma("unroll") for (int _i = 0; _i < 2; ++_i) \
;         __builtin_amdgcn_raw_ptr_buffer_load_lds(rs, (LAS unsigned*)(lds + (bufoff) + ldsw + _i * 8192), 16, (voff)[_i], (soff), 0, 0); } while (0)
; #define PG8_LDA(dst, b, h) do { _Pragma("unroll") for (int m = 0; m < 4; ++m) _Pragma("unroll") for (int k = 0; k < 2; ++k) dst[m][k] = *(const LAS bf16x8*)(lds + PG8_SA(b, h) + aoff + m * 2048 + k * 1024); } while (0)
; #define PG8_LDB(dst, b, h) do { _Pragma("unroll") for (int n = 0; n < 2; ++n) _Pragma("unroll") for (int k = 0; k < 2; ++k) dst[n][k] = *(const LAS bf16x8*)(lds + PG8_SB(b, h) + boff + n * 2048 + k * 1024); } while (0)
; #define PG8_WAIT_V(n) asm volatile("s_waitcnt vmcnt(" #n ")" ::: "memory")
; #define PG8_WAIT_L(n) asm volatile("s_waitcnt lgkmcnt(" #n ")" ::: "memory")
; #define PG8_BAR __builtin_amdgcn_s_barrier()
; #define PG8_SCHED __builtin_amdgcn_sched_barrier(0)
;     ...
;         for (int t = 0; t < nt; t += 2) {
;             const bool last = (t == nt - 2);
;             const unsigned a1 = cA + (unsigned)(t + 1) * kstep;
;             const unsigned a2 = last ? nA : cA + (unsigned)(t + 2) * kstep, b2 = last ? nB : cB + (unsigned)(t + 2) * kstep;
;             const unsigned a3 = a2 + kstep, b3 = b2 + kstep;
;             PG8_LDB(B0, 0, 0); PG8_LDB(B1, 0, 1); PG8_SCHED; PG8_LDA(At, 0, 0); PG8_STAGEX(rsA, PG8_SA(1, 1), a1 + hstepA, voffA);
;             PG8_WAIT_V(8); PG8_WAIT_L(0); PG8_BAR; PG8_MMA(0, 0, At, B0); PG8_MMA(0, 1, At, B1); PG8_BAR; PG8_SCHED;
;             PG8_LDA(At, 0, 1); PG8_STAGEX(rsB, PG8_SB(0, 0), b2, voffB); PG8_STAGEX(rsB, PG8_SB(0, 1), b2 + hstepB, voffB); PG8_STAGEX(rsA, PG8_SA(0, 0), a2, voffA);
;             PG8_WAIT_V(8); PG8_WAIT_L(0); PG8_BAR; PG8_MMA(1, 0, At, B0); PG8_MMA(1, 1, At, B1); PG8_BAR; PG8_SCHED;
.LBB0_788:
	v_add_u32_e32 v150, 0x10000, v153
	ds_read_b128 v[138:141], v150
	ds_read_b128 v[142:145], v150 offset:1024
	ds_read_b128 v[146:149], v150 offset:2048
	ds_read_b128 v[156:159], v150 offset:3072
	v_add_u32_e32 v150, 0x14000, v153
	ds_read_b128 v[160:163], v150
	ds_read_b128 v[164:167], v150 offset:1024
	ds_read_b128 v[182:185], v150 offset:2048
	ds_read_b128 v[186:189], v150 offset:3072
	s_add_i32 s48, s31, 0xfffc0080
	s_cmp_eq_u32 s55, s47
	s_cselect_b32 s50, s7, s48
	s_cselect_b32 s49, s30, s46
	s_add_i32 s48, s50, 0x80
	s_mov_b32 m0, s35
	ds_read_b128 v[190:193], v154
	ds_read_b128 v[194:197], v154 offset:1024
	ds_read_b128 v[198:201], v154 offset:2048
	ds_read_b128 v[202:205], v154 offset:3072
	ds_read_b128 v[206:209], v154 offset:4096
	ds_read_b128 v[210:213], v154 offset:5120
	ds_read_b128 v[214:217], v154 offset:6144
	ds_read_b128 v[218:221], v154 offset:7168
	buffer_load_dwordx4 v130, s[76:79], s31 offen lds
	s_mov_b32 m0, s82
	s_nop 0
	buffer_load_dwordx4 v134, s[76:79], s31 offen lds
	s_waitcnt vmcnt(8)
	s_waitcnt lgkmcnt(0)
	s_setprio 1
	s_barrier
	v_mfma_f32_16x16x32_bf16 v[126:129], v[190:193], v[138:141], v[126:129]
	v_mfma_f32_16x16x32_bf16 v[126:129], v[194:197], v[142:145], v[126:129]
	v_mfma_f32_16x16x32_bf16 v[62:65], v[190:193], v[146:149], v[62:65]
	v_mfma_f32_16x16x32_bf16 v[62:65], v[194:197], v[156:159], v[62:65]
	v_mfma_f32_16x16x32_bf16 v[54:57], v[198:201], v[146:149], v[54:57]
	v_mfma_f32_16x16x32_bf16 v[54:57], v[202:205], v[156:159], v[54:57]
	v_mfma_f32_16x16x32_bf16 v[118:121], v[198:201], v[138:141], v[118:121]
	v_mfma_f32_16x16x32_bf16 v[118:121], v[202:205], v[142:145], v[118:121]
	v_mfma_f32_16x16x32_bf16 v[110:113], v[206:209], v[138:141], v[110:113]
	v_mfma_f32_16x16x32_bf16 v[110:113], v[210:213], v[142:145], v[110:113]
	v_mfma_f32_16x16x32_bf16 v[46:49], v[206:209], v[146:149], v[46:49]
	v_mfma_f32_16x16x32_bf16 v[46:49], v[210:213], v[156:159], v[46:49]
	v_mfma_f32_16x16x32_bf16 v[38:41], v[214:217], v[146:149], v[38:41]
	v_mfma_f32_16x16x32_bf16 v[38:41], v[218:221], v[156:159], v[38:41]
	v_mfma_f32_16x16x32_bf16 v[102:105], v[214:217], v[138:141], v[102:105]
	v_mfma_f32_16x16x32_bf16 v[102:105], v[218:221], v[142:145], v[102:105]
	v_mfma_f32_16x16x32_bf16 v[122:125], v[190:193], v[160:163], v[122:125]
	v_mfma_f32_16x16x32_bf16 v[122:125], v[194:197], v[164:167], v[122:125]
	v_mfma_f32_16x16x32_bf16 v[58:61], v[190:193], v[182:185], v[58:61]
	v_mfma_f32_16x16x32_bf16 v[58:61], v[194:197], v[186:189], v[58:61]
	v_mfma_f32_16x16x32_bf16 v[50:53], v[198:201], v[182:185], v[50:53]
	v_mfma_f32_16x16x32_bf16 v[50:53], v[202:205], v[186:189], v[50:53]
	v_mfma_f32_16x16x32_bf16 v[114:117], v[198:201], v[160:163], v[114:117]
	v_mfma_f32_16x16x32_bf16 v[114:117], v[202:205], v[164:167], v[114:117]
	v_mfma_f32_16x16x32_bf16 v[106:109], v[206:209], v[160:163], v[106:109]
	v_mfma_f32_16x16x32_bf16 v[106:109], v[210:213], v[164:167], v[106:109]
	v_mfma_f32_16x16x32_bf16 v[42:45], v[206:209], v[182:185], v[42:45]
	v_mfma_f32_16x16x32_bf16 v[42:45], v[210:213], v[186:189], v[42:45]
	v_mfma_f32_16x16x32_bf16 v[34:37], v[214:217], v[182:185], v[34:37]
	v_mfma_f32_16x16x32_bf16 v[34:37], v[218:221], v[186:189], v[34:37]
	v_mfma_f32_16x16x32_bf16 v[98:101], v[214:217], v[160:163], v[98:101]
	v_mfma_f32_16x16x32_bf16 v[98:101], v[218:221], v[164:167], v[98:101]
	s_barrier
	s_setprio 0
	s_mov_b32 m0, s15
	s_mov_b32 s86, s78
	s_mov_b32 s87, s79
	ds_read_b128 v[190:193], v154 offset:16384
	ds_read_b128 v[194:197], v154 offset:17408
	ds_read_b128 v[198:201], v154 offset:18432
	ds_read_b128 v[202:205], v154 offset:19456
	ds_read_b128 v[206:209], v154 offset:20480
	ds_read_b128 v[210:213], v154 offset:21504
	ds_read_b128 v[214:217], v154 offset:22528
	ds_read_b128 v[218:221], v154 offset:23552
	buffer_load_dwordx4 v132, s[84:87], s49 offen lds
	s_mov_b32 m0, s16
	s_add_i32 s51, s49, 0x8000
	buffer_load_dwordx4 v136, s[84:87], s49 offen lds
	s_mov_b32 m0, s17
	s_nop 0
	buffer_load_dwordx4 v132, s[84:87], s51 offen lds
	s_mov_b32 m0, s18
	s_nop 0
	buffer_load_dwordx4 v136, s[84:87], s51 offen lds
	s_mov_b32 m0, s14
	s_nop 0
	buffer_load_dwordx4 v130, s[76:79], s50 offen lds
	s_mov_b32 m0, s19
	s_nop 0
	buffer_load_dwordx4 v134, s[76:79], s50 offen lds
	s_waitcnt vmcnt(8)
	s_waitcnt lgkmcnt(0)
	s_setprio 1
	s_barrier
	v_mfma_f32_16x16x32_bf16 v[94:97], v[190:193], v[138:141], v[94:97]
	v_mfma_f32_16x16x32_bf16 v[94:97], v[194:197], v[142:145], v[94:97]
	v_mfma_f32_16x16x32_bf16 v[30:33], v[190:193], v[146:149], v[30:33]
	v_mfma_f32_16x16x32_bf16 v[30:33], v[194:197], v[156:159], v[30:33]
	v_mfma_f32_16x16x32_bf16 v[22:25], v[198:201], v[146:149], v[22:25]
	v_mfma_f32_16x16x32_bf16 v[22:25], v[202:205], v[156:159], v[22:25]
	v_mfma_f32_16x16x32_bf16 v[86:89], v[198:201], v[138:141], v[86:89]
	v_mfma_f32_16x16x32_bf16 v[86:89], v[202:205], v[142:145], v[86:89]
	v_mfma_f32_16x16x32_bf16 v[78:81], v[206:209], v[138:141], v[78:81]
	v_mfma_f32_16x16x32_bf16 v[78:81], v[210:213], v[142:145], v[78:81]
	v_mfma_f32_16x16x32_bf16 v[14:17], v[206:209], v[146:149], v[14:17]
	v_mfma_f32_16x16x32_bf16 v[14:17], v[210:213], v[156:159], v[14:17]
	v_mfma_f32_16x16x32_bf16 v[6:9], v[214:217], v[146:149], v[6:9]
	v_mfma_f32_16x16x32_bf16 v[6:9], v[218:221], v[156:159], v[6:9]
	v_mfma_f32_16x16x32_bf16 v[70:73], v[214:217], v[138:141], v[70:73]
	v_mfma_f32_16x16x32_bf16 v[70:73], v[218:221], v[142:145], v[70:73]
	v_mfma_f32_16x16x32_bf16 v[90:93], v[190:193], v[160:163], v[90:93]
	v_mfma_f32_16x16x32_bf16 v[90:93], v[194:197], v[164:167], v[90:93]
	v_mfma_f32_16x16x32_bf16 v[26:29], v[190:193], v[182:185], v[26:29]
	v_mfma_f32_16x16x32_bf16 v[26:29], v[194:197], v[186:189], v[26:29]
	v_mfma_f32_16x16x32_bf16 v[18:21], v[198:201], v[182:185], v[18:21]
	v_mfma_f32_16x16x32_bf16 v[18:21], v[202:205], v[186:189], v[18:21]
	v_mfma_f32_16x16x32_bf16 v[82:85], v[198:201], v[160:163], v[82:85]
	v_mfma_f32_16x16x32_bf16 v[82:85], v[202:205], v[164:167], v[82:85]
	v_mfma_f32_16x16x32_bf16 v[74:77], v[206:209], v[160:163], v[74:77]
	v_mfma_f32_16x16x32_bf16 v[74:77], v[210:213], v[164:167], v[74:77]
	v_mfma_f32_16x16x32_bf16 v[10:13], v[206:209], v[182:185], v[10:13]
	v_mfma_f32_16x16x32_bf16 v[10:13], v[210:213], v[186:189], v[10:13]
	v_mfma_f32_16x16x32_bf16 v[2:5], v[214:217], v[182:185], v[2:5]
	v_mfma_f32_16x16x32_bf16 v[2:5], v[218:221], v[186:189], v[2:5]
	v_mfma_f32_16x16x32_bf16 v[66:69], v[214:217], v[160:163], v[66:69]
	v_mfma_f32_16x16x32_bf16 v[66:69], v[218:221], v[164:167], v[66:69]
	s_barrier
; #define PG8_STAGEX(rs, bufoff, soff, voff) do { _Pragma("unroll") for (int _i = 0; _i < 2; ++_i) \
;         __builtin_amdgcn_raw_ptr_buffer_load_lds(rs, (LAS unsigned*)(lds + (bufoff) + ldsw + _i * 8192), 16, (voff)[_i], (soff), 0, 0); } while (0)
; #define PG8_LDA(dst, b, h) do { _Pragma("unroll") for (int m = 0; m < 4; ++m) _Pragma("unroll") for (int k = 0; k < 2; ++k) dst[m][k] = *(const LAS bf16x8*)(lds + PG8_SA(b, h) + aoff + m * 2048 + k * 1024); } while (0)
; #define PG8_LDB(dst, b, h) do { _Pragma("unroll") for (int n = 0; n < 2; ++n) _Pragma("unroll") for (int k = 0; k < 2; ++k) dst[n][k] = *(const LAS bf16x8*)(lds + PG8_SB(b, h) + boff + n * 2048 + k * 1024); } while (0)
; #define PG8_WAIT_V(n) asm volatile("s_waitcnt vmcnt(" #n ")" ::: "memory")
; #define PG8_WAIT_L(n) asm volatile("s_waitcnt lgkmcnt(" #n ")" ::: "memory")
; #define PG8_BAR __builtin_amdgcn_s_barrier()
; #define PG8_SCHED __builtin_amdgcn_sched_barrier(0)
;     ...
;             PG8_LDB(B0, 1, 0); PG8_LDB(B1, 1, 1); PG8_SCHED; PG8_LDA(At, 1, 0); PG8_STAGEX(rsA, PG8_SA(0, 1), a2 + hstepA, voffA);
;             PG8_WAIT_V(8); PG8_WAIT_L(0); PG8_BAR; PG8_MMA(0, 0, At, B0); PG8_MMA(0, 1, At, B1); PG8_BAR; PG8_SCHED;
;             PG8_LDA(At, 1, 1); PG8_STAGEX(rsB, PG8_SB(1, 0), b3, voffB); PG8_STAGEX(rsB, PG8_SB(1, 1), b3 + hstepB, voffB); PG8_STAGEX(rsA, PG8_SA(1, 0), a3, voffA);
;             PG8_WAIT_V(8); PG8_WAIT_L(0); PG8_BAR; PG8_MMA(1, 0, At, B0); PG8_MMA(1, 1, At, B1); PG8_BAR; PG8_SCHED;
;         }
	s_setprio 0
	v_add_u32_e32 v150, 0x18000, v153
	ds_read_b128 v[138:141], v150
	ds_read_b128 v[142:145], v150 offset:1024
	ds_read_b128 v[146:149], v150 offset:2048
	ds_read_b128 v[156:159], v150 offset:3072
	v_add_u32_e32 v150, 0x1c000, v153
	ds_read_b128 v[160:163], v150
	ds_read_b128 v[164:167], v150 offset:1024
	ds_read_b128 v[182:185], v150 offset:2048
	ds_read_b128 v[186:189], v150 offset:3072
	s_add_i32 s50, s50, 0x40000
	s_mov_b32 m0, s20
	ds_read_b128 v[190:193], v154 offset:32768
	ds_read_b128 v[194:197], v154 offset:33792
	ds_read_b128 v[198:201], v154 offset:34816
	ds_read_b128 v[202:205], v154 offset:35840
	ds_read_b128 v[206:209], v154 offset:36864
	ds_read_b128 v[210:213], v154 offset:37888
	ds_read_b128 v[214:217], v154 offset:38912
	ds_read_b128 v[218:221], v154 offset:39936
	buffer_load_dwordx4 v130, s[76:79], s50 offen lds
	s_mov_b32 m0, s21
	s_nop 0
	buffer_load_dwordx4 v134, s[76:79], s50 offen lds
	s_waitcnt vmcnt(8)
	s_waitcnt lgkmcnt(0)
	s_setprio 1
	s_barrier
	v_mfma_f32_16x16x32_bf16 v[126:129], v[190:193], v[138:141], v[126:129]
	v_mfma_f32_16x16x32_bf16 v[126:129], v[194:197], v[142:145], v[126:129]
	v_mfma_f32_16x16x32_bf16 v[62:65], v[190:193], v[146:149], v[62:65]
	v_mfma_f32_16x16x32_bf16 v[62:65], v[194:197], v[156:159], v[62:65]
	v_mfma_f32_16x16x32_bf16 v[54:57], v[198:201], v[146:149], v[54:57]
	v_mfma_f32_16x16x32_bf16 v[54:57], v[202:205], v[156:159], v[54:57]
	v_mfma_f32_16x16x32_bf16 v[118:121], v[198:201], v[138:141], v[118:121]
	v_mfma_f32_16x16x32_bf16 v[118:121], v[202:205], v[142:145], v[118:121]
	v_mfma_f32_16x16x32_bf16 v[110:113], v[206:209], v[138:141], v[110:113]
	v_mfma_f32_16x16x32_bf16 v[110:113], v[210:213], v[142:145], v[110:113]
	v_mfma_f32_16x16x32_bf16 v[46:49], v[206:209], v[146:149], v[46:49]
	v_mfma_f32_16x16x32_bf16 v[46:49], v[210:213], v[156:159], v[46:49]
	v_mfma_f32_16x16x32_bf16 v[38:41], v[214:217], v[146:149], v[38:41]
	v_mfma_f32_16x16x32_bf16 v[38:41], v[218:221], v[156:159], v[38:41]
	v_mfma_f32_16x16x32_bf16 v[102:105], v[214:217], v[138:141], v[102:105]
	v_mfma_f32_16x16x32_bf16 v[102:105], v[218:221], v[142:145], v[102:105]
	v_mfma_f32_16x16x32_bf16 v[122:125], v[190:193], v[160:163], v[122:125]
	v_mfma_f32_16x16x32_bf16 v[122:125], v[194:197], v[164:167], v[122:125]
	v_mfma_f32_16x16x32_bf16 v[58:61], v[190:193], v[182:185], v[58:61]
	v_mfma_f32_16x16x32_bf16 v[58:61], v[194:197], v[186:189], v[58:61]
	v_mfma_f32_16x16x32_bf16 v[50:53], v[198:201], v[182:185], v[50:53]
	v_mfma_f32_16x16x32_bf16 v[50:53], v[202:205], v[186:189], v[50:53]
	v_mfma_f32_16x16x32_bf16 v[114:117], v[198:201], v[160:163], v[114:117]
	v_mfma_f32_16x16x32_bf16 v[114:117], v[202:205], v[164:167], v[114:117]
	v_mfma_f32_16x16x32_bf16 v[106:109], v[206:209], v[160:163], v[106:109]
	v_mfma_f32_16x16x32_bf16 v[106:109], v[210:213], v[164:167], v[106:109]
	v_mfma_f32_16x16x32_bf16 v[42:45], v[206:209], v[182:185], v[42:45]
	v_mfma_f32_16x16x32_bf16 v[42:45], v[210:213], v[186:189], v[42:45]
	v_mfma_f32_16x16x32_bf16 v[34:37], v[214:217], v[182:185], v[34:37]
	v_mfma_f32_16x16x32_bf16 v[34:37], v[218:221], v[186:189], v[34:37]
	v_mfma_f32_16x16x32_bf16 v[98:101], v[214:217], v[160:163], v[98:101]
	v_mfma_f32_16x16x32_bf16 v[98:101], v[218:221], v[164:167], v[98:101]
	s_barrier
	s_setprio 0
	s_mov_b32 m0, s93
	s_or_b32 s50, s49, 0x80
	ds_read_b128 v[190:193], v154 offset:49152
	ds_read_b128 v[194:197], v154 offset:50176
	ds_read_b128 v[198:201], v154 offset:51200
	ds_read_b128 v[202:205], v154 offset:52224
	ds_read_b128 v[206:209], v154 offset:53248
	ds_read_b128 v[210:213], v154 offset:54272
	ds_read_b128 v[214:217], v154 offset:55296
	ds_read_b128 v[218:221], v154 offset:56320
	buffer_load_dwordx4 v132, s[84:87], s50 offen lds
	s_mov_b32 m0, s94
	s_add_i32 s49, s49, 0x8080
	buffer_load_dwordx4 v136, s[84:87], s50 offen lds
	s_mov_b32 m0, s9
	s_nop 0
	buffer_load_dwordx4 v132, s[84:87], s49 offen lds
	s_mov_b32 m0, s54
	s_nop 0
	buffer_load_dwordx4 v136, s[84:87], s49 offen lds
	s_mov_b32 m0, s95
	s_nop 0
	buffer_load_dwordx4 v130, s[76:79], s48 offen lds
	s_mov_b32 m0, s97
	s_nop 0
	buffer_load_dwordx4 v134, s[76:79], s48 offen lds
	s_waitcnt vmcnt(8)
	s_waitcnt lgkmcnt(0)
	s_setprio 1
	s_barrier
	v_mfma_f32_16x16x32_bf16 v[94:97], v[190:193], v[138:141], v[94:97]
	v_mfma_f32_16x16x32_bf16 v[94:97], v[194:197], v[142:145], v[94:97]
	v_mfma_f32_16x16x32_bf16 v[30:33], v[190:193], v[146:149], v[30:33]
	v_mfma_f32_16x16x32_bf16 v[30:33], v[194:197], v[156:159], v[30:33]
	v_mfma_f32_16x16x32_bf16 v[22:25], v[198:201], v[146:149], v[22:25]
	v_mfma_f32_16x16x32_bf16 v[22:25], v[202:205], v[156:159], v[22:25]
	v_mfma_f32_16x16x32_bf16 v[86:89], v[198:201], v[138:141], v[86:89]
	v_mfma_f32_16x16x32_bf16 v[86:89], v[202:205], v[142:145], v[86:89]
	v_mfma_f32_16x16x32_bf16 v[78:81], v[206:209], v[138:141], v[78:81]
	v_mfma_f32_16x16x32_bf16 v[78:81], v[210:213], v[142:145], v[78:81]
	v_mfma_f32_16x16x32_bf16 v[14:17], v[206:209], v[146:149], v[14:17]
	v_mfma_f32_16x16x32_bf16 v[14:17], v[210:213], v[156:159], v[14:17]
	v_mfma_f32_16x16x32_bf16 v[6:9], v[214:217], v[146:149], v[6:9]
	v_mfma_f32_16x16x32_bf16 v[6:9], v[218:221], v[156:159], v[6:9]
	v_mfma_f32_16x16x32_bf16 v[70:73], v[214:217], v[138:141], v[70:73]
	v_mfma_f32_16x16x32_bf16 v[70:73], v[218:221], v[142:145], v[70:73]
	v_mfma_f32_16x16x32_bf16 v[90:93], v[190:193], v[160:163], v[90:93]
	v_mfma_f32_16x16x32_bf16 v[90:93], v[194:197], v[164:167], v[90:93]
	v_mfma_f32_16x16x32_bf16 v[26:29], v[190:193], v[182:185], v[26:29]
	v_mfma_f32_16x16x32_bf16 v[26:29], v[194:197], v[186:189], v[26:29]
	v_mfma_f32_16x16x32_bf16 v[18:21], v[198:201], v[182:185], v[18:21]
	v_mfma_f32_16x16x32_bf16 v[18:21], v[202:205], v[186:189], v[18:21]
	v_mfma_f32_16x16x32_bf16 v[82:85], v[198:201], v[160:163], v[82:85]
	v_mfma_f32_16x16x32_bf16 v[82:85], v[202:205], v[164:167], v[82:85]
	v_mfma_f32_16x16x32_bf16 v[74:77], v[206:209], v[160:163], v[74:77]
	v_mfma_f32_16x16x32_bf16 v[74:77], v[210:213], v[164:167], v[74:77]
	v_mfma_f32_16x16x32_bf16 v[10:13], v[206:209], v[182:185], v[10:13]
	v_mfma_f32_16x16x32_bf16 v[10:13], v[210:213], v[186:189], v[10:13]
	v_mfma_f32_16x16x32_bf16 v[2:5], v[214:217], v[182:185], v[2:5]
	v_mfma_f32_16x16x32_bf16 v[2:5], v[218:221], v[186:189], v[2:5]
	v_mfma_f32_16x16x32_bf16 v[66:69], v[214:217], v[160:163], v[66:69]
	v_mfma_f32_16x16x32_bf16 v[66:69], v[218:221], v[164:167], v[66:69]
	s_barrier
	s_setprio 0
	s_add_i32 s47, s47, 2
	s_addk_i32 s31, 0x100
	s_addk_i32 s46, 0x100
	s_cmp_ge_i32 s47, s34
	s_cbranch_scc0 .LBB0_788
	s_mov_b32 s61, s96
	s_and_b64 vcc, exec, s[62:63]
	s_cbranch_vccz .LBB0_791

; #define PG8_STAGEX(rs, bufoff, soff, voff) do { _Pragma("unroll") for (int _i = 0; _i < 2; ++_i) \
;         __builtin_amdgcn_raw_ptr_buffer_load_lds(rs, (LAS unsigned*)(lds + (bufoff) + ldsw + _i * 8192), 16, (voff)[_i], (soff), 0, 0); } while (0)
; #define PG8_LDA(dst, b, h) do { _Pragma("unroll") for (int m = 0; m < 4; ++m) _Pragma("unroll") for (int k = 0; k < 2; ++k) dst[m][k] = *(const LAS bf16x8*)(lds + PG8_SA(b, h) + aoff + m * 2048 + k * 1024); } while (0)
; #define PG8_LDB(dst, b, h) do { _Pragma("unroll") for (int n = 0; n < 2; ++n) _Pragma("unroll") for (int k = 0; k < 2; ++k) dst[n][k] = *(const LAS bf16x8*)(lds + PG8_SB(b, h) + boff + n * 2048 + k * 1024); } while (0)
; #define PG8_WAIT_V(n) asm volatile("s_waitcnt vmcnt(" #n ")" ::: "memory")
; #define PG8_WAIT_L(n) asm volatile("s_waitcnt lgkmcnt(" #n ")" ::: "memory")
; #define PG8_BAR __builtin_amdgcn_s_barrier()
; #define PG8_SCHED __builtin_amdgcn_sched_barrier(0)
;     ...
;         for (int t = 0; t < nt; t += 2) {
;             const bool last = (t == nt - 2);
;             const unsigned a1 = cA + (unsigned)(t + 1) * kstep;
;             const unsigned a2 = last ? nA : cA + (unsigned)(t + 2) * kstep, b2 = last ? nB : cB + (unsigned)(t + 2) * kstep;
;             const unsigned a3 = a2 + kstep, b3 = b2 + kstep;
;             PG8_LDB(B0, 0, 0); PG8_LDB(B1, 0, 1); PG8_SCHED; PG8_LDA(At, 0, 0); PG8_STAGEX(rsA, PG8_SA(1, 1), a1 + hstepA, voffA);
;             PG8_WAIT_V(8); PG8_WAIT_L(0); PG8_BAR; PG8_MMA(0, 0, At, B0); PG8_MMA(0, 1, At, B1); PG8_BAR; PG8_SCHED;
;             PG8_LDA(At, 0, 1); PG8_STAGEX(rsB, PG8_SB(0, 0), b2, voffB); PG8_STAGEX(rsB, PG8_SB(0, 1), b2 + hstepB, voffB); PG8_STAGEX(rsA, PG8_SA(0, 0), a2, voffA);
;             PG8_WAIT_V(8); PG8_WAIT_L(0); PG8_BAR; PG8_MMA(1, 0, At, B0); PG8_MMA(1, 1, At, B1); PG8_BAR; PG8_SCHED;
.LBB0_1274:
	v_add_u32_e32 v142, 0x10000, v157
	v_add_u32_e32 v159, 0x14000, v157
	ds_read_b128 v[130:133], v142
	ds_read_b128 v[134:137], v142 offset:1024
	ds_read_b128 v[138:141], v142 offset:2048
	ds_read_b128 v[142:145], v142 offset:3072
	ds_read_b128 v[146:149], v159
	ds_read_b128 v[164:167], v159 offset:1024
	ds_read_b128 v[168:171], v159 offset:2048
	ds_read_b128 v[182:185], v159 offset:3072
	s_add_i32 s42, s62, 0xfff80080
	s_cmp_eq_u32 s67, 28
	s_cselect_b32 s70, s30, s42
	s_cselect_b32 s69, s31, s63
	s_or_b32 s68, s70, 0x80
	s_mov_b32 m0, s29
	ds_read_b128 v[186:189], v158
	ds_read_b128 v[190:193], v158 offset:1024
	ds_read_b128 v[194:197], v158 offset:2048
	ds_read_b128 v[198:201], v158 offset:3072
	ds_read_b128 v[202:205], v158 offset:4096
	ds_read_b128 v[206:209], v158 offset:5120
	ds_read_b128 v[210:213], v158 offset:6144
	ds_read_b128 v[214:217], v158 offset:7168
	buffer_load_dwordx4 v150, s[76:79], s62 offen lds
	s_mov_b32 m0, s35
	s_nop 0
	buffer_load_dwordx4 v152, s[76:79], s62 offen lds
	s_waitcnt vmcnt(8)
	s_waitcnt lgkmcnt(0)
	s_setprio 1
	s_barrier
	v_mfma_f32_16x16x32_bf16 v[126:129], v[130:133], v[186:189], v[126:129]
	v_mfma_f32_16x16x32_bf16 v[126:129], v[134:137], v[190:193], v[126:129]
	v_mfma_f32_16x16x32_bf16 v[122:125], v[138:141], v[186:189], v[122:125]
	v_mfma_f32_16x16x32_bf16 v[122:125], v[142:145], v[190:193], v[122:125]
	v_mfma_f32_16x16x32_bf16 v[114:117], v[138:141], v[194:197], v[114:117]
	v_mfma_f32_16x16x32_bf16 v[114:117], v[142:145], v[198:201], v[114:117]
	v_mfma_f32_16x16x32_bf16 v[118:121], v[130:133], v[194:197], v[118:121]
	v_mfma_f32_16x16x32_bf16 v[118:121], v[134:137], v[198:201], v[118:121]
	v_mfma_f32_16x16x32_bf16 v[110:113], v[130:133], v[202:205], v[110:113]
	v_mfma_f32_16x16x32_bf16 v[110:113], v[134:137], v[206:209], v[110:113]
	v_mfma_f32_16x16x32_bf16 v[106:109], v[138:141], v[202:205], v[106:109]
	v_mfma_f32_16x16x32_bf16 v[106:109], v[142:145], v[206:209], v[106:109]
	v_mfma_f32_16x16x32_bf16 v[98:101], v[138:141], v[210:213], v[98:101]
	v_mfma_f32_16x16x32_bf16 v[98:101], v[142:145], v[214:217], v[98:101]
	v_mfma_f32_16x16x32_bf16 v[102:105], v[130:133], v[210:213], v[102:105]
	v_mfma_f32_16x16x32_bf16 v[102:105], v[134:137], v[214:217], v[102:105]
	v_mfma_f32_16x16x32_bf16 v[62:65], v[146:149], v[186:189], v[62:65]
	v_mfma_f32_16x16x32_bf16 v[62:65], v[164:167], v[190:193], v[62:65]
	v_mfma_f32_16x16x32_bf16 v[58:61], v[168:171], v[186:189], v[58:61]
	v_mfma_f32_16x16x32_bf16 v[58:61], v[182:185], v[190:193], v[58:61]
	v_mfma_f32_16x16x32_bf16 v[50:53], v[168:171], v[194:197], v[50:53]
	v_mfma_f32_16x16x32_bf16 v[50:53], v[182:185], v[198:201], v[50:53]
	v_mfma_f32_16x16x32_bf16 v[54:57], v[146:149], v[194:197], v[54:57]
	v_mfma_f32_16x16x32_bf16 v[54:57], v[164:167], v[198:201], v[54:57]
	v_mfma_f32_16x16x32_bf16 v[46:49], v[146:149], v[202:205], v[46:49]
	v_mfma_f32_16x16x32_bf16 v[46:49], v[164:167], v[206:209], v[46:49]
	v_mfma_f32_16x16x32_bf16 v[42:45], v[168:171], v[202:205], v[42:45]
	v_mfma_f32_16x16x32_bf16 v[42:45], v[182:185], v[206:209], v[42:45]
	v_mfma_f32_16x16x32_bf16 v[34:37], v[168:171], v[210:213], v[34:37]
	v_mfma_f32_16x16x32_bf16 v[34:37], v[182:185], v[214:217], v[34:37]
	v_mfma_f32_16x16x32_bf16 v[38:41], v[146:149], v[210:213], v[38:41]
	v_mfma_f32_16x16x32_bf16 v[38:41], v[164:167], v[214:217], v[38:41]
	s_barrier
	s_setprio 0
	s_mov_b32 m0, s16
	s_mov_b32 s42, s78
	s_mov_b32 s43, s79
	ds_read_b128 v[186:189], v158 offset:16384
	ds_read_b128 v[190:193], v158 offset:17408
	ds_read_b128 v[194:197], v158 offset:18432
	ds_read_b128 v[198:201], v158 offset:19456
	ds_read_b128 v[202:205], v158 offset:20480
	ds_read_b128 v[206:209], v158 offset:21504
	ds_read_b128 v[210:213], v158 offset:22528
	ds_read_b128 v[214:217], v158 offset:23552
	buffer_load_dwordx4 v151, s[40:43], s69 offen lds
	s_mov_b32 m0, s17
	s_add_i32 s71, s69, 0x80000
	buffer_load_dwordx4 v153, s[40:43], s69 offen lds
	s_mov_b32 m0, s18
	s_nop 0
	buffer_load_dwordx4 v151, s[40:43], s71 offen lds
	s_mov_b32 m0, s19
	s_nop 0
	buffer_load_dwordx4 v153, s[40:43], s71 offen lds
	s_mov_b32 m0, s15
	s_nop 0
	buffer_load_dwordx4 v150, s[76:79], s70 offen lds
	s_mov_b32 m0, s20
	s_nop 0
	buffer_load_dwordx4 v152, s[76:79], s70 offen lds
	s_waitcnt vmcnt(8)
	s_waitcnt lgkmcnt(0)
	s_setprio 1
	s_barrier
	v_mfma_f32_16x16x32_bf16 v[94:97], v[130:133], v[186:189], v[94:97]
	v_mfma_f32_16x16x32_bf16 v[94:97], v[134:137], v[190:193], v[94:97]
	v_mfma_f32_16x16x32_bf16 v[90:93], v[138:141], v[186:189], v[90:93]
	v_mfma_f32_16x16x32_bf16 v[90:93], v[142:145], v[190:193], v[90:93]
	v_mfma_f32_16x16x32_bf16 v[82:85], v[138:141], v[194:197], v[82:85]
	v_mfma_f32_16x16x32_bf16 v[82:85], v[142:145], v[198:201], v[82:85]
	v_mfma_f32_16x16x32_bf16 v[86:89], v[130:133], v[194:197], v[86:89]
	v_mfma_f32_16x16x32_bf16 v[86:89], v[134:137], v[198:201], v[86:89]
	v_mfma_f32_16x16x32_bf16 v[78:81], v[130:133], v[202:205], v[78:81]
	v_mfma_f32_16x16x32_bf16 v[78:81], v[134:137], v[206:209], v[78:81]
	v_mfma_f32_16x16x32_bf16 v[74:77], v[138:141], v[202:205], v[74:77]
	v_mfma_f32_16x16x32_bf16 v[74:77], v[142:145], v[206:209], v[74:77]
	v_mfma_f32_16x16x32_bf16 v[66:69], v[138:141], v[210:213], v[66:69]
	v_mfma_f32_16x16x32_bf16 v[66:69], v[142:145], v[214:217], v[66:69]
	v_mfma_f32_16x16x32_bf16 v[70:73], v[130:133], v[210:213], v[70:73]
	v_mfma_f32_16x16x32_bf16 v[70:73], v[134:137], v[214:217], v[70:73]
	v_mfma_f32_16x16x32_bf16 v[30:33], v[146:149], v[186:189], v[30:33]
	v_mfma_f32_16x16x32_bf16 v[30:33], v[164:167], v[190:193], v[30:33]
	v_mfma_f32_16x16x32_bf16 v[26:29], v[168:171], v[186:189], v[26:29]
	v_mfma_f32_16x16x32_bf16 v[26:29], v[182:185], v[190:193], v[26:29]
	v_mfma_f32_16x16x32_bf16 v[18:21], v[168:171], v[194:197], v[18:21]
	v_mfma_f32_16x16x32_bf16 v[18:21], v[182:185], v[198:201], v[18:21]
	v_mfma_f32_16x16x32_bf16 v[22:25], v[146:149], v[194:197], v[22:25]
	v_mfma_f32_16x16x32_bf16 v[22:25], v[164:167], v[198:201], v[22:25]
	v_mfma_f32_16x16x32_bf16 v[14:17], v[146:149], v[202:205], v[14:17]
	v_mfma_f32_16x16x32_bf16 v[14:17], v[164:167], v[206:209], v[14:17]
	v_mfma_f32_16x16x32_bf16 v[10:13], v[168:171], v[202:205], v[10:13]
	v_mfma_f32_16x16x32_bf16 v[10:13], v[182:185], v[206:209], v[10:13]
	v_mfma_f32_16x16x32_bf16 v[2:5], v[168:171], v[210:213], v[2:5]
	v_mfma_f32_16x16x32_bf16 v[2:5], v[182:185], v[214:217], v[2:5]
	v_mfma_f32_16x16x32_bf16 v[6:9], v[146:149], v[210:213], v[6:9]
	v_mfma_f32_16x16x32_bf16 v[6:9], v[164:167], v[214:217], v[6:9]
	s_barrier
; #define PG8_STAGEX(rs, bufoff, soff, voff) do { _Pragma("unroll") for (int _i = 0; _i < 2; ++_i) \
;         __builtin_amdgcn_raw_ptr_buffer_load_lds(rs, (LAS unsigned*)(lds + (bufoff) + ldsw + _i * 8192), 16, (voff)[_i], (soff), 0, 0); } while (0)
; #define PG8_LDA(dst, b, h) do { _Pragma("unroll") for (int m = 0; m < 4; ++m) _Pragma("unroll") for (int k = 0; k < 2; ++k) dst[m][k] = *(const LAS bf16x8*)(lds + PG8_SA(b, h) + aoff + m * 2048 + k * 1024); } while (0)
; #define PG8_LDB(dst, b, h) do { _Pragma("unroll") for (int n = 0; n < 2; ++n) _Pragma("unroll") for (int k = 0; k < 2; ++k) dst[n][k] = *(const LAS bf16x8*)(lds + PG8_SB(b, h) + boff + n * 2048 + k * 1024); } while (0)
; #define PG8_WAIT_V(n) asm volatile("s_waitcnt vmcnt(" #n ")" ::: "memory")
; #define PG8_WAIT_L(n) asm volatile("s_waitcnt lgkmcnt(" #n ")" ::: "memory")
; #define PG8_BAR __builtin_amdgcn_s_barrier()
; #define PG8_SCHED __builtin_amdgcn_sched_barrier(0)
;     ...
;             PG8_LDB(B0, 1, 0); PG8_LDB(B1, 1, 1); PG8_SCHED; PG8_LDA(At, 1, 0); PG8_STAGEX(rsA, PG8_SA(0, 1), a2 + hstepA, voffA);
;             PG8_WAIT_V(8); PG8_WAIT_L(0); PG8_BAR; PG8_MMA(0, 0, At, B0); PG8_MMA(0, 1, At, B1); PG8_BAR; PG8_SCHED;
;             PG8_LDA(At, 1, 1); PG8_STAGEX(rsB, PG8_SB(1, 0), b3, voffB); PG8_STAGEX(rsB, PG8_SB(1, 1), b3 + hstepB, voffB); PG8_STAGEX(rsA, PG8_SA(1, 0), a3, voffA);
;             PG8_WAIT_V(8); PG8_WAIT_L(0); PG8_BAR; PG8_MMA(1, 0, At, B0); PG8_MMA(1, 1, At, B1); PG8_BAR; PG8_SCHED;
;         }
	s_setprio 0
	v_add_u32_e32 v142, 0x18000, v157
	v_add_u32_e32 v159, 0x1c000, v157
	ds_read_b128 v[130:133], v142
	ds_read_b128 v[134:137], v142 offset:1024
	ds_read_b128 v[138:141], v142 offset:2048
	ds_read_b128 v[142:145], v142 offset:3072
	ds_read_b128 v[146:149], v159
	ds_read_b128 v[164:167], v159 offset:1024
	ds_read_b128 v[168:171], v159 offset:2048
	ds_read_b128 v[182:185], v159 offset:3072
	s_add_i32 s70, s70, 0x80000
	s_mov_b32 m0, s21
	ds_read_b128 v[186:189], v158 offset:32768
	ds_read_b128 v[190:193], v158 offset:33792
	ds_read_b128 v[194:197], v158 offset:34816
	ds_read_b128 v[198:201], v158 offset:35840
	ds_read_b128 v[202:205], v158 offset:36864
	ds_read_b128 v[206:209], v158 offset:37888
	ds_read_b128 v[210:213], v158 offset:38912
	ds_read_b128 v[214:217], v158 offset:39936
	buffer_load_dwordx4 v150, s[76:79], s70 offen lds
	s_mov_b32 m0, s22
	s_nop 0
	buffer_load_dwordx4 v152, s[76:79], s70 offen lds
	s_waitcnt vmcnt(8)
	s_waitcnt lgkmcnt(0)
	s_setprio 1
	s_barrier
	v_mfma_f32_16x16x32_bf16 v[126:129], v[130:133], v[186:189], v[126:129]
	v_mfma_f32_16x16x32_bf16 v[126:129], v[134:137], v[190:193], v[126:129]
	v_mfma_f32_16x16x32_bf16 v[122:125], v[138:141], v[186:189], v[122:125]
	v_mfma_f32_16x16x32_bf16 v[122:125], v[142:145], v[190:193], v[122:125]
	v_mfma_f32_16x16x32_bf16 v[114:117], v[138:141], v[194:197], v[114:117]
	v_mfma_f32_16x16x32_bf16 v[114:117], v[142:145], v[198:201], v[114:117]
	v_mfma_f32_16x16x32_bf16 v[118:121], v[130:133], v[194:197], v[118:121]
	v_mfma_f32_16x16x32_bf16 v[118:121], v[134:137], v[198:201], v[118:121]
	v_mfma_f32_16x16x32_bf16 v[110:113], v[130:133], v[202:205], v[110:113]
	v_mfma_f32_16x16x32_bf16 v[110:113], v[134:137], v[206:209], v[110:113]
	v_mfma_f32_16x16x32_bf16 v[106:109], v[138:141], v[202:205], v[106:109]
	v_mfma_f32_16x16x32_bf16 v[106:109], v[142:145], v[206:209], v[106:109]
	v_mfma_f32_16x16x32_bf16 v[98:101], v[138:141], v[210:213], v[98:101]
	v_mfma_f32_16x16x32_bf16 v[98:101], v[142:145], v[214:217], v[98:101]
	v_mfma_f32_16x16x32_bf16 v[102:105], v[130:133], v[210:213], v[102:105]
	v_mfma_f32_16x16x32_bf16 v[102:105], v[134:137], v[214:217], v[102:105]
	v_mfma_f32_16x16x32_bf16 v[62:65], v[146:149], v[186:189], v[62:65]
	v_mfma_f32_16x16x32_bf16 v[62:65], v[164:167], v[190:193], v[62:65]
	v_mfma_f32_16x16x32_bf16 v[58:61], v[168:171], v[186:189], v[58:61]
	v_mfma_f32_16x16x32_bf16 v[58:61], v[182:185], v[190:193], v[58:61]
	v_mfma_f32_16x16x32_bf16 v[50:53], v[168:171], v[194:197], v[50:53]
	v_mfma_f32_16x16x32_bf16 v[50:53], v[182:185], v[198:201], v[50:53]
	v_mfma_f32_16x16x32_bf16 v[54:57], v[146:149], v[194:197], v[54:57]
	v_mfma_f32_16x16x32_bf16 v[54:57], v[164:167], v[198:201], v[54:57]
	v_mfma_f32_16x16x32_bf16 v[46:49], v[146:149], v[202:205], v[46:49]
	v_mfma_f32_16x16x32_bf16 v[46:49], v[164:167], v[206:209], v[46:49]
	v_mfma_f32_16x16x32_bf16 v[42:45], v[168:171], v[202:205], v[42:45]
	v_mfma_f32_16x16x32_bf16 v[42:45], v[182:185], v[206:209], v[42:45]
	v_mfma_f32_16x16x32_bf16 v[34:37], v[168:171], v[210:213], v[34:37]
	v_mfma_f32_16x16x32_bf16 v[34:37], v[182:185], v[214:217], v[34:37]
	v_mfma_f32_16x16x32_bf16 v[38:41], v[146:149], v[210:213], v[38:41]
	v_mfma_f32_16x16x32_bf16 v[38:41], v[164:167], v[214:217], v[38:41]
	s_barrier
	s_setprio 0
	s_mov_b32 m0, s23
	s_or_b32 s70, s69, 0x80
	ds_read_b128 v[186:189], v158 offset:49152
	ds_read_b128 v[190:193], v158 offset:50176
	ds_read_b128 v[194:197], v158 offset:51200
	ds_read_b128 v[198:201], v158 offset:52224
	ds_read_b128 v[202:205], v158 offset:53248
	ds_read_b128 v[206:209], v158 offset:54272
	ds_read_b128 v[210:213], v158 offset:55296
	ds_read_b128 v[214:217], v158 offset:56320
	buffer_load_dwordx4 v151, s[40:43], s70 offen lds
	s_mov_b32 m0, s24
	s_add_i32 s69, s69, 0x80080
	buffer_load_dwordx4 v153, s[40:43], s70 offen lds
	s_mov_b32 m0, s27
	s_nop 0
	buffer_load_dwordx4 v151, s[40:43], s69 offen lds
	s_mov_b32 m0, s28
	s_nop 0
	buffer_load_dwordx4 v153, s[40:43], s69 offen lds
	s_mov_b32 m0, s25
	s_nop 0
	buffer_load_dwordx4 v150, s[76:79], s68 offen lds
	s_mov_b32 m0, s26
	s_nop 0
	buffer_load_dwordx4 v152, s[76:79], s68 offen lds
	s_waitcnt vmcnt(8)
	s_waitcnt lgkmcnt(0)
	s_setprio 1
	s_barrier
	v_mfma_f32_16x16x32_bf16 v[94:97], v[130:133], v[186:189], v[94:97]
	v_mfma_f32_16x16x32_bf16 v[94:97], v[134:137], v[190:193], v[94:97]
	v_mfma_f32_16x16x32_bf16 v[90:93], v[138:141], v[186:189], v[90:93]
	v_mfma_f32_16x16x32_bf16 v[90:93], v[142:145], v[190:193], v[90:93]
	v_mfma_f32_16x16x32_bf16 v[82:85], v[138:141], v[194:197], v[82:85]
	v_mfma_f32_16x16x32_bf16 v[82:85], v[142:145], v[198:201], v[82:85]
	v_mfma_f32_16x16x32_bf16 v[86:89], v[130:133], v[194:197], v[86:89]
	v_mfma_f32_16x16x32_bf16 v[86:89], v[134:137], v[198:201], v[86:89]
	v_mfma_f32_16x16x32_bf16 v[78:81], v[130:133], v[202:205], v[78:81]
	v_mfma_f32_16x16x32_bf16 v[78:81], v[134:137], v[206:209], v[78:81]
	v_mfma_f32_16x16x32_bf16 v[74:77], v[138:141], v[202:205], v[74:77]
	v_mfma_f32_16x16x32_bf16 v[74:77], v[142:145], v[206:209], v[74:77]
	v_mfma_f32_16x16x32_bf16 v[66:69], v[138:141], v[210:213], v[66:69]
	v_mfma_f32_16x16x32_bf16 v[66:69], v[142:145], v[214:217], v[66:69]
	v_mfma_f32_16x16x32_bf16 v[70:73], v[130:133], v[210:213], v[70:73]
	v_mfma_f32_16x16x32_bf16 v[70:73], v[134:137], v[214:217], v[70:73]
	v_mfma_f32_16x16x32_bf16 v[30:33], v[146:149], v[186:189], v[30:33]
	v_mfma_f32_16x16x32_bf16 v[30:33], v[164:167], v[190:193], v[30:33]
	v_mfma_f32_16x16x32_bf16 v[26:29], v[168:171], v[186:189], v[26:29]
	v_mfma_f32_16x16x32_bf16 v[26:29], v[182:185], v[190:193], v[26:29]
	v_mfma_f32_16x16x32_bf16 v[18:21], v[168:171], v[194:197], v[18:21]
	v_mfma_f32_16x16x32_bf16 v[18:21], v[182:185], v[198:201], v[18:21]
	v_mfma_f32_16x16x32_bf16 v[22:25], v[146:149], v[194:197], v[22:25]
	v_mfma_f32_16x16x32_bf16 v[22:25], v[164:167], v[198:201], v[22:25]
	v_mfma_f32_16x16x32_bf16 v[14:17], v[146:149], v[202:205], v[14:17]
	v_mfma_f32_16x16x32_bf16 v[14:17], v[164:167], v[206:209], v[14:17]
	v_mfma_f32_16x16x32_bf16 v[10:13], v[168:171], v[202:205], v[10:13]
	v_mfma_f32_16x16x32_bf16 v[10:13], v[182:185], v[206:209], v[10:13]
	v_mfma_f32_16x16x32_bf16 v[2:5], v[168:171], v[210:213], v[2:5]
	v_mfma_f32_16x16x32_bf16 v[2:5], v[182:185], v[214:217], v[2:5]
	v_mfma_f32_16x16x32_bf16 v[6:9], v[146:149], v[210:213], v[6:9]
	v_mfma_f32_16x16x32_bf16 v[6:9], v[164:167], v[214:217], v[6:9]
	s_barrier
	s_setprio 0
	s_add_i32 s67, s67, 2
	s_addk_i32 s62, 0x100
	s_addk_i32 s63, 0x100
	s_cmp_gt_u32 s67, 29
	s_cbranch_scc0 .LBB0_1274
	s_and_b64 vcc, exec, s[50:51]
	s_cbranch_vccz .LBB0_1277
	s_barrier

; #define PG8_STAGEX(rs, bufoff, soff, voff) do { _Pragma("unroll") for (int _i = 0; _i < 2; ++_i) \
;         __builtin_amdgcn_raw_ptr_buffer_load_lds(rs, (LAS unsigned*)(lds + (bufoff) + ldsw + _i * 8192), 16, (voff)[_i], (soff), 0, 0); } while (0)
; #define PG8_LDA(dst, b, h) do { _Pragma("unroll") for (int m = 0; m < 4; ++m) _Pragma("unroll") for (int k = 0; k < 2; ++k) dst[m][k] = *(const LAS bf16x8*)(lds + PG8_SA(b, h) + aoff + m * 2048 + k * 1024); } while (0)
; #define PG8_LDB(dst, b, h) do { _Pragma("unroll") for (int n = 0; n < 2; ++n) _Pragma("unroll") for (int k = 0; k < 2; ++k) dst[n][k] = *(const LAS bf16x8*)(lds + PG8_SB(b, h) + boff + n * 2048 + k * 1024); } while (0)
; #define PG8_WAIT_V(n) asm volatile("s_waitcnt vmcnt(" #n ")" ::: "memory")
; #define PG8_WAIT_L(n) asm volatile("s_waitcnt lgkmcnt(" #n ")" ::: "memory")
; #define PG8_BAR __builtin_amdgcn_s_barrier()
; #define PG8_SCHED __builtin_amdgcn_sched_barrier(0)
;     ...
;             for (int t = 0; t < nt; t += 2) {
;                 const bool last = (t == nt - 2);
;                 const unsigned a1 = cA + (unsigned)(t + 1) * kstep;
;                 const unsigned a2 = last ? nA : cA + (unsigned)(t + 2) * kstep, b2 = last ? nB : cB + (unsigned)(t + 2) * kstep;
;                 const unsigned a3 = a2 + kstep, b3 = b2 + kstep;
;                 if (w0) { PG8_LDB(B0, 0, 0); PG8_LDB(B1, 0, 1); PG8_SCHED; PG8_LDA(At, 0, 0); }
;                 PG8_WAIT_L(0); PG8_BAR; if (w0) { PG8_MMA(0, 0, At, B0); PG8_MMA(0, 1, At, B1); } PG8_BAR; PG8_SCHED;
;                 PG8_STAGEX(rsB, PG8_SB(0, 0), b2, voffB); PG8_STAGEX(rsB, PG8_SB(0, 1), b2 + hstepB, voffB); PG8_STAGEX(rsA, PG8_SA(0, 0), a2, voffA);
;                 PG8_WAIT_V(6); PG8_BAR; PG8_BAR; PG8_SCHED;
.LBB0_1287:
	v_add_u32_e32 v86, 0x10000, v72
	v_add_u32_e32 v102, 0x14000, v72
	ds_read_b128 v[74:77], v86
	ds_read_b128 v[78:81], v86 offset:1024
	ds_read_b128 v[82:85], v86 offset:2048
	ds_read_b128 v[86:89], v86 offset:3072
	ds_read_b128 v[90:93], v102
	ds_read_b128 v[94:97], v102 offset:1024
	ds_read_b128 v[98:101], v102 offset:2048
	ds_read_b128 v[102:105], v102 offset:3072
	s_cmp_lg_u32 s29, 28
	s_cselect_b32 s30, s28, 0
	s_add_i32 s31, s30, s19
	s_or_b32 s35, s31, 0x80
	s_add_i32 s30, s30, s13
	ds_read_b128 v[106:109], v73
	ds_read_b128 v[110:113], v73 offset:1024
	ds_read_b128 v[114:117], v73 offset:2048
	ds_read_b128 v[118:121], v73 offset:3072
	ds_read_b128 v[122:125], v73 offset:4096
	ds_read_b128 v[126:129], v73 offset:5120
	ds_read_b128 v[130:133], v73 offset:6144
	ds_read_b128 v[134:137], v73 offset:7168
	s_waitcnt lgkmcnt(0)
	s_setprio 1
	s_barrier
	v_mfma_f32_16x16x32_bf16 v[62:65], v[74:77], v[106:109], v[62:65]
	v_mfma_f32_16x16x32_bf16 v[62:65], v[78:81], v[110:113], v[62:65]
	v_mfma_f32_16x16x32_bf16 v[58:61], v[82:85], v[106:109], v[58:61]
	v_mfma_f32_16x16x32_bf16 v[58:61], v[86:89], v[110:113], v[58:61]
	v_mfma_f32_16x16x32_bf16 v[50:53], v[82:85], v[114:117], v[50:53]
	v_mfma_f32_16x16x32_bf16 v[50:53], v[86:89], v[118:121], v[50:53]
	v_mfma_f32_16x16x32_bf16 v[54:57], v[74:77], v[114:117], v[54:57]
	v_mfma_f32_16x16x32_bf16 v[54:57], v[78:81], v[118:121], v[54:57]
	v_mfma_f32_16x16x32_bf16 v[46:49], v[74:77], v[122:125], v[46:49]
	v_mfma_f32_16x16x32_bf16 v[46:49], v[78:81], v[126:129], v[46:49]
	v_mfma_f32_16x16x32_bf16 v[42:45], v[82:85], v[122:125], v[42:45]
	v_mfma_f32_16x16x32_bf16 v[42:45], v[86:89], v[126:129], v[42:45]
	v_mfma_f32_16x16x32_bf16 v[34:37], v[82:85], v[130:133], v[34:37]
	v_mfma_f32_16x16x32_bf16 v[34:37], v[86:89], v[134:137], v[34:37]
	v_mfma_f32_16x16x32_bf16 v[38:41], v[74:77], v[130:133], v[38:41]
	v_mfma_f32_16x16x32_bf16 v[38:41], v[78:81], v[134:137], v[38:41]
	v_mfma_f32_16x16x32_bf16 v[30:33], v[90:93], v[106:109], v[30:33]
	v_mfma_f32_16x16x32_bf16 v[30:33], v[94:97], v[110:113], v[30:33]
	v_mfma_f32_16x16x32_bf16 v[26:29], v[98:101], v[106:109], v[26:29]
	v_mfma_f32_16x16x32_bf16 v[26:29], v[102:105], v[110:113], v[26:29]
	v_mfma_f32_16x16x32_bf16 v[18:21], v[98:101], v[114:117], v[18:21]
	v_mfma_f32_16x16x32_bf16 v[18:21], v[102:105], v[118:121], v[18:21]
	v_mfma_f32_16x16x32_bf16 v[22:25], v[90:93], v[114:117], v[22:25]
	v_mfma_f32_16x16x32_bf16 v[22:25], v[94:97], v[118:121], v[22:25]
	v_mfma_f32_16x16x32_bf16 v[14:17], v[90:93], v[122:125], v[14:17]
	v_mfma_f32_16x16x32_bf16 v[14:17], v[94:97], v[126:129], v[14:17]
	v_mfma_f32_16x16x32_bf16 v[10:13], v[98:101], v[122:125], v[10:13]
	v_mfma_f32_16x16x32_bf16 v[10:13], v[102:105], v[126:129], v[10:13]
	v_mfma_f32_16x16x32_bf16 v[2:5], v[98:101], v[130:133], v[2:5]
	v_mfma_f32_16x16x32_bf16 v[2:5], v[102:105], v[134:137], v[2:5]
	v_mfma_f32_16x16x32_bf16 v[6:9], v[90:93], v[130:133], v[6:9]
	v_mfma_f32_16x16x32_bf16 v[6:9], v[94:97], v[134:137], v[6:9]
	s_barrier
	s_setprio 0
	s_mov_b32 m0, s15
	s_mov_b32 s42, s78
	s_mov_b32 s43, s79
	buffer_load_dwordx4 v67, s[40:43], s30 offen lds
	s_mov_b32 m0, s16
	s_add_i32 s38, s30, 0x80000
	buffer_load_dwordx4 v69, s[40:43], s30 offen lds
	s_mov_b32 m0, s17
	s_nop 0
	buffer_load_dwordx4 v67, s[40:43], s38 offen lds
	s_mov_b32 m0, s18
	s_nop 0
	buffer_load_dwordx4 v69, s[40:43], s38 offen lds
	s_mov_b32 m0, s14
	s_nop 0
	buffer_load_dwordx4 v66, s[76:79], s31 offen lds
	s_mov_b32 m0, s20
	s_nop 0
	buffer_load_dwordx4 v68, s[76:79], s31 offen lds
	s_waitcnt vmcnt(6)
	s_barrier
	s_barrier
; #define PG8_STAGEX(rs, bufoff, soff, voff) do { _Pragma("unroll") for (int _i = 0; _i < 2; ++_i) \
;         __builtin_amdgcn_raw_ptr_buffer_load_lds(rs, (LAS unsigned*)(lds + (bufoff) + ldsw + _i * 8192), 16, (voff)[_i], (soff), 0, 0); } while (0)
; #define PG8_LDA(dst, b, h) do { _Pragma("unroll") for (int m = 0; m < 4; ++m) _Pragma("unroll") for (int k = 0; k < 2; ++k) dst[m][k] = *(const LAS bf16x8*)(lds + PG8_SA(b, h) + aoff + m * 2048 + k * 1024); } while (0)
; #define PG8_LDB(dst, b, h) do { _Pragma("unroll") for (int n = 0; n < 2; ++n) _Pragma("unroll") for (int k = 0; k < 2; ++k) dst[n][k] = *(const LAS bf16x8*)(lds + PG8_SB(b, h) + boff + n * 2048 + k * 1024); } while (0)
; #define PG8_WAIT_V(n) asm volatile("s_waitcnt vmcnt(" #n ")" ::: "memory")
; #define PG8_WAIT_L(n) asm volatile("s_waitcnt lgkmcnt(" #n ")" ::: "memory")
; #define PG8_BAR __builtin_amdgcn_s_barrier()
; #define PG8_SCHED __builtin_amdgcn_sched_barrier(0)
;     ...
;                 if (w0) { PG8_LDB(B0, 1, 0); PG8_LDB(B1, 1, 1); PG8_SCHED; PG8_LDA(At, 1, 0); }
;                 PG8_WAIT_L(0); PG8_BAR; if (w0) { PG8_MMA(0, 0, At, B0); PG8_MMA(0, 1, At, B1); } PG8_BAR; PG8_SCHED;
;                 PG8_STAGEX(rsB, PG8_SB(1, 0), b3, voffB); PG8_STAGEX(rsB, PG8_SB(1, 1), b3 + hstepB, voffB); PG8_STAGEX(rsA, PG8_SA(1, 0), a3, voffA);
;                 PG8_WAIT_V(6); PG8_BAR; PG8_BAR; PG8_SCHED;
;             }
;         }
;         if (wr == 0) PG8_BAR;
	v_add_u32_e32 v86, 0x18000, v72
	v_add_u32_e32 v102, 0x1c000, v72
	ds_read_b128 v[74:77], v86
	ds_read_b128 v[78:81], v86 offset:1024
	ds_read_b128 v[82:85], v86 offset:2048
	ds_read_b128 v[86:89], v86 offset:3072
	ds_read_b128 v[90:93], v102
	ds_read_b128 v[94:97], v102 offset:1024
	ds_read_b128 v[98:101], v102 offset:2048
	ds_read_b128 v[102:105], v102 offset:3072
	ds_read_b128 v[106:109], v73 offset:32768
	ds_read_b128 v[110:113], v73 offset:33792
	ds_read_b128 v[114:117], v73 offset:34816
	ds_read_b128 v[118:121], v73 offset:35840
	ds_read_b128 v[122:125], v73 offset:36864
	ds_read_b128 v[126:129], v73 offset:37888
	ds_read_b128 v[130:133], v73 offset:38912
	ds_read_b128 v[134:137], v73 offset:39936
	s_waitcnt lgkmcnt(0)
	s_setprio 1
	s_barrier
	v_mfma_f32_16x16x32_bf16 v[62:65], v[74:77], v[106:109], v[62:65]
	v_mfma_f32_16x16x32_bf16 v[58:61], v[82:85], v[106:109], v[58:61]
	v_mfma_f32_16x16x32_bf16 v[54:57], v[74:77], v[114:117], v[54:57]
	v_mfma_f32_16x16x32_bf16 v[50:53], v[82:85], v[114:117], v[50:53]
	v_mfma_f32_16x16x32_bf16 v[46:49], v[74:77], v[122:125], v[46:49]
	v_mfma_f32_16x16x32_bf16 v[42:45], v[82:85], v[122:125], v[42:45]
	v_mfma_f32_16x16x32_bf16 v[38:41], v[74:77], v[130:133], v[38:41]
	v_mfma_f32_16x16x32_bf16 v[34:37], v[82:85], v[130:133], v[34:37]
	v_mfma_f32_16x16x32_bf16 v[62:65], v[78:81], v[110:113], v[62:65]
	v_mfma_f32_16x16x32_bf16 v[58:61], v[86:89], v[110:113], v[58:61]
	v_mfma_f32_16x16x32_bf16 v[54:57], v[78:81], v[118:121], v[54:57]
	v_mfma_f32_16x16x32_bf16 v[50:53], v[86:89], v[118:121], v[50:53]
	v_mfma_f32_16x16x32_bf16 v[46:49], v[78:81], v[126:129], v[46:49]
	v_mfma_f32_16x16x32_bf16 v[42:45], v[86:89], v[126:129], v[42:45]
	v_mfma_f32_16x16x32_bf16 v[38:41], v[78:81], v[134:137], v[38:41]
	v_mfma_f32_16x16x32_bf16 v[34:37], v[86:89], v[134:137], v[34:37]
	v_mfma_f32_16x16x32_bf16 v[30:33], v[90:93], v[106:109], v[30:33]
	s_or_b32 s31, s30, 0x80
	v_mfma_f32_16x16x32_bf16 v[26:29], v[98:101], v[106:109], v[26:29]
	v_mfma_f32_16x16x32_bf16 v[22:25], v[90:93], v[114:117], v[22:25]
	v_mfma_f32_16x16x32_bf16 v[18:21], v[98:101], v[114:117], v[18:21]
	v_mfma_f32_16x16x32_bf16 v[14:17], v[90:93], v[122:125], v[14:17]
	v_mfma_f32_16x16x32_bf16 v[10:13], v[98:101], v[122:125], v[10:13]
	v_mfma_f32_16x16x32_bf16 v[6:9], v[90:93], v[130:133], v[6:9]
	v_mfma_f32_16x16x32_bf16 v[2:5], v[98:101], v[130:133], v[2:5]
	v_mfma_f32_16x16x32_bf16 v[30:33], v[94:97], v[110:113], v[30:33]
	v_mfma_f32_16x16x32_bf16 v[26:29], v[102:105], v[110:113], v[26:29]
	v_mfma_f32_16x16x32_bf16 v[22:25], v[94:97], v[118:121], v[22:25]
	v_mfma_f32_16x16x32_bf16 v[18:21], v[102:105], v[118:121], v[18:21]
	v_mfma_f32_16x16x32_bf16 v[14:17], v[94:97], v[126:129], v[14:17]
	v_mfma_f32_16x16x32_bf16 v[10:13], v[102:105], v[126:129], v[10:13]
	v_mfma_f32_16x16x32_bf16 v[6:9], v[94:97], v[134:137], v[6:9]
	v_mfma_f32_16x16x32_bf16 v[2:5], v[102:105], v[134:137], v[2:5]
	s_barrier
	s_setprio 0
	s_mov_b32 m0, s22
	s_add_i32 s30, s30, 0x80080
	buffer_load_dwordx4 v67, s[40:43], s31 offen lds
	s_mov_b32 m0, s23
	s_nop 0
	buffer_load_dwordx4 v69, s[40:43], s31 offen lds
	s_mov_b32 m0, s26
	s_nop 0
	buffer_load_dwordx4 v67, s[40:43], s30 offen lds
	s_mov_b32 m0, s27
	s_nop 0
	buffer_load_dwordx4 v69, s[40:43], s30 offen lds
	s_mov_b32 m0, s24
	s_nop 0
	buffer_load_dwordx4 v66, s[76:79], s35 offen lds
	s_mov_b32 m0, s25
	s_nop 0
	buffer_load_dwordx4 v68, s[76:79], s35 offen lds
	s_waitcnt vmcnt(6)
	s_barrier
	s_barrier
	s_addk_i32 s28, 0x100
	s_add_i32 s29, s29, 2
	s_cmp_gt_u32 s29, 29
	s_cbranch_scc0 .LBB0_1287
	s_cmpk_lt_u32 s12, 0x100
	s_cbranch_scc0 .LBB0_1290
	s_barrier

; #define PG8_STAGEX(rs, bufoff, soff, voff) do { _Pragma("unroll") for (int _i = 0; _i < 2; ++_i) \
;         __builtin_amdgcn_raw_ptr_buffer_load_lds(rs, (LAS unsigned*)(lds + (bufoff) + ldsw + _i * 8192), 16, (voff)[_i], (soff), 0, 0); } while (0)
; #define PG8_LDA(dst, b, h) do { _Pragma("unroll") for (int m = 0; m < 4; ++m) _Pragma("unroll") for (int k = 0; k < 2; ++k) dst[m][k] = *(const LAS bf16x8*)(lds + PG8_SA(b, h) + aoff + m * 2048 + k * 1024); } while (0)
; #define PG8_LDB(dst, b, h) do { _Pragma("unroll") for (int n = 0; n < 2; ++n) _Pragma("unroll") for (int k = 0; k < 2; ++k) dst[n][k] = *(const LAS bf16x8*)(lds + PG8_SB(b, h) + boff + n * 2048 + k * 1024); } while (0)
; #define PG8_WAIT_V(n) asm volatile("s_waitcnt vmcnt(" #n ")" ::: "memory")
; #define PG8_WAIT_L(n) asm volatile("s_waitcnt lgkmcnt(" #n ")" ::: "memory")
; #define PG8_BAR __builtin_amdgcn_s_barrier()
; #define PG8_SCHED __builtin_amdgcn_sched_barrier(0)
;     ...
;         for (int t = 0; t < nt; t += 2) {
;             const bool last = (t == nt - 2);
;             const unsigned a1 = cA + (unsigned)(t + 1) * kstep;
;             const unsigned a2 = last ? nA : cA + (unsigned)(t + 2) * kstep, b2 = last ? nB : cB + (unsigned)(t + 2) * kstep;
;             const unsigned a3 = a2 + kstep, b3 = b2 + kstep;
;             PG8_LDB(B0, 0, 0); PG8_LDB(B1, 0, 1); PG8_SCHED; PG8_LDA(At, 0, 0); PG8_STAGEX(rsA, PG8_SA(1, 1), a1 + hstepA, voffA);
;             PG8_WAIT_V(8); PG8_WAIT_L(0); PG8_BAR; PG8_MMA(0, 0, At, B0); PG8_MMA(0, 1, At, B1); PG8_BAR; PG8_SCHED;
;             PG8_LDA(At, 0, 1); PG8_STAGEX(rsB, PG8_SB(0, 0), b2, voffB); PG8_STAGEX(rsB, PG8_SB(0, 1), b2 + hstepB, voffB); PG8_STAGEX(rsA, PG8_SA(0, 0), a2, voffA);
;             PG8_WAIT_V(8); PG8_WAIT_L(0); PG8_BAR; PG8_MMA(1, 0, At, B0); PG8_MMA(1, 1, At, B1); PG8_BAR; PG8_SCHED;
.LBB0_1377:
	v_add_u32_e32 v142, 0x10000, v185
	v_add_u32_e32 v158, 0x14000, v185
	ds_read_b128 v[130:133], v142
	ds_read_b128 v[134:137], v142 offset:1024
	ds_read_b128 v[138:141], v142 offset:2048
	ds_read_b128 v[142:145], v142 offset:3072
	ds_read_b128 v[146:149], v158
	ds_read_b128 v[150:153], v158 offset:1024
	ds_read_b128 v[154:157], v158 offset:2048
	ds_read_b128 v[158:161], v158 offset:3072
	s_add_i32 s50, s43, 0xfff40080
	s_cmp_eq_u32 s60, 12
	s_cselect_b32 s63, s30, s50
	s_cselect_b32 s62, s31, s59
	s_add_i32 s61, s63, 0x80
	s_mov_b32 m0, s23
	ds_read_b128 v[162:165], v186
	ds_read_b128 v[166:169], v186 offset:1024
	ds_read_b128 v[190:193], v186 offset:2048
	ds_read_b128 v[194:197], v186 offset:3072
	ds_read_b128 v[198:201], v186 offset:4096
	ds_read_b128 v[202:205], v186 offset:5120
	ds_read_b128 v[206:209], v186 offset:6144
	ds_read_b128 v[210:213], v186 offset:7168
	buffer_load_dwordx4 v173, s[76:79], s43 offen lds
	s_mov_b32 m0, s24
	s_nop 0
	buffer_load_dwordx4 v178, s[76:79], s43 offen lds
	s_waitcnt vmcnt(8)
	s_waitcnt lgkmcnt(0)
	s_setprio 1
	s_barrier
	v_mfma_f32_16x16x32_bf16 v[126:129], v[130:133], v[162:165], v[126:129]
	v_mfma_f32_16x16x32_bf16 v[126:129], v[134:137], v[166:169], v[126:129]
	v_mfma_f32_16x16x32_bf16 v[122:125], v[138:141], v[162:165], v[122:125]
	v_mfma_f32_16x16x32_bf16 v[122:125], v[142:145], v[166:169], v[122:125]
	v_mfma_f32_16x16x32_bf16 v[114:117], v[138:141], v[190:193], v[114:117]
	v_mfma_f32_16x16x32_bf16 v[114:117], v[142:145], v[194:197], v[114:117]
	v_mfma_f32_16x16x32_bf16 v[118:121], v[130:133], v[190:193], v[118:121]
	v_mfma_f32_16x16x32_bf16 v[118:121], v[134:137], v[194:197], v[118:121]
	v_mfma_f32_16x16x32_bf16 v[110:113], v[130:133], v[198:201], v[110:113]
	v_mfma_f32_16x16x32_bf16 v[110:113], v[134:137], v[202:205], v[110:113]
	v_mfma_f32_16x16x32_bf16 v[106:109], v[138:141], v[198:201], v[106:109]
	v_mfma_f32_16x16x32_bf16 v[106:109], v[142:145], v[202:205], v[106:109]
	v_mfma_f32_16x16x32_bf16 v[98:101], v[138:141], v[206:209], v[98:101]
	v_mfma_f32_16x16x32_bf16 v[98:101], v[142:145], v[210:213], v[98:101]
	v_mfma_f32_16x16x32_bf16 v[102:105], v[130:133], v[206:209], v[102:105]
	v_mfma_f32_16x16x32_bf16 v[102:105], v[134:137], v[210:213], v[102:105]
	v_mfma_f32_16x16x32_bf16 v[94:97], v[146:149], v[162:165], v[94:97]
	v_mfma_f32_16x16x32_bf16 v[94:97], v[150:153], v[166:169], v[94:97]
	v_mfma_f32_16x16x32_bf16 v[90:93], v[154:157], v[162:165], v[90:93]
	v_mfma_f32_16x16x32_bf16 v[90:93], v[158:161], v[166:169], v[90:93]
	v_mfma_f32_16x16x32_bf16 v[82:85], v[154:157], v[190:193], v[82:85]
	v_mfma_f32_16x16x32_bf16 v[82:85], v[158:161], v[194:197], v[82:85]
	v_mfma_f32_16x16x32_bf16 v[86:89], v[146:149], v[190:193], v[86:89]
	v_mfma_f32_16x16x32_bf16 v[86:89], v[150:153], v[194:197], v[86:89]
	v_mfma_f32_16x16x32_bf16 v[78:81], v[146:149], v[198:201], v[78:81]
	v_mfma_f32_16x16x32_bf16 v[78:81], v[150:153], v[202:205], v[78:81]
	v_mfma_f32_16x16x32_bf16 v[74:77], v[154:157], v[198:201], v[74:77]
	v_mfma_f32_16x16x32_bf16 v[74:77], v[158:161], v[202:205], v[74:77]
	v_mfma_f32_16x16x32_bf16 v[66:69], v[154:157], v[206:209], v[66:69]
	v_mfma_f32_16x16x32_bf16 v[66:69], v[158:161], v[210:213], v[66:69]
	v_mfma_f32_16x16x32_bf16 v[70:73], v[146:149], v[206:209], v[70:73]
	v_mfma_f32_16x16x32_bf16 v[70:73], v[150:153], v[210:213], v[70:73]
	s_barrier
	s_setprio 0
	s_mov_b32 m0, s7
	s_mov_b32 s50, s78
	s_mov_b32 s51, s79
	ds_read_b128 v[162:165], v186 offset:16384
	ds_read_b128 v[166:169], v186 offset:17408
	ds_read_b128 v[190:193], v186 offset:18432
	ds_read_b128 v[194:197], v186 offset:19456
	ds_read_b128 v[198:201], v186 offset:20480
	ds_read_b128 v[202:205], v186 offset:21504
	ds_read_b128 v[206:209], v186 offset:22528
	ds_read_b128 v[210:213], v186 offset:23552
	buffer_load_dwordx4 v177, s[48:51], s62 offen lds
	s_mov_b32 m0, s11
	s_add_i32 s64, s62, 0x40000
	buffer_load_dwordx4 v179, s[48:51], s62 offen lds
	s_mov_b32 m0, s12
	s_nop 0
	buffer_load_dwordx4 v177, s[48:51], s64 offen lds
	s_mov_b32 m0, s13
	s_nop 0
	buffer_load_dwordx4 v179, s[48:51], s64 offen lds
	s_mov_b32 m0, s5
	s_nop 0
	buffer_load_dwordx4 v173, s[76:79], s63 offen lds
	s_mov_b32 m0, s14
	s_nop 0
	buffer_load_dwordx4 v178, s[76:79], s63 offen lds
	s_waitcnt vmcnt(8)
	s_waitcnt lgkmcnt(0)
	s_setprio 1
	s_barrier
	v_mfma_f32_16x16x32_bf16 v[62:65], v[130:133], v[162:165], v[62:65]
	v_mfma_f32_16x16x32_bf16 v[62:65], v[134:137], v[166:169], v[62:65]
	v_mfma_f32_16x16x32_bf16 v[58:61], v[138:141], v[162:165], v[58:61]
	v_mfma_f32_16x16x32_bf16 v[58:61], v[142:145], v[166:169], v[58:61]
	v_mfma_f32_16x16x32_bf16 v[50:53], v[138:141], v[190:193], v[50:53]
	v_mfma_f32_16x16x32_bf16 v[50:53], v[142:145], v[194:197], v[50:53]
	v_mfma_f32_16x16x32_bf16 v[54:57], v[130:133], v[190:193], v[54:57]
	v_mfma_f32_16x16x32_bf16 v[54:57], v[134:137], v[194:197], v[54:57]
	v_mfma_f32_16x16x32_bf16 v[46:49], v[130:133], v[198:201], v[46:49]
	v_mfma_f32_16x16x32_bf16 v[46:49], v[134:137], v[202:205], v[46:49]
	v_mfma_f32_16x16x32_bf16 v[42:45], v[138:141], v[198:201], v[42:45]
	v_mfma_f32_16x16x32_bf16 v[42:45], v[142:145], v[202:205], v[42:45]
	v_mfma_f32_16x16x32_bf16 v[34:37], v[138:141], v[206:209], v[34:37]
	v_mfma_f32_16x16x32_bf16 v[34:37], v[142:145], v[210:213], v[34:37]
	v_mfma_f32_16x16x32_bf16 v[38:41], v[130:133], v[206:209], v[38:41]
	v_mfma_f32_16x16x32_bf16 v[38:41], v[134:137], v[210:213], v[38:41]
	v_mfma_f32_16x16x32_bf16 v[30:33], v[146:149], v[162:165], v[30:33]
	v_mfma_f32_16x16x32_bf16 v[30:33], v[150:153], v[166:169], v[30:33]
	v_mfma_f32_16x16x32_bf16 v[26:29], v[154:157], v[162:165], v[26:29]
	v_mfma_f32_16x16x32_bf16 v[26:29], v[158:161], v[166:169], v[26:29]
	v_mfma_f32_16x16x32_bf16 v[18:21], v[154:157], v[190:193], v[18:21]
	v_mfma_f32_16x16x32_bf16 v[18:21], v[158:161], v[194:197], v[18:21]
	v_mfma_f32_16x16x32_bf16 v[22:25], v[146:149], v[190:193], v[22:25]
	v_mfma_f32_16x16x32_bf16 v[22:25], v[150:153], v[194:197], v[22:25]
	v_mfma_f32_16x16x32_bf16 v[14:17], v[146:149], v[198:201], v[14:17]
	v_mfma_f32_16x16x32_bf16 v[14:17], v[150:153], v[202:205], v[14:17]
	v_mfma_f32_16x16x32_bf16 v[10:13], v[154:157], v[198:201], v[10:13]
	v_mfma_f32_16x16x32_bf16 v[10:13], v[158:161], v[202:205], v[10:13]
	v_mfma_f32_16x16x32_bf16 v[2:5], v[154:157], v[206:209], v[2:5]
	v_mfma_f32_16x16x32_bf16 v[2:5], v[158:161], v[210:213], v[2:5]
	v_mfma_f32_16x16x32_bf16 v[6:9], v[146:149], v[206:209], v[6:9]
	v_mfma_f32_16x16x32_bf16 v[6:9], v[150:153], v[210:213], v[6:9]
	s_barrier
; #define PG8_STAGEX(rs, bufoff, soff, voff) do { _Pragma("unroll") for (int _i = 0; _i < 2; ++_i) \
;         __builtin_amdgcn_raw_ptr_buffer_load_lds(rs, (LAS unsigned*)(lds + (bufoff) + ldsw + _i * 8192), 16, (voff)[_i], (soff), 0, 0); } while (0)
; #define PG8_LDA(dst, b, h) do { _Pragma("unroll") for (int m = 0; m < 4; ++m) _Pragma("unroll") for (int k = 0; k < 2; ++k) dst[m][k] = *(const LAS bf16x8*)(lds + PG8_SA(b, h) + aoff + m * 2048 + k * 1024); } while (0)
; #define PG8_LDB(dst, b, h) do { _Pragma("unroll") for (int n = 0; n < 2; ++n) _Pragma("unroll") for (int k = 0; k < 2; ++k) dst[n][k] = *(const LAS bf16x8*)(lds + PG8_SB(b, h) + boff + n * 2048 + k * 1024); } while (0)
; #define PG8_WAIT_V(n) asm volatile("s_waitcnt vmcnt(" #n ")" ::: "memory")
; #define PG8_WAIT_L(n) asm volatile("s_waitcnt lgkmcnt(" #n ")" ::: "memory")
; #define PG8_BAR __builtin_amdgcn_s_barrier()
; #define PG8_SCHED __builtin_amdgcn_sched_barrier(0)
;     ...
;             PG8_LDB(B0, 1, 0); PG8_LDB(B1, 1, 1); PG8_SCHED; PG8_LDA(At, 1, 0); PG8_STAGEX(rsA, PG8_SA(0, 1), a2 + hstepA, voffA);
;             PG8_WAIT_V(8); PG8_WAIT_L(0); PG8_BAR; PG8_MMA(0, 0, At, B0); PG8_MMA(0, 1, At, B1); PG8_BAR; PG8_SCHED;
;             PG8_LDA(At, 1, 1); PG8_STAGEX(rsB, PG8_SB(1, 0), b3, voffB); PG8_STAGEX(rsB, PG8_SB(1, 1), b3 + hstepB, voffB); PG8_STAGEX(rsA, PG8_SA(1, 0), a3, voffA);
;             PG8_WAIT_V(8); PG8_WAIT_L(0); PG8_BAR; PG8_MMA(1, 0, At, B0); PG8_MMA(1, 1, At, B1); PG8_BAR; PG8_SCHED;
;         }
	s_setprio 0
	v_add_u32_e32 v142, 0x18000, v185
	v_add_u32_e32 v158, 0x1c000, v185
	ds_read_b128 v[130:133], v142
	ds_read_b128 v[134:137], v142 offset:1024
	ds_read_b128 v[138:141], v142 offset:2048
	ds_read_b128 v[142:145], v142 offset:3072
	ds_read_b128 v[146:149], v158
	ds_read_b128 v[150:153], v158 offset:1024
	ds_read_b128 v[154:157], v158 offset:2048
	ds_read_b128 v[158:161], v158 offset:3072
	s_add_i32 s63, s63, 0xc0000
	s_mov_b32 m0, s15
	ds_read_b128 v[162:165], v186 offset:32768
	ds_read_b128 v[166:169], v186 offset:33792
	ds_read_b128 v[190:193], v186 offset:34816
	ds_read_b128 v[194:197], v186 offset:35840
	ds_read_b128 v[198:201], v186 offset:36864
	ds_read_b128 v[202:205], v186 offset:37888
	ds_read_b128 v[206:209], v186 offset:38912
	ds_read_b128 v[210:213], v186 offset:39936
	buffer_load_dwordx4 v173, s[76:79], s63 offen lds
	s_mov_b32 m0, s16
	s_nop 0
	buffer_load_dwordx4 v178, s[76:79], s63 offen lds
	s_waitcnt vmcnt(8)
	s_waitcnt lgkmcnt(0)
	s_setprio 1
	s_barrier
	v_mfma_f32_16x16x32_bf16 v[126:129], v[130:133], v[162:165], v[126:129]
	v_mfma_f32_16x16x32_bf16 v[126:129], v[134:137], v[166:169], v[126:129]
	v_mfma_f32_16x16x32_bf16 v[122:125], v[138:141], v[162:165], v[122:125]
	v_mfma_f32_16x16x32_bf16 v[122:125], v[142:145], v[166:169], v[122:125]
	v_mfma_f32_16x16x32_bf16 v[114:117], v[138:141], v[190:193], v[114:117]
	v_mfma_f32_16x16x32_bf16 v[114:117], v[142:145], v[194:197], v[114:117]
	v_mfma_f32_16x16x32_bf16 v[118:121], v[130:133], v[190:193], v[118:121]
	v_mfma_f32_16x16x32_bf16 v[118:121], v[134:137], v[194:197], v[118:121]
	v_mfma_f32_16x16x32_bf16 v[110:113], v[130:133], v[198:201], v[110:113]
	v_mfma_f32_16x16x32_bf16 v[110:113], v[134:137], v[202:205], v[110:113]
	v_mfma_f32_16x16x32_bf16 v[106:109], v[138:141], v[198:201], v[106:109]
	v_mfma_f32_16x16x32_bf16 v[106:109], v[142:145], v[202:205], v[106:109]
	v_mfma_f32_16x16x32_bf16 v[98:101], v[138:141], v[206:209], v[98:101]
	v_mfma_f32_16x16x32_bf16 v[98:101], v[142:145], v[210:213], v[98:101]
	v_mfma_f32_16x16x32_bf16 v[102:105], v[130:133], v[206:209], v[102:105]
	v_mfma_f32_16x16x32_bf16 v[102:105], v[134:137], v[210:213], v[102:105]
	v_mfma_f32_16x16x32_bf16 v[94:97], v[146:149], v[162:165], v[94:97]
	v_mfma_f32_16x16x32_bf16 v[94:97], v[150:153], v[166:169], v[94:97]
	v_mfma_f32_16x16x32_bf16 v[90:93], v[154:157], v[162:165], v[90:93]
	v_mfma_f32_16x16x32_bf16 v[90:93], v[158:161], v[166:169], v[90:93]
	v_mfma_f32_16x16x32_bf16 v[82:85], v[154:157], v[190:193], v[82:85]
	v_mfma_f32_16x16x32_bf16 v[82:85], v[158:161], v[194:197], v[82:85]
	v_mfma_f32_16x16x32_bf16 v[86:89], v[146:149], v[190:193], v[86:89]
	v_mfma_f32_16x16x32_bf16 v[86:89], v[150:153], v[194:197], v[86:89]
	v_mfma_f32_16x16x32_bf16 v[78:81], v[146:149], v[198:201], v[78:81]
	v_mfma_f32_16x16x32_bf16 v[78:81], v[150:153], v[202:205], v[78:81]
	v_mfma_f32_16x16x32_bf16 v[74:77], v[154:157], v[198:201], v[74:77]
	v_mfma_f32_16x16x32_bf16 v[74:77], v[158:161], v[202:205], v[74:77]
	v_mfma_f32_16x16x32_bf16 v[66:69], v[154:157], v[206:209], v[66:69]
	v_mfma_f32_16x16x32_bf16 v[66:69], v[158:161], v[210:213], v[66:69]
	v_mfma_f32_16x16x32_bf16 v[70:73], v[146:149], v[206:209], v[70:73]
	v_mfma_f32_16x16x32_bf16 v[70:73], v[150:153], v[210:213], v[70:73]
	s_barrier
	s_setprio 0
	s_mov_b32 m0, s17
	s_add_i32 s63, s62, 0x80
	ds_read_b128 v[162:165], v186 offset:49152
	ds_read_b128 v[166:169], v186 offset:50176
	ds_read_b128 v[190:193], v186 offset:51200
	ds_read_b128 v[194:197], v186 offset:52224
	ds_read_b128 v[198:201], v186 offset:53248
	ds_read_b128 v[202:205], v186 offset:54272
	ds_read_b128 v[206:209], v186 offset:55296
	ds_read_b128 v[210:213], v186 offset:56320
	buffer_load_dwordx4 v177, s[48:51], s63 offen lds
	s_mov_b32 m0, s18
	s_add_i32 s62, s62, 0x40080
	buffer_load_dwordx4 v179, s[48:51], s63 offen lds
	s_mov_b32 m0, s21
	s_nop 0
	buffer_load_dwordx4 v177, s[48:51], s62 offen lds
	s_mov_b32 m0, s22
	s_nop 0
	buffer_load_dwordx4 v179, s[48:51], s62 offen lds
	s_mov_b32 m0, s19
	s_nop 0
	buffer_load_dwordx4 v173, s[76:79], s61 offen lds
	s_mov_b32 m0, s20
	s_nop 0
	buffer_load_dwordx4 v178, s[76:79], s61 offen lds
	s_waitcnt vmcnt(8)
	s_waitcnt lgkmcnt(0)
	s_setprio 1
	s_barrier
	v_mfma_f32_16x16x32_bf16 v[62:65], v[130:133], v[162:165], v[62:65]
	v_mfma_f32_16x16x32_bf16 v[62:65], v[134:137], v[166:169], v[62:65]
	v_mfma_f32_16x16x32_bf16 v[58:61], v[138:141], v[162:165], v[58:61]
	v_mfma_f32_16x16x32_bf16 v[58:61], v[142:145], v[166:169], v[58:61]
	v_mfma_f32_16x16x32_bf16 v[50:53], v[138:141], v[190:193], v[50:53]
	v_mfma_f32_16x16x32_bf16 v[50:53], v[142:145], v[194:197], v[50:53]
	v_mfma_f32_16x16x32_bf16 v[54:57], v[130:133], v[190:193], v[54:57]
	v_mfma_f32_16x16x32_bf16 v[54:57], v[134:137], v[194:197], v[54:57]
	v_mfma_f32_16x16x32_bf16 v[46:49], v[130:133], v[198:201], v[46:49]
	v_mfma_f32_16x16x32_bf16 v[46:49], v[134:137], v[202:205], v[46:49]
	v_mfma_f32_16x16x32_bf16 v[42:45], v[138:141], v[198:201], v[42:45]
	v_mfma_f32_16x16x32_bf16 v[42:45], v[142:145], v[202:205], v[42:45]
	v_mfma_f32_16x16x32_bf16 v[34:37], v[138:141], v[206:209], v[34:37]
	v_mfma_f32_16x16x32_bf16 v[34:37], v[142:145], v[210:213], v[34:37]
	v_mfma_f32_16x16x32_bf16 v[38:41], v[130:133], v[206:209], v[38:41]
	v_mfma_f32_16x16x32_bf16 v[38:41], v[134:137], v[210:213], v[38:41]
	v_mfma_f32_16x16x32_bf16 v[30:33], v[146:149], v[162:165], v[30:33]
	v_mfma_f32_16x16x32_bf16 v[30:33], v[150:153], v[166:169], v[30:33]
	v_mfma_f32_16x16x32_bf16 v[26:29], v[154:157], v[162:165], v[26:29]
	v_mfma_f32_16x16x32_bf16 v[26:29], v[158:161], v[166:169], v[26:29]
	v_mfma_f32_16x16x32_bf16 v[18:21], v[154:157], v[190:193], v[18:21]
	v_mfma_f32_16x16x32_bf16 v[18:21], v[158:161], v[194:197], v[18:21]
	v_mfma_f32_16x16x32_bf16 v[22:25], v[146:149], v[190:193], v[22:25]
	v_mfma_f32_16x16x32_bf16 v[22:25], v[150:153], v[194:197], v[22:25]
	v_mfma_f32_16x16x32_bf16 v[14:17], v[146:149], v[198:201], v[14:17]
	v_mfma_f32_16x16x32_bf16 v[14:17], v[150:153], v[202:205], v[14:17]
	v_mfma_f32_16x16x32_bf16 v[10:13], v[154:157], v[198:201], v[10:13]
	v_mfma_f32_16x16x32_bf16 v[10:13], v[158:161], v[202:205], v[10:13]
	v_mfma_f32_16x16x32_bf16 v[2:5], v[154:157], v[206:209], v[2:5]
	v_mfma_f32_16x16x32_bf16 v[2:5], v[158:161], v[210:213], v[2:5]
	v_mfma_f32_16x16x32_bf16 v[6:9], v[146:149], v[206:209], v[6:9]
	v_mfma_f32_16x16x32_bf16 v[6:9], v[150:153], v[210:213], v[6:9]
	s_barrier
	s_setprio 0
	s_add_i32 s60, s60, 2
	s_addk_i32 s43, 0x100
	s_addk_i32 s59, 0x100
	s_cmp_gt_u32 s60, 13
	s_cbranch_scc0 .LBB0_1377
	s_and_b64 vcc, exec, s[52:53]
	s_cbranch_vccz .LBB0_1380
	s_barrier

; #define PG8_STAGEX(rs, bufoff, soff, voff) do { _Pragma("unroll") for (int _i = 0; _i < 2; ++_i) \
;         __builtin_amdgcn_raw_ptr_buffer_load_lds(rs, (LAS unsigned*)(lds + (bufoff) + ldsw + _i * 8192), 16, (voff)[_i], (soff), 0, 0); } while (0)
; #define PG8_LDA(dst, b, h) do { _Pragma("unroll") for (int m = 0; m < 4; ++m) _Pragma("unroll") for (int k = 0; k < 2; ++k) dst[m][k] = *(const LAS bf16x8*)(lds + PG8_SA(b, h) + aoff + m * 2048 + k * 1024); } while (0)
; #define PG8_LDB(dst, b, h) do { _Pragma("unroll") for (int n = 0; n < 2; ++n) _Pragma("unroll") for (int k = 0; k < 2; ++k) dst[n][k] = *(const LAS bf16x8*)(lds + PG8_SB(b, h) + boff + n * 2048 + k * 1024); } while (0)
; #define PG8_WAIT_V(n) asm volatile("s_waitcnt vmcnt(" #n ")" ::: "memory")
; #define PG8_WAIT_L(n) asm volatile("s_waitcnt lgkmcnt(" #n ")" ::: "memory")
; #define PG8_BAR __builtin_amdgcn_s_barrier()
; #define PG8_SCHED __builtin_amdgcn_sched_barrier(0)
;     ...
;             for (int t = 0; t < nt; t += 2) {
;                 const bool last = (t == nt - 2);
;                 const unsigned a1 = cA + (unsigned)(t + 1) * kstep;
;                 const unsigned a2 = last ? nA : cA + (unsigned)(t + 2) * kstep, b2 = last ? nB : cB + (unsigned)(t + 2) * kstep;
;                 const unsigned a3 = a2 + kstep, b3 = b2 + kstep;
;                 if (w0) { PG8_LDB(B0, 0, 0); PG8_LDB(B1, 0, 1); PG8_SCHED; PG8_LDA(At, 0, 0); }
;                 PG8_WAIT_L(0); PG8_BAR; if (w0) { PG8_MMA(0, 0, At, B0); PG8_MMA(0, 1, At, B1); } PG8_BAR; PG8_SCHED;
;                 PG8_STAGEX(rsB, PG8_SB(0, 0), b2, voffB); PG8_STAGEX(rsB, PG8_SB(0, 1), b2 + hstepB, voffB); PG8_STAGEX(rsA, PG8_SA(0, 0), a2, voffA);
;                 PG8_WAIT_V(6); PG8_BAR; PG8_BAR; PG8_SCHED;
.LBB0_1429:
	v_add_u32_e32 v78, 0x10000, v95
	v_add_u32_e32 v86, 0x14000, v95
	ds_read_b128 v[66:69], v78
	ds_read_b128 v[70:73], v78 offset:1024
	ds_read_b128 v[74:77], v78 offset:2048
	ds_read_b128 v[78:81], v78 offset:3072
	ds_read_b128 v[82:85], v86
	ds_read_b128 v[100:103], v86 offset:1024
	ds_read_b128 v[104:107], v86 offset:2048
	ds_read_b128 v[108:111], v86 offset:3072
	s_cmp_eq_u32 s40, 12
	s_cselect_b32 s41, s38, s39
	s_cselect_b32 s46, s30, s31
	s_add_i32 s47, s41, 0x80
	ds_read_b128 v[112:115], v96
	ds_read_b128 v[116:119], v96 offset:1024
	ds_read_b128 v[120:123], v96 offset:2048
	ds_read_b128 v[124:127], v96 offset:3072
	ds_read_b128 v[128:131], v96 offset:4096
	ds_read_b128 v[132:135], v96 offset:5120
	ds_read_b128 v[136:139], v96 offset:6144
	ds_read_b128 v[140:143], v96 offset:7168
	s_waitcnt lgkmcnt(0)
	s_setprio 1
	s_barrier
	v_mfma_f32_16x16x32_bf16 v[62:65], v[66:69], v[112:115], v[62:65]
	v_mfma_f32_16x16x32_bf16 v[62:65], v[70:73], v[116:119], v[62:65]
	v_mfma_f32_16x16x32_bf16 v[58:61], v[74:77], v[112:115], v[58:61]
	v_mfma_f32_16x16x32_bf16 v[58:61], v[78:81], v[116:119], v[58:61]
	v_mfma_f32_16x16x32_bf16 v[50:53], v[74:77], v[120:123], v[50:53]
	v_mfma_f32_16x16x32_bf16 v[50:53], v[78:81], v[124:127], v[50:53]
	v_mfma_f32_16x16x32_bf16 v[54:57], v[66:69], v[120:123], v[54:57]
	v_mfma_f32_16x16x32_bf16 v[54:57], v[70:73], v[124:127], v[54:57]
	v_mfma_f32_16x16x32_bf16 v[46:49], v[66:69], v[128:131], v[46:49]
	v_mfma_f32_16x16x32_bf16 v[46:49], v[70:73], v[132:135], v[46:49]
	v_mfma_f32_16x16x32_bf16 v[42:45], v[74:77], v[128:131], v[42:45]
	v_mfma_f32_16x16x32_bf16 v[42:45], v[78:81], v[132:135], v[42:45]
	v_mfma_f32_16x16x32_bf16 v[34:37], v[74:77], v[136:139], v[34:37]
	v_mfma_f32_16x16x32_bf16 v[34:37], v[78:81], v[140:143], v[34:37]
	v_mfma_f32_16x16x32_bf16 v[38:41], v[66:69], v[136:139], v[38:41]
	v_mfma_f32_16x16x32_bf16 v[38:41], v[70:73], v[140:143], v[38:41]
	v_mfma_f32_16x16x32_bf16 v[30:33], v[82:85], v[112:115], v[30:33]
	v_mfma_f32_16x16x32_bf16 v[30:33], v[100:103], v[116:119], v[30:33]
	v_mfma_f32_16x16x32_bf16 v[26:29], v[104:107], v[112:115], v[26:29]
	v_mfma_f32_16x16x32_bf16 v[26:29], v[108:111], v[116:119], v[26:29]
	v_mfma_f32_16x16x32_bf16 v[18:21], v[104:107], v[120:123], v[18:21]
	v_mfma_f32_16x16x32_bf16 v[18:21], v[108:111], v[124:127], v[18:21]
	v_mfma_f32_16x16x32_bf16 v[22:25], v[82:85], v[120:123], v[22:25]
	v_mfma_f32_16x16x32_bf16 v[22:25], v[100:103], v[124:127], v[22:25]
	v_mfma_f32_16x16x32_bf16 v[14:17], v[82:85], v[128:131], v[14:17]
	v_mfma_f32_16x16x32_bf16 v[14:17], v[100:103], v[132:135], v[14:17]
	v_mfma_f32_16x16x32_bf16 v[10:13], v[104:107], v[128:131], v[10:13]
	v_mfma_f32_16x16x32_bf16 v[10:13], v[108:111], v[132:135], v[10:13]
	v_mfma_f32_16x16x32_bf16 v[2:5], v[104:107], v[136:139], v[2:5]
	v_mfma_f32_16x16x32_bf16 v[2:5], v[108:111], v[140:143], v[2:5]
	v_mfma_f32_16x16x32_bf16 v[6:9], v[82:85], v[136:139], v[6:9]
	v_mfma_f32_16x16x32_bf16 v[6:9], v[100:103], v[140:143], v[6:9]
	s_barrier
	s_setprio 0
	s_mov_b32 m0, s5
	s_mov_b32 s50, s78
	s_mov_b32 s51, s79
	buffer_load_dwordx4 v89, s[48:51], s46 offen lds
	s_mov_b32 m0, s7
	s_add_i32 s52, s46, 0x40000
	buffer_load_dwordx4 v91, s[48:51], s46 offen lds
	s_mov_b32 m0, s11
	s_nop 0
	buffer_load_dwordx4 v89, s[48:51], s52 offen lds
	s_mov_b32 m0, s12
	s_nop 0
	buffer_load_dwordx4 v91, s[48:51], s52 offen lds
	s_mov_b32 m0, s3
	s_nop 0
	buffer_load_dwordx4 v88, s[76:79], s41 offen lds
	s_mov_b32 m0, s13
	s_nop 0
	buffer_load_dwordx4 v90, s[76:79], s41 offen lds
	s_waitcnt vmcnt(6)
	s_barrier
	s_barrier
; #define PG8_STAGEX(rs, bufoff, soff, voff) do { _Pragma("unroll") for (int _i = 0; _i < 2; ++_i) \
;         __builtin_amdgcn_raw_ptr_buffer_load_lds(rs, (LAS unsigned*)(lds + (bufoff) + ldsw + _i * 8192), 16, (voff)[_i], (soff), 0, 0); } while (0)
; #define PG8_LDA(dst, b, h) do { _Pragma("unroll") for (int m = 0; m < 4; ++m) _Pragma("unroll") for (int k = 0; k < 2; ++k) dst[m][k] = *(const LAS bf16x8*)(lds + PG8_SA(b, h) + aoff + m * 2048 + k * 1024); } while (0)
; #define PG8_LDB(dst, b, h) do { _Pragma("unroll") for (int n = 0; n < 2; ++n) _Pragma("unroll") for (int k = 0; k < 2; ++k) dst[n][k] = *(const LAS bf16x8*)(lds + PG8_SB(b, h) + boff + n * 2048 + k * 1024); } while (0)
; #define PG8_WAIT_V(n) asm volatile("s_waitcnt vmcnt(" #n ")" ::: "memory")
; #define PG8_WAIT_L(n) asm volatile("s_waitcnt lgkmcnt(" #n ")" ::: "memory")
; #define PG8_BAR __builtin_amdgcn_s_barrier()
; #define PG8_SCHED __builtin_amdgcn_sched_barrier(0)
;     ...
;                 if (w0) { PG8_LDB(B0, 1, 0); PG8_LDB(B1, 1, 1); PG8_SCHED; PG8_LDA(At, 1, 0); }
;                 PG8_WAIT_L(0); PG8_BAR; if (w0) { PG8_MMA(0, 0, At, B0); PG8_MMA(0, 1, At, B1); } PG8_BAR; PG8_SCHED;
;                 PG8_STAGEX(rsB, PG8_SB(1, 0), b3, voffB); PG8_STAGEX(rsB, PG8_SB(1, 1), b3 + hstepB, voffB); PG8_STAGEX(rsA, PG8_SA(1, 0), a3, voffA);
;                 PG8_WAIT_V(6); PG8_BAR; PG8_BAR; PG8_SCHED;
;             }
;         }
;         if (wr == 0) PG8_BAR;
	v_add_u32_e32 v78, 0x18000, v95
	v_add_u32_e32 v86, 0x1c000, v95
	ds_read_b128 v[66:69], v78
	ds_read_b128 v[70:73], v78 offset:1024
	ds_read_b128 v[74:77], v78 offset:2048
	ds_read_b128 v[78:81], v78 offset:3072
	ds_read_b128 v[82:85], v86
	ds_read_b128 v[100:103], v86 offset:1024
	ds_read_b128 v[104:107], v86 offset:2048
	ds_read_b128 v[108:111], v86 offset:3072
	ds_read_b128 v[112:115], v96 offset:32768
	ds_read_b128 v[116:119], v96 offset:33792
	ds_read_b128 v[120:123], v96 offset:34816
	ds_read_b128 v[124:127], v96 offset:35840
	ds_read_b128 v[128:131], v96 offset:36864
	ds_read_b128 v[132:135], v96 offset:37888
	ds_read_b128 v[136:139], v96 offset:38912
	ds_read_b128 v[140:143], v96 offset:39936
	s_waitcnt lgkmcnt(0)
	s_setprio 1
	s_barrier
	v_mfma_f32_16x16x32_bf16 v[62:65], v[66:69], v[112:115], v[62:65]
	v_mfma_f32_16x16x32_bf16 v[58:61], v[74:77], v[112:115], v[58:61]
	v_mfma_f32_16x16x32_bf16 v[54:57], v[66:69], v[120:123], v[54:57]
	v_mfma_f32_16x16x32_bf16 v[50:53], v[74:77], v[120:123], v[50:53]
	v_mfma_f32_16x16x32_bf16 v[46:49], v[66:69], v[128:131], v[46:49]
	v_mfma_f32_16x16x32_bf16 v[42:45], v[74:77], v[128:131], v[42:45]
	v_mfma_f32_16x16x32_bf16 v[38:41], v[66:69], v[136:139], v[38:41]
	v_mfma_f32_16x16x32_bf16 v[34:37], v[74:77], v[136:139], v[34:37]
	v_mfma_f32_16x16x32_bf16 v[62:65], v[70:73], v[116:119], v[62:65]
	v_mfma_f32_16x16x32_bf16 v[58:61], v[78:81], v[116:119], v[58:61]
	v_mfma_f32_16x16x32_bf16 v[54:57], v[70:73], v[124:127], v[54:57]
	v_mfma_f32_16x16x32_bf16 v[50:53], v[78:81], v[124:127], v[50:53]
	v_mfma_f32_16x16x32_bf16 v[46:49], v[70:73], v[132:135], v[46:49]
	v_mfma_f32_16x16x32_bf16 v[42:45], v[78:81], v[132:135], v[42:45]
	v_mfma_f32_16x16x32_bf16 v[38:41], v[70:73], v[140:143], v[38:41]
	v_mfma_f32_16x16x32_bf16 v[34:37], v[78:81], v[140:143], v[34:37]
	v_mfma_f32_16x16x32_bf16 v[30:33], v[82:85], v[112:115], v[30:33]
	s_add_i32 s41, s46, 0x80
	v_mfma_f32_16x16x32_bf16 v[26:29], v[104:107], v[112:115], v[26:29]
	v_mfma_f32_16x16x32_bf16 v[22:25], v[82:85], v[120:123], v[22:25]
	v_mfma_f32_16x16x32_bf16 v[18:21], v[104:107], v[120:123], v[18:21]
	v_mfma_f32_16x16x32_bf16 v[14:17], v[82:85], v[128:131], v[14:17]
	v_mfma_f32_16x16x32_bf16 v[10:13], v[104:107], v[128:131], v[10:13]
	v_mfma_f32_16x16x32_bf16 v[6:9], v[82:85], v[136:139], v[6:9]
	v_mfma_f32_16x16x32_bf16 v[2:5], v[104:107], v[136:139], v[2:5]
	v_mfma_f32_16x16x32_bf16 v[30:33], v[100:103], v[116:119], v[30:33]
	v_mfma_f32_16x16x32_bf16 v[26:29], v[108:111], v[116:119], v[26:29]
	v_mfma_f32_16x16x32_bf16 v[22:25], v[100:103], v[124:127], v[22:25]
	v_mfma_f32_16x16x32_bf16 v[18:21], v[108:111], v[124:127], v[18:21]
	v_mfma_f32_16x16x32_bf16 v[14:17], v[100:103], v[132:135], v[14:17]
	v_mfma_f32_16x16x32_bf16 v[10:13], v[108:111], v[132:135], v[10:13]
	v_mfma_f32_16x16x32_bf16 v[6:9], v[100:103], v[140:143], v[6:9]
	v_mfma_f32_16x16x32_bf16 v[2:5], v[108:111], v[140:143], v[2:5]
	s_barrier
	s_setprio 0
	s_mov_b32 m0, s14
	s_add_i32 s46, s46, 0x40080
	buffer_load_dwordx4 v89, s[48:51], s41 offen lds
	s_mov_b32 m0, s15
	s_nop 0
	buffer_load_dwordx4 v91, s[48:51], s41 offen lds
	s_mov_b32 m0, s18
	s_nop 0
	buffer_load_dwordx4 v89, s[48:51], s46 offen lds
	s_mov_b32 m0, s19
	s_nop 0
	buffer_load_dwordx4 v91, s[48:51], s46 offen lds
	s_mov_b32 m0, s16
	s_nop 0
	buffer_load_dwordx4 v88, s[76:79], s47 offen lds
	s_mov_b32 m0, s17
	s_nop 0
	buffer_load_dwordx4 v90, s[76:79], s47 offen lds
	s_waitcnt vmcnt(6)
	s_barrier
	s_barrier
	s_add_i32 s40, s40, 2
	s_addk_i32 s31, 0x100
	s_addk_i32 s39, 0x100
	s_cmp_gt_u32 s40, 13
	s_cbranch_scc0 .LBB0_1429
	s_and_b64 vcc, exec, s[42:43]
	s_cbranch_vccz .LBB0_1432
	s_barrier

; #define PG8_STAGEX(rs, bufoff, soff, voff) do { _Pragma("unroll") for (int _i = 0; _i < 2; ++_i) \
;         __builtin_amdgcn_raw_ptr_buffer_load_lds(rs, (LAS unsigned*)(lds + (bufoff) + ldsw + _i * 8192), 16, (voff)[_i], (soff), 0, 0); } while (0)
; #define PG8_LDA(dst, b, h) do { _Pragma("unroll") for (int m = 0; m < 4; ++m) _Pragma("unroll") for (int k = 0; k < 2; ++k) dst[m][k] = *(const LAS bf16x8*)(lds + PG8_SA(b, h) + aoff + m * 2048 + k * 1024); } while (0)
; #define PG8_LDB(dst, b, h) do { _Pragma("unroll") for (int n = 0; n < 2; ++n) _Pragma("unroll") for (int k = 0; k < 2; ++k) dst[n][k] = *(const LAS bf16x8*)(lds + PG8_SB(b, h) + boff + n * 2048 + k * 1024); } while (0)
; #define PG8_WAIT_V(n) asm volatile("s_waitcnt vmcnt(" #n ")" ::: "memory")
; #define PG8_WAIT_L(n) asm volatile("s_waitcnt lgkmcnt(" #n ")" ::: "memory")
; #define PG8_BAR __builtin_amdgcn_s_barrier()
; #define PG8_SCHED __builtin_amdgcn_sched_barrier(0)
;     ...
;         for (int t = 0; t < nt; t += 2) {
;             const bool last = (t == nt - 2);
;             const unsigned a1 = cA + (unsigned)(t + 1) * kstep;
;             const unsigned a2 = last ? nA : cA + (unsigned)(t + 2) * kstep, b2 = last ? nB : cB + (unsigned)(t + 2) * kstep;
;             const unsigned a3 = a2 + kstep, b3 = b2 + kstep;
;             PG8_LDB(B0, 0, 0); PG8_LDB(B1, 0, 1); PG8_SCHED; PG8_LDA(At, 0, 0); PG8_STAGEX(rsA, PG8_SA(1, 1), a1 + hstepA, voffA);
;             PG8_WAIT_V(8); PG8_WAIT_L(0); PG8_BAR; PG8_MMA(0, 0, At, B0); PG8_MMA(0, 1, At, B1); PG8_BAR; PG8_SCHED;
;             PG8_LDA(At, 0, 1); PG8_STAGEX(rsB, PG8_SB(0, 0), b2, voffB); PG8_STAGEX(rsB, PG8_SB(0, 1), b2 + hstepB, voffB); PG8_STAGEX(rsA, PG8_SA(0, 0), a2, voffA);
;             PG8_WAIT_V(8); PG8_WAIT_L(0); PG8_BAR; PG8_MMA(1, 0, At, B0); PG8_MMA(1, 1, At, B1); PG8_BAR; PG8_SCHED;
.LBB0_1529:
	v_add_u32_e32 v118, 0x10000, v210
	v_add_u32_e32 v142, 0x14000, v210
	ds_read_b128 v[106:109], v118
	ds_read_b128 v[110:113], v118 offset:1024
	ds_read_b128 v[114:117], v118 offset:2048
	ds_read_b128 v[118:121], v118 offset:3072
	ds_read_b128 v[122:125], v142
	ds_read_b128 v[126:129], v142 offset:1024
	ds_read_b128 v[130:133], v142 offset:2048
	ds_read_b128 v[142:145], v142 offset:3072
	s_add_i32 s46, s59, 0xfff80080
	s_cmp_eq_u32 s64, 28
	s_cselect_b32 s67, s30, s46
	s_cselect_b32 s66, s31, s63
	s_or_b32 s65, s67, 0x80
	s_mov_b32 m0, s76
	ds_read_b128 v[164:167], v211
	ds_read_b128 v[168:171], v211 offset:1024
	ds_read_b128 v[182:185], v211 offset:2048
	ds_read_b128 v[186:189], v211 offset:3072
	ds_read_b128 v[190:193], v211 offset:4096
	ds_read_b128 v[194:197], v211 offset:5120
	ds_read_b128 v[198:201], v211 offset:6144
	ds_read_b128 v[202:205], v211 offset:7168
	buffer_load_dwordx4 v178, s[40:43], s59 offen lds
	s_mov_b32 m0, s77
	s_nop 0
	buffer_load_dwordx4 v206, s[40:43], s59 offen lds
	s_waitcnt vmcnt(8)
	s_waitcnt lgkmcnt(0)
	s_setprio 1
	s_barrier
	v_mfma_f32_16x16x32_bf16 v[158:161], v[106:109], v[164:167], v[158:161]
	v_mfma_f32_16x16x32_bf16 v[158:161], v[110:113], v[168:171], v[158:161]
	v_mfma_f32_16x16x32_bf16 v[154:157], v[114:117], v[164:167], v[154:157]
	v_mfma_f32_16x16x32_bf16 v[154:157], v[118:121], v[168:171], v[154:157]
	v_mfma_f32_16x16x32_bf16 v[146:149], v[114:117], v[182:185], v[146:149]
	v_mfma_f32_16x16x32_bf16 v[146:149], v[118:121], v[186:189], v[146:149]
	v_mfma_f32_16x16x32_bf16 v[150:153], v[106:109], v[182:185], v[150:153]
	v_mfma_f32_16x16x32_bf16 v[150:153], v[110:113], v[186:189], v[150:153]
	v_mfma_f32_16x16x32_bf16 v[138:141], v[106:109], v[190:193], v[138:141]
	v_mfma_f32_16x16x32_bf16 v[138:141], v[110:113], v[194:197], v[138:141]
	v_mfma_f32_16x16x32_bf16 v[134:137], v[114:117], v[190:193], v[134:137]
	v_mfma_f32_16x16x32_bf16 v[134:137], v[118:121], v[194:197], v[134:137]
	v_mfma_f32_16x16x32_bf16 v[98:101], v[114:117], v[198:201], v[98:101]
	v_mfma_f32_16x16x32_bf16 v[98:101], v[118:121], v[202:205], v[98:101]
	v_mfma_f32_16x16x32_bf16 v[102:105], v[106:109], v[198:201], v[102:105]
	v_mfma_f32_16x16x32_bf16 v[102:105], v[110:113], v[202:205], v[102:105]
	v_mfma_f32_16x16x32_bf16 v[62:65], v[122:125], v[164:167], v[62:65]
	v_mfma_f32_16x16x32_bf16 v[62:65], v[126:129], v[168:171], v[62:65]
	v_mfma_f32_16x16x32_bf16 v[58:61], v[130:133], v[164:167], v[58:61]
	v_mfma_f32_16x16x32_bf16 v[58:61], v[142:145], v[168:171], v[58:61]
	v_mfma_f32_16x16x32_bf16 v[50:53], v[130:133], v[182:185], v[50:53]
	v_mfma_f32_16x16x32_bf16 v[50:53], v[142:145], v[186:189], v[50:53]
	v_mfma_f32_16x16x32_bf16 v[54:57], v[122:125], v[182:185], v[54:57]
	v_mfma_f32_16x16x32_bf16 v[54:57], v[126:129], v[186:189], v[54:57]
	v_mfma_f32_16x16x32_bf16 v[46:49], v[122:125], v[190:193], v[46:49]
	v_mfma_f32_16x16x32_bf16 v[46:49], v[126:129], v[194:197], v[46:49]
	v_mfma_f32_16x16x32_bf16 v[42:45], v[130:133], v[190:193], v[42:45]
	v_mfma_f32_16x16x32_bf16 v[42:45], v[142:145], v[194:197], v[42:45]
	v_mfma_f32_16x16x32_bf16 v[34:37], v[130:133], v[198:201], v[34:37]
	v_mfma_f32_16x16x32_bf16 v[34:37], v[142:145], v[202:205], v[34:37]
	v_mfma_f32_16x16x32_bf16 v[38:41], v[122:125], v[198:201], v[38:41]
	v_mfma_f32_16x16x32_bf16 v[38:41], v[126:129], v[202:205], v[38:41]
	s_barrier
	s_setprio 0
	s_mov_b32 m0, s17
	s_mov_b32 s46, s42
	s_mov_b32 s47, s43
	ds_read_b128 v[164:167], v211 offset:16384
	ds_read_b128 v[168:171], v211 offset:17408
	ds_read_b128 v[182:185], v211 offset:18432
	ds_read_b128 v[186:189], v211 offset:19456
	ds_read_b128 v[190:193], v211 offset:20480
	ds_read_b128 v[194:197], v211 offset:21504
	ds_read_b128 v[198:201], v211 offset:22528
	ds_read_b128 v[202:205], v211 offset:23552
	buffer_load_dwordx4 v179, s[44:47], s66 offen lds
	s_mov_b32 m0, s18
	s_add_i32 s68, s66, 0x80000
	buffer_load_dwordx4 v207, s[44:47], s66 offen lds
	s_mov_b32 m0, s19
	s_nop 0
	buffer_load_dwordx4 v179, s[44:47], s68 offen lds
	s_mov_b32 m0, s20
	s_nop 0
	buffer_load_dwordx4 v207, s[44:47], s68 offen lds
	s_mov_b32 m0, s16
	s_nop 0
	buffer_load_dwordx4 v178, s[40:43], s67 offen lds
	s_mov_b32 m0, s21
	s_nop 0
	buffer_load_dwordx4 v206, s[40:43], s67 offen lds
	s_waitcnt vmcnt(8)
	s_waitcnt lgkmcnt(0)
	s_setprio 1
	s_barrier
	v_mfma_f32_16x16x32_bf16 v[94:97], v[106:109], v[164:167], v[94:97]
	v_mfma_f32_16x16x32_bf16 v[94:97], v[110:113], v[168:171], v[94:97]
	v_mfma_f32_16x16x32_bf16 v[90:93], v[114:117], v[164:167], v[90:93]
	v_mfma_f32_16x16x32_bf16 v[90:93], v[118:121], v[168:171], v[90:93]
	v_mfma_f32_16x16x32_bf16 v[82:85], v[114:117], v[182:185], v[82:85]
	v_mfma_f32_16x16x32_bf16 v[82:85], v[118:121], v[186:189], v[82:85]
	v_mfma_f32_16x16x32_bf16 v[86:89], v[106:109], v[182:185], v[86:89]
	v_mfma_f32_16x16x32_bf16 v[86:89], v[110:113], v[186:189], v[86:89]
	v_mfma_f32_16x16x32_bf16 v[78:81], v[106:109], v[190:193], v[78:81]
	v_mfma_f32_16x16x32_bf16 v[78:81], v[110:113], v[194:197], v[78:81]
	v_mfma_f32_16x16x32_bf16 v[74:77], v[114:117], v[190:193], v[74:77]
	v_mfma_f32_16x16x32_bf16 v[74:77], v[118:121], v[194:197], v[74:77]
	v_mfma_f32_16x16x32_bf16 v[66:69], v[114:117], v[198:201], v[66:69]
	v_mfma_f32_16x16x32_bf16 v[66:69], v[118:121], v[202:205], v[66:69]
	v_mfma_f32_16x16x32_bf16 v[70:73], v[106:109], v[198:201], v[70:73]
	v_mfma_f32_16x16x32_bf16 v[70:73], v[110:113], v[202:205], v[70:73]
	v_mfma_f32_16x16x32_bf16 v[30:33], v[122:125], v[164:167], v[30:33]
	v_mfma_f32_16x16x32_bf16 v[30:33], v[126:129], v[168:171], v[30:33]
	v_mfma_f32_16x16x32_bf16 v[26:29], v[130:133], v[164:167], v[26:29]
	v_mfma_f32_16x16x32_bf16 v[26:29], v[142:145], v[168:171], v[26:29]
	v_mfma_f32_16x16x32_bf16 v[18:21], v[130:133], v[182:185], v[18:21]
	v_mfma_f32_16x16x32_bf16 v[18:21], v[142:145], v[186:189], v[18:21]
	v_mfma_f32_16x16x32_bf16 v[22:25], v[122:125], v[182:185], v[22:25]
	v_mfma_f32_16x16x32_bf16 v[22:25], v[126:129], v[186:189], v[22:25]
	v_mfma_f32_16x16x32_bf16 v[14:17], v[122:125], v[190:193], v[14:17]
	v_mfma_f32_16x16x32_bf16 v[14:17], v[126:129], v[194:197], v[14:17]
	v_mfma_f32_16x16x32_bf16 v[10:13], v[130:133], v[190:193], v[10:13]
	v_mfma_f32_16x16x32_bf16 v[10:13], v[142:145], v[194:197], v[10:13]
	v_mfma_f32_16x16x32_bf16 v[2:5], v[130:133], v[198:201], v[2:5]
	v_mfma_f32_16x16x32_bf16 v[2:5], v[142:145], v[202:205], v[2:5]
	v_mfma_f32_16x16x32_bf16 v[6:9], v[122:125], v[198:201], v[6:9]
	v_mfma_f32_16x16x32_bf16 v[6:9], v[126:129], v[202:205], v[6:9]
	s_barrier
; #define PG8_STAGEX(rs, bufoff, soff, voff) do { _Pragma("unroll") for (int _i = 0; _i < 2; ++_i) \
;         __builtin_amdgcn_raw_ptr_buffer_load_lds(rs, (LAS unsigned*)(lds + (bufoff) + ldsw + _i * 8192), 16, (voff)[_i], (soff), 0, 0); } while (0)
; #define PG8_LDA(dst, b, h) do { _Pragma("unroll") for (int m = 0; m < 4; ++m) _Pragma("unroll") for (int k = 0; k < 2; ++k) dst[m][k] = *(const LAS bf16x8*)(lds + PG8_SA(b, h) + aoff + m * 2048 + k * 1024); } while (0)
; #define PG8_LDB(dst, b, h) do { _Pragma("unroll") for (int n = 0; n < 2; ++n) _Pragma("unroll") for (int k = 0; k < 2; ++k) dst[n][k] = *(const LAS bf16x8*)(lds + PG8_SB(b, h) + boff + n * 2048 + k * 1024); } while (0)
; #define PG8_WAIT_V(n) asm volatile("s_waitcnt vmcnt(" #n ")" ::: "memory")
; #define PG8_WAIT_L(n) asm volatile("s_waitcnt lgkmcnt(" #n ")" ::: "memory")
; #define PG8_BAR __builtin_amdgcn_s_barrier()
; #define PG8_SCHED __builtin_amdgcn_sched_barrier(0)
;     ...
;             PG8_LDB(B0, 1, 0); PG8_LDB(B1, 1, 1); PG8_SCHED; PG8_LDA(At, 1, 0); PG8_STAGEX(rsA, PG8_SA(0, 1), a2 + hstepA, voffA);
;             PG8_WAIT_V(8); PG8_WAIT_L(0); PG8_BAR; PG8_MMA(0, 0, At, B0); PG8_MMA(0, 1, At, B1); PG8_BAR; PG8_SCHED;
;             PG8_LDA(At, 1, 1); PG8_STAGEX(rsB, PG8_SB(1, 0), b3, voffB); PG8_STAGEX(rsB, PG8_SB(1, 1), b3 + hstepB, voffB); PG8_STAGEX(rsA, PG8_SA(1, 0), a3, voffA);
;             PG8_WAIT_V(8); PG8_WAIT_L(0); PG8_BAR; PG8_MMA(1, 0, At, B0); PG8_MMA(1, 1, At, B1); PG8_BAR; PG8_SCHED;
;         }
	s_setprio 0
	v_add_u32_e32 v118, 0x18000, v210
	v_add_u32_e32 v142, 0x1c000, v210
	ds_read_b128 v[106:109], v118
	ds_read_b128 v[110:113], v118 offset:1024
	ds_read_b128 v[114:117], v118 offset:2048
	ds_read_b128 v[118:121], v118 offset:3072
	ds_read_b128 v[122:125], v142
	ds_read_b128 v[126:129], v142 offset:1024
	ds_read_b128 v[130:133], v142 offset:2048
	ds_read_b128 v[142:145], v142 offset:3072
	s_add_i32 s67, s67, 0x80000
	s_mov_b32 m0, s22
	ds_read_b128 v[164:167], v211 offset:32768
	ds_read_b128 v[168:171], v211 offset:33792
	ds_read_b128 v[182:185], v211 offset:34816
	ds_read_b128 v[186:189], v211 offset:35840
	ds_read_b128 v[190:193], v211 offset:36864
	ds_read_b128 v[194:197], v211 offset:37888
	ds_read_b128 v[198:201], v211 offset:38912
	ds_read_b128 v[202:205], v211 offset:39936
	buffer_load_dwordx4 v178, s[40:43], s67 offen lds
	s_mov_b32 m0, s23
	s_nop 0
	buffer_load_dwordx4 v206, s[40:43], s67 offen lds
	s_waitcnt vmcnt(8)
	s_waitcnt lgkmcnt(0)
	s_setprio 1
	s_barrier
	v_mfma_f32_16x16x32_bf16 v[158:161], v[106:109], v[164:167], v[158:161]
	v_mfma_f32_16x16x32_bf16 v[158:161], v[110:113], v[168:171], v[158:161]
	v_mfma_f32_16x16x32_bf16 v[154:157], v[114:117], v[164:167], v[154:157]
	v_mfma_f32_16x16x32_bf16 v[154:157], v[118:121], v[168:171], v[154:157]
	v_mfma_f32_16x16x32_bf16 v[146:149], v[114:117], v[182:185], v[146:149]
	v_mfma_f32_16x16x32_bf16 v[146:149], v[118:121], v[186:189], v[146:149]
	v_mfma_f32_16x16x32_bf16 v[150:153], v[106:109], v[182:185], v[150:153]
	v_mfma_f32_16x16x32_bf16 v[150:153], v[110:113], v[186:189], v[150:153]
	v_mfma_f32_16x16x32_bf16 v[138:141], v[106:109], v[190:193], v[138:141]
	v_mfma_f32_16x16x32_bf16 v[138:141], v[110:113], v[194:197], v[138:141]
	v_mfma_f32_16x16x32_bf16 v[134:137], v[114:117], v[190:193], v[134:137]
	v_mfma_f32_16x16x32_bf16 v[134:137], v[118:121], v[194:197], v[134:137]
	v_mfma_f32_16x16x32_bf16 v[98:101], v[114:117], v[198:201], v[98:101]
	v_mfma_f32_16x16x32_bf16 v[98:101], v[118:121], v[202:205], v[98:101]
	v_mfma_f32_16x16x32_bf16 v[102:105], v[106:109], v[198:201], v[102:105]
	v_mfma_f32_16x16x32_bf16 v[102:105], v[110:113], v[202:205], v[102:105]
	v_mfma_f32_16x16x32_bf16 v[62:65], v[122:125], v[164:167], v[62:65]
	v_mfma_f32_16x16x32_bf16 v[62:65], v[126:129], v[168:171], v[62:65]
	v_mfma_f32_16x16x32_bf16 v[58:61], v[130:133], v[164:167], v[58:61]
	v_mfma_f32_16x16x32_bf16 v[58:61], v[142:145], v[168:171], v[58:61]
	v_mfma_f32_16x16x32_bf16 v[50:53], v[130:133], v[182:185], v[50:53]
	v_mfma_f32_16x16x32_bf16 v[50:53], v[142:145], v[186:189], v[50:53]
	v_mfma_f32_16x16x32_bf16 v[54:57], v[122:125], v[182:185], v[54:57]
	v_mfma_f32_16x16x32_bf16 v[54:57], v[126:129], v[186:189], v[54:57]
	v_mfma_f32_16x16x32_bf16 v[46:49], v[122:125], v[190:193], v[46:49]
	v_mfma_f32_16x16x32_bf16 v[46:49], v[126:129], v[194:197], v[46:49]
	v_mfma_f32_16x16x32_bf16 v[42:45], v[130:133], v[190:193], v[42:45]
	v_mfma_f32_16x16x32_bf16 v[42:45], v[142:145], v[194:197], v[42:45]
	v_mfma_f32_16x16x32_bf16 v[34:37], v[130:133], v[198:201], v[34:37]
	v_mfma_f32_16x16x32_bf16 v[34:37], v[142:145], v[202:205], v[34:37]
	v_mfma_f32_16x16x32_bf16 v[38:41], v[122:125], v[198:201], v[38:41]
	v_mfma_f32_16x16x32_bf16 v[38:41], v[126:129], v[202:205], v[38:41]
	s_barrier
	s_setprio 0
	s_mov_b32 m0, s54
	s_or_b32 s67, s66, 0x80
	ds_read_b128 v[164:167], v211 offset:49152
	ds_read_b128 v[168:171], v211 offset:50176
	ds_read_b128 v[182:185], v211 offset:51200
	ds_read_b128 v[186:189], v211 offset:52224
	ds_read_b128 v[190:193], v211 offset:53248
	ds_read_b128 v[194:197], v211 offset:54272
	ds_read_b128 v[198:201], v211 offset:55296
	ds_read_b128 v[202:205], v211 offset:56320
	buffer_load_dwordx4 v179, s[44:47], s67 offen lds
	s_mov_b32 m0, s55
	s_add_i32 s66, s66, 0x80080
	buffer_load_dwordx4 v207, s[44:47], s67 offen lds
	s_mov_b32 m0, s74
	s_nop 0
	buffer_load_dwordx4 v179, s[44:47], s66 offen lds
	s_mov_b32 m0, s75
	s_nop 0
	buffer_load_dwordx4 v207, s[44:47], s66 offen lds
	s_mov_b32 m0, s72
	s_nop 0
	buffer_load_dwordx4 v178, s[40:43], s65 offen lds
	s_mov_b32 m0, s73
	s_nop 0
	buffer_load_dwordx4 v206, s[40:43], s65 offen lds
	s_waitcnt vmcnt(8)
	s_waitcnt lgkmcnt(0)
	s_setprio 1
	s_barrier
	v_mfma_f32_16x16x32_bf16 v[94:97], v[106:109], v[164:167], v[94:97]
	v_mfma_f32_16x16x32_bf16 v[94:97], v[110:113], v[168:171], v[94:97]
	v_mfma_f32_16x16x32_bf16 v[90:93], v[114:117], v[164:167], v[90:93]
	v_mfma_f32_16x16x32_bf16 v[90:93], v[118:121], v[168:171], v[90:93]
	v_mfma_f32_16x16x32_bf16 v[82:85], v[114:117], v[182:185], v[82:85]
	v_mfma_f32_16x16x32_bf16 v[82:85], v[118:121], v[186:189], v[82:85]
	v_mfma_f32_16x16x32_bf16 v[86:89], v[106:109], v[182:185], v[86:89]
	v_mfma_f32_16x16x32_bf16 v[86:89], v[110:113], v[186:189], v[86:89]
	v_mfma_f32_16x16x32_bf16 v[78:81], v[106:109], v[190:193], v[78:81]
	v_mfma_f32_16x16x32_bf16 v[78:81], v[110:113], v[194:197], v[78:81]
	v_mfma_f32_16x16x32_bf16 v[74:77], v[114:117], v[190:193], v[74:77]
	v_mfma_f32_16x16x32_bf16 v[74:77], v[118:121], v[194:197], v[74:77]
	v_mfma_f32_16x16x32_bf16 v[66:69], v[114:117], v[198:201], v[66:69]
	v_mfma_f32_16x16x32_bf16 v[66:69], v[118:121], v[202:205], v[66:69]
	v_mfma_f32_16x16x32_bf16 v[70:73], v[106:109], v[198:201], v[70:73]
	v_mfma_f32_16x16x32_bf16 v[70:73], v[110:113], v[202:205], v[70:73]
	v_mfma_f32_16x16x32_bf16 v[30:33], v[122:125], v[164:167], v[30:33]
	v_mfma_f32_16x16x32_bf16 v[30:33], v[126:129], v[168:171], v[30:33]
	v_mfma_f32_16x16x32_bf16 v[26:29], v[130:133], v[164:167], v[26:29]
	v_mfma_f32_16x16x32_bf16 v[26:29], v[142:145], v[168:171], v[26:29]
	v_mfma_f32_16x16x32_bf16 v[18:21], v[130:133], v[182:185], v[18:21]
	v_mfma_f32_16x16x32_bf16 v[18:21], v[142:145], v[186:189], v[18:21]
	v_mfma_f32_16x16x32_bf16 v[22:25], v[122:125], v[182:185], v[22:25]
	v_mfma_f32_16x16x32_bf16 v[22:25], v[126:129], v[186:189], v[22:25]
	v_mfma_f32_16x16x32_bf16 v[14:17], v[122:125], v[190:193], v[14:17]
	v_mfma_f32_16x16x32_bf16 v[14:17], v[126:129], v[194:197], v[14:17]
	v_mfma_f32_16x16x32_bf16 v[10:13], v[130:133], v[190:193], v[10:13]
	v_mfma_f32_16x16x32_bf16 v[10:13], v[142:145], v[194:197], v[10:13]
	v_mfma_f32_16x16x32_bf16 v[2:5], v[130:133], v[198:201], v[2:5]
	v_mfma_f32_16x16x32_bf16 v[2:5], v[142:145], v[202:205], v[2:5]
	v_mfma_f32_16x16x32_bf16 v[6:9], v[122:125], v[198:201], v[6:9]
	v_mfma_f32_16x16x32_bf16 v[6:9], v[126:129], v[202:205], v[6:9]
	s_barrier
	s_setprio 0
	s_add_i32 s64, s64, 2
	s_addk_i32 s59, 0x100
	s_addk_i32 s63, 0x100
	s_cmp_gt_u32 s64, 29
	s_cbranch_scc0 .LBB0_1529
	s_and_b64 vcc, exec, s[52:53]
	s_cbranch_vccz .LBB0_1532
	s_barrier

; #define PG8_STAGEX(rs, bufoff, soff, voff) do { _Pragma("unroll") for (int _i = 0; _i < 2; ++_i) \
;         __builtin_amdgcn_raw_ptr_buffer_load_lds(rs, (LAS unsigned*)(lds + (bufoff) + ldsw + _i * 8192), 16, (voff)[_i], (soff), 0, 0); } while (0)
; #define PG8_LDA(dst, b, h) do { _Pragma("unroll") for (int m = 0; m < 4; ++m) _Pragma("unroll") for (int k = 0; k < 2; ++k) dst[m][k] = *(const LAS bf16x8*)(lds + PG8_SA(b, h) + aoff + m * 2048 + k * 1024); } while (0)
; #define PG8_LDB(dst, b, h) do { _Pragma("unroll") for (int n = 0; n < 2; ++n) _Pragma("unroll") for (int k = 0; k < 2; ++k) dst[n][k] = *(const LAS bf16x8*)(lds + PG8_SB(b, h) + boff + n * 2048 + k * 1024); } while (0)
; #define PG8_WAIT_V(n) asm volatile("s_waitcnt vmcnt(" #n ")" ::: "memory")
; #define PG8_WAIT_L(n) asm volatile("s_waitcnt lgkmcnt(" #n ")" ::: "memory")
; #define PG8_BAR __builtin_amdgcn_s_barrier()
; #define PG8_SCHED __builtin_amdgcn_sched_barrier(0)
;     ...
;         for (int t = 0; t < nt; t += 2) {
;             const bool last = (t == nt - 2);
;             const unsigned a1 = cA + (unsigned)(t + 1) * kstep;
;             const unsigned a2 = last ? nA : cA + (unsigned)(t + 2) * kstep, b2 = last ? nB : cB + (unsigned)(t + 2) * kstep;
;             const unsigned a3 = a2 + kstep, b3 = b2 + kstep;
;             PG8_LDB(B0, 0, 0); PG8_LDB(B1, 0, 1); PG8_SCHED; PG8_LDA(At, 0, 0); PG8_STAGEX(rsA, PG8_SA(1, 1), a1 + hstepA, voffA);
;             PG8_WAIT_V(8); PG8_WAIT_L(0); PG8_BAR; PG8_MMA(0, 0, At, B0); PG8_MMA(0, 1, At, B1); PG8_BAR; PG8_SCHED;
;             PG8_LDA(At, 0, 1); PG8_STAGEX(rsB, PG8_SB(0, 0), b2, voffB); PG8_STAGEX(rsB, PG8_SB(0, 1), b2 + hstepB, voffB); PG8_STAGEX(rsA, PG8_SA(0, 0), a2, voffA);
;             PG8_WAIT_V(8); PG8_WAIT_L(0); PG8_BAR; PG8_MMA(1, 0, At, B0); PG8_MMA(1, 1, At, B1); PG8_BAR; PG8_SCHED;
.LBB0_1651:
	v_add_u32_e32 v102, 0x10000, v172
	v_add_u32_e32 v146, 0x14000, v172
	ds_read_b128 v[82:85], v102
	ds_read_b128 v[86:89], v102 offset:1024
	ds_read_b128 v[98:101], v102 offset:2048
	ds_read_b128 v[102:105], v102 offset:3072
	ds_read_b128 v[150:153], v146
	ds_read_b128 v[154:157], v146 offset:1024
	ds_read_b128 v[182:185], v146 offset:2048
	ds_read_b128 v[186:189], v146 offset:3072
	s_add_i32 s42, s61, 0xfff80080
	s_cmp_eq_u32 s63, 28
	s_cselect_b32 s66, s30, s42
	s_cselect_b32 s65, s31, s62
	s_or_b32 s64, s66, 0x80
	s_mov_b32 m0, s29
	ds_read_b128 v[190:193], v173
	ds_read_b128 v[194:197], v173 offset:1024
	ds_read_b128 v[198:201], v173 offset:2048
	ds_read_b128 v[202:205], v173 offset:3072
	ds_read_b128 v[206:209], v173 offset:4096
	ds_read_b128 v[210:213], v173 offset:5120
	ds_read_b128 v[214:217], v173 offset:6144
	ds_read_b128 v[218:221], v173 offset:7168
	buffer_load_dwordx4 v159, s[76:79], s61 offen lds
	s_mov_b32 m0, s50
	s_nop 0
	buffer_load_dwordx4 v163, s[76:79], s61 offen lds
	s_waitcnt vmcnt(8)
	s_waitcnt lgkmcnt(0)
	s_setprio 1
	s_barrier
	v_mfma_f32_16x16x32_bf16 v[142:145], v[82:85], v[190:193], v[142:145]
	v_mfma_f32_16x16x32_bf16 v[142:145], v[86:89], v[194:197], v[142:145]
	v_mfma_f32_16x16x32_bf16 v[134:137], v[98:101], v[190:193], v[134:137]
	v_mfma_f32_16x16x32_bf16 v[134:137], v[102:105], v[194:197], v[134:137]
	v_mfma_f32_16x16x32_bf16 v[118:121], v[98:101], v[198:201], v[118:121]
	v_mfma_f32_16x16x32_bf16 v[118:121], v[102:105], v[202:205], v[118:121]
	v_mfma_f32_16x16x32_bf16 v[126:129], v[82:85], v[198:201], v[126:129]
	v_mfma_f32_16x16x32_bf16 v[126:129], v[86:89], v[202:205], v[126:129]
	v_mfma_f32_16x16x32_bf16 v[110:113], v[82:85], v[206:209], v[110:113]
	v_mfma_f32_16x16x32_bf16 v[110:113], v[86:89], v[210:213], v[110:113]
	v_mfma_f32_16x16x32_bf16 v[94:97], v[98:101], v[206:209], v[94:97]
	v_mfma_f32_16x16x32_bf16 v[94:97], v[102:105], v[210:213], v[94:97]
	v_mfma_f32_16x16x32_bf16 v[70:73], v[98:101], v[214:217], v[70:73]
	v_mfma_f32_16x16x32_bf16 v[70:73], v[102:105], v[218:221], v[70:73]
	v_mfma_f32_16x16x32_bf16 v[78:81], v[82:85], v[214:217], v[78:81]
	v_mfma_f32_16x16x32_bf16 v[78:81], v[86:89], v[218:221], v[78:81]
	v_mfma_f32_16x16x32_bf16 v[138:141], v[150:153], v[190:193], v[138:141]
	v_mfma_f32_16x16x32_bf16 v[138:141], v[154:157], v[194:197], v[138:141]
	v_mfma_f32_16x16x32_bf16 v[130:133], v[182:185], v[190:193], v[130:133]
	v_mfma_f32_16x16x32_bf16 v[130:133], v[186:189], v[194:197], v[130:133]
	v_mfma_f32_16x16x32_bf16 v[114:117], v[182:185], v[198:201], v[114:117]
	v_mfma_f32_16x16x32_bf16 v[114:117], v[186:189], v[202:205], v[114:117]
	v_mfma_f32_16x16x32_bf16 v[122:125], v[150:153], v[198:201], v[122:125]
	v_mfma_f32_16x16x32_bf16 v[122:125], v[154:157], v[202:205], v[122:125]
	v_mfma_f32_16x16x32_bf16 v[106:109], v[150:153], v[206:209], v[106:109]
	v_mfma_f32_16x16x32_bf16 v[106:109], v[154:157], v[210:213], v[106:109]
	v_mfma_f32_16x16x32_bf16 v[90:93], v[182:185], v[206:209], v[90:93]
	v_mfma_f32_16x16x32_bf16 v[90:93], v[186:189], v[210:213], v[90:93]
	v_mfma_f32_16x16x32_bf16 v[66:69], v[182:185], v[214:217], v[66:69]
	v_mfma_f32_16x16x32_bf16 v[66:69], v[186:189], v[218:221], v[66:69]
	v_mfma_f32_16x16x32_bf16 v[74:77], v[150:153], v[214:217], v[74:77]
	v_mfma_f32_16x16x32_bf16 v[74:77], v[154:157], v[218:221], v[74:77]
	s_barrier
	s_setprio 0
	s_mov_b32 m0, s16
	s_mov_b32 s42, s78
	s_mov_b32 s43, s79
	ds_read_b128 v[190:193], v173 offset:16384
	ds_read_b128 v[194:197], v173 offset:17408
	ds_read_b128 v[198:201], v173 offset:18432
	ds_read_b128 v[202:205], v173 offset:19456
	ds_read_b128 v[206:209], v173 offset:20480
	ds_read_b128 v[210:213], v173 offset:21504
	ds_read_b128 v[214:217], v173 offset:22528
	ds_read_b128 v[218:221], v173 offset:23552
	buffer_load_dwordx4 v161, s[40:43], s65 offen lds
	s_mov_b32 m0, s17
	s_add_i32 s67, s65, 0x80000
	buffer_load_dwordx4 v165, s[40:43], s65 offen lds
	s_mov_b32 m0, s18
	s_nop 0
	buffer_load_dwordx4 v161, s[40:43], s67 offen lds
	s_mov_b32 m0, s19
	s_nop 0
	buffer_load_dwordx4 v165, s[40:43], s67 offen lds
	s_mov_b32 m0, s15
	s_nop 0
	buffer_load_dwordx4 v159, s[76:79], s66 offen lds
	s_mov_b32 m0, s20
	s_nop 0
	buffer_load_dwordx4 v163, s[76:79], s66 offen lds
	s_waitcnt vmcnt(8)
	s_waitcnt lgkmcnt(0)
	s_setprio 1
	s_barrier
	v_mfma_f32_16x16x32_bf16 v[62:65], v[82:85], v[190:193], v[62:65]
	v_mfma_f32_16x16x32_bf16 v[62:65], v[86:89], v[194:197], v[62:65]
	v_mfma_f32_16x16x32_bf16 v[54:57], v[98:101], v[190:193], v[54:57]
	v_mfma_f32_16x16x32_bf16 v[54:57], v[102:105], v[194:197], v[54:57]
	v_mfma_f32_16x16x32_bf16 v[38:41], v[98:101], v[198:201], v[38:41]
	v_mfma_f32_16x16x32_bf16 v[38:41], v[102:105], v[202:205], v[38:41]
	v_mfma_f32_16x16x32_bf16 v[46:49], v[82:85], v[198:201], v[46:49]
	v_mfma_f32_16x16x32_bf16 v[46:49], v[86:89], v[202:205], v[46:49]
	v_mfma_f32_16x16x32_bf16 v[30:33], v[82:85], v[206:209], v[30:33]
	v_mfma_f32_16x16x32_bf16 v[30:33], v[86:89], v[210:213], v[30:33]
	v_mfma_f32_16x16x32_bf16 v[22:25], v[98:101], v[206:209], v[22:25]
	v_mfma_f32_16x16x32_bf16 v[22:25], v[102:105], v[210:213], v[22:25]
	v_mfma_f32_16x16x32_bf16 v[6:9], v[98:101], v[214:217], v[6:9]
	v_mfma_f32_16x16x32_bf16 v[6:9], v[102:105], v[218:221], v[6:9]
	v_mfma_f32_16x16x32_bf16 v[14:17], v[82:85], v[214:217], v[14:17]
	v_mfma_f32_16x16x32_bf16 v[14:17], v[86:89], v[218:221], v[14:17]
	v_mfma_f32_16x16x32_bf16 v[58:61], v[150:153], v[190:193], v[58:61]
	v_mfma_f32_16x16x32_bf16 v[58:61], v[154:157], v[194:197], v[58:61]
	v_mfma_f32_16x16x32_bf16 v[50:53], v[182:185], v[190:193], v[50:53]
	v_mfma_f32_16x16x32_bf16 v[50:53], v[186:189], v[194:197], v[50:53]
	v_mfma_f32_16x16x32_bf16 v[34:37], v[182:185], v[198:201], v[34:37]
	v_mfma_f32_16x16x32_bf16 v[34:37], v[186:189], v[202:205], v[34:37]
	v_mfma_f32_16x16x32_bf16 v[42:45], v[150:153], v[198:201], v[42:45]
	v_mfma_f32_16x16x32_bf16 v[42:45], v[154:157], v[202:205], v[42:45]
	v_mfma_f32_16x16x32_bf16 v[26:29], v[150:153], v[206:209], v[26:29]
	v_mfma_f32_16x16x32_bf16 v[26:29], v[154:157], v[210:213], v[26:29]
	v_mfma_f32_16x16x32_bf16 v[18:21], v[182:185], v[206:209], v[18:21]
	v_mfma_f32_16x16x32_bf16 v[18:21], v[186:189], v[210:213], v[18:21]
	v_mfma_f32_16x16x32_bf16 v[2:5], v[182:185], v[214:217], v[2:5]
	v_mfma_f32_16x16x32_bf16 v[2:5], v[186:189], v[218:221], v[2:5]
	v_mfma_f32_16x16x32_bf16 v[10:13], v[150:153], v[214:217], v[10:13]
	v_mfma_f32_16x16x32_bf16 v[10:13], v[154:157], v[218:221], v[10:13]
	s_barrier
; #define PG8_STAGEX(rs, bufoff, soff, voff) do { _Pragma("unroll") for (int _i = 0; _i < 2; ++_i) \
;         __builtin_amdgcn_raw_ptr_buffer_load_lds(rs, (LAS unsigned*)(lds + (bufoff) + ldsw + _i * 8192), 16, (voff)[_i], (soff), 0, 0); } while (0)
; #define PG8_LDA(dst, b, h) do { _Pragma("unroll") for (int m = 0; m < 4; ++m) _Pragma("unroll") for (int k = 0; k < 2; ++k) dst[m][k] = *(const LAS bf16x8*)(lds + PG8_SA(b, h) + aoff + m * 2048 + k * 1024); } while (0)
; #define PG8_LDB(dst, b, h) do { _Pragma("unroll") for (int n = 0; n < 2; ++n) _Pragma("unroll") for (int k = 0; k < 2; ++k) dst[n][k] = *(const LAS bf16x8*)(lds + PG8_SB(b, h) + boff + n * 2048 + k * 1024); } while (0)
; #define PG8_WAIT_V(n) asm volatile("s_waitcnt vmcnt(" #n ")" ::: "memory")
; #define PG8_WAIT_L(n) asm volatile("s_waitcnt lgkmcnt(" #n ")" ::: "memory")
; #define PG8_BAR __builtin_amdgcn_s_barrier()
; #define PG8_SCHED __builtin_amdgcn_sched_barrier(0)
;     ...
;             PG8_LDB(B0, 1, 0); PG8_LDB(B1, 1, 1); PG8_SCHED; PG8_LDA(At, 1, 0); PG8_STAGEX(rsA, PG8_SA(0, 1), a2 + hstepA, voffA);
;             PG8_WAIT_V(8); PG8_WAIT_L(0); PG8_BAR; PG8_MMA(0, 0, At, B0); PG8_MMA(0, 1, At, B1); PG8_BAR; PG8_SCHED;
;             PG8_LDA(At, 1, 1); PG8_STAGEX(rsB, PG8_SB(1, 0), b3, voffB); PG8_STAGEX(rsB, PG8_SB(1, 1), b3 + hstepB, voffB); PG8_STAGEX(rsA, PG8_SA(1, 0), a3, voffA);
;             PG8_WAIT_V(8); PG8_WAIT_L(0); PG8_BAR; PG8_MMA(1, 0, At, B0); PG8_MMA(1, 1, At, B1); PG8_BAR; PG8_SCHED;
;         }
	s_setprio 0
	v_add_u32_e32 v102, 0x18000, v172
	v_add_u32_e32 v146, 0x1c000, v172
	ds_read_b128 v[82:85], v102
	ds_read_b128 v[86:89], v102 offset:1024
	ds_read_b128 v[98:101], v102 offset:2048
	ds_read_b128 v[102:105], v102 offset:3072
	ds_read_b128 v[150:153], v146
	ds_read_b128 v[154:157], v146 offset:1024
	ds_read_b128 v[182:185], v146 offset:2048
	ds_read_b128 v[186:189], v146 offset:3072
	s_add_i32 s66, s66, 0x80000
	s_mov_b32 m0, s21
	ds_read_b128 v[190:193], v173 offset:32768
	ds_read_b128 v[194:197], v173 offset:33792
	ds_read_b128 v[198:201], v173 offset:34816
	ds_read_b128 v[202:205], v173 offset:35840
	ds_read_b128 v[206:209], v173 offset:36864
	ds_read_b128 v[210:213], v173 offset:37888
	ds_read_b128 v[214:217], v173 offset:38912
	ds_read_b128 v[218:221], v173 offset:39936
	buffer_load_dwordx4 v159, s[76:79], s66 offen lds
	s_mov_b32 m0, s22
	s_nop 0
	buffer_load_dwordx4 v163, s[76:79], s66 offen lds
	s_waitcnt vmcnt(8)
	s_waitcnt lgkmcnt(0)
	s_setprio 1
	s_barrier
	v_mfma_f32_16x16x32_bf16 v[142:145], v[82:85], v[190:193], v[142:145]
	v_mfma_f32_16x16x32_bf16 v[142:145], v[86:89], v[194:197], v[142:145]
	v_mfma_f32_16x16x32_bf16 v[134:137], v[98:101], v[190:193], v[134:137]
	v_mfma_f32_16x16x32_bf16 v[134:137], v[102:105], v[194:197], v[134:137]
	v_mfma_f32_16x16x32_bf16 v[118:121], v[98:101], v[198:201], v[118:121]
	v_mfma_f32_16x16x32_bf16 v[118:121], v[102:105], v[202:205], v[118:121]
	v_mfma_f32_16x16x32_bf16 v[126:129], v[82:85], v[198:201], v[126:129]
	v_mfma_f32_16x16x32_bf16 v[126:129], v[86:89], v[202:205], v[126:129]
	v_mfma_f32_16x16x32_bf16 v[110:113], v[82:85], v[206:209], v[110:113]
	v_mfma_f32_16x16x32_bf16 v[110:113], v[86:89], v[210:213], v[110:113]
	v_mfma_f32_16x16x32_bf16 v[94:97], v[98:101], v[206:209], v[94:97]
	v_mfma_f32_16x16x32_bf16 v[94:97], v[102:105], v[210:213], v[94:97]
	v_mfma_f32_16x16x32_bf16 v[70:73], v[98:101], v[214:217], v[70:73]
	v_mfma_f32_16x16x32_bf16 v[70:73], v[102:105], v[218:221], v[70:73]
	v_mfma_f32_16x16x32_bf16 v[78:81], v[82:85], v[214:217], v[78:81]
	v_mfma_f32_16x16x32_bf16 v[78:81], v[86:89], v[218:221], v[78:81]
	v_mfma_f32_16x16x32_bf16 v[138:141], v[150:153], v[190:193], v[138:141]
	v_mfma_f32_16x16x32_bf16 v[138:141], v[154:157], v[194:197], v[138:141]
	v_mfma_f32_16x16x32_bf16 v[130:133], v[182:185], v[190:193], v[130:133]
	v_mfma_f32_16x16x32_bf16 v[130:133], v[186:189], v[194:197], v[130:133]
	v_mfma_f32_16x16x32_bf16 v[114:117], v[182:185], v[198:201], v[114:117]
	v_mfma_f32_16x16x32_bf16 v[114:117], v[186:189], v[202:205], v[114:117]
	v_mfma_f32_16x16x32_bf16 v[122:125], v[150:153], v[198:201], v[122:125]
	v_mfma_f32_16x16x32_bf16 v[122:125], v[154:157], v[202:205], v[122:125]
	v_mfma_f32_16x16x32_bf16 v[106:109], v[150:153], v[206:209], v[106:109]
	v_mfma_f32_16x16x32_bf16 v[106:109], v[154:157], v[210:213], v[106:109]
	v_mfma_f32_16x16x32_bf16 v[90:93], v[182:185], v[206:209], v[90:93]
	v_mfma_f32_16x16x32_bf16 v[90:93], v[186:189], v[210:213], v[90:93]
	v_mfma_f32_16x16x32_bf16 v[66:69], v[182:185], v[214:217], v[66:69]
	v_mfma_f32_16x16x32_bf16 v[66:69], v[186:189], v[218:221], v[66:69]
	v_mfma_f32_16x16x32_bf16 v[74:77], v[150:153], v[214:217], v[74:77]
	v_mfma_f32_16x16x32_bf16 v[74:77], v[154:157], v[218:221], v[74:77]
	s_barrier
	s_setprio 0
	s_mov_b32 m0, s23
	s_or_b32 s66, s65, 0x80
	ds_read_b128 v[190:193], v173 offset:49152
	ds_read_b128 v[194:197], v173 offset:50176
	ds_read_b128 v[198:201], v173 offset:51200
	ds_read_b128 v[202:205], v173 offset:52224
	ds_read_b128 v[206:209], v173 offset:53248
	ds_read_b128 v[210:213], v173 offset:54272
	ds_read_b128 v[214:217], v173 offset:55296
	ds_read_b128 v[218:221], v173 offset:56320
	buffer_load_dwordx4 v161, s[40:43], s66 offen lds
	s_mov_b32 m0, s24
	s_add_i32 s65, s65, 0x80080
	buffer_load_dwordx4 v165, s[40:43], s66 offen lds
	s_mov_b32 m0, s27
	s_nop 0
	buffer_load_dwordx4 v161, s[40:43], s65 offen lds
	s_mov_b32 m0, s28
	s_nop 0
	buffer_load_dwordx4 v165, s[40:43], s65 offen lds
	s_mov_b32 m0, s25
	s_nop 0
	buffer_load_dwordx4 v159, s[76:79], s64 offen lds
	s_mov_b32 m0, s26
	s_nop 0
	buffer_load_dwordx4 v163, s[76:79], s64 offen lds
	s_waitcnt vmcnt(8)
	s_waitcnt lgkmcnt(0)
	s_setprio 1
	s_barrier
	v_mfma_f32_16x16x32_bf16 v[62:65], v[82:85], v[190:193], v[62:65]
	v_mfma_f32_16x16x32_bf16 v[62:65], v[86:89], v[194:197], v[62:65]
	v_mfma_f32_16x16x32_bf16 v[54:57], v[98:101], v[190:193], v[54:57]
	v_mfma_f32_16x16x32_bf16 v[54:57], v[102:105], v[194:197], v[54:57]
	v_mfma_f32_16x16x32_bf16 v[38:41], v[98:101], v[198:201], v[38:41]
	v_mfma_f32_16x16x32_bf16 v[38:41], v[102:105], v[202:205], v[38:41]
	v_mfma_f32_16x16x32_bf16 v[46:49], v[82:85], v[198:201], v[46:49]
	v_mfma_f32_16x16x32_bf16 v[46:49], v[86:89], v[202:205], v[46:49]
	v_mfma_f32_16x16x32_bf16 v[30:33], v[82:85], v[206:209], v[30:33]
	v_mfma_f32_16x16x32_bf16 v[30:33], v[86:89], v[210:213], v[30:33]
	v_mfma_f32_16x16x32_bf16 v[22:25], v[98:101], v[206:209], v[22:25]
	v_mfma_f32_16x16x32_bf16 v[22:25], v[102:105], v[210:213], v[22:25]
	v_mfma_f32_16x16x32_bf16 v[6:9], v[98:101], v[214:217], v[6:9]
	v_mfma_f32_16x16x32_bf16 v[6:9], v[102:105], v[218:221], v[6:9]
	v_mfma_f32_16x16x32_bf16 v[14:17], v[82:85], v[214:217], v[14:17]
	v_mfma_f32_16x16x32_bf16 v[14:17], v[86:89], v[218:221], v[14:17]
	v_mfma_f32_16x16x32_bf16 v[58:61], v[150:153], v[190:193], v[58:61]
	v_mfma_f32_16x16x32_bf16 v[58:61], v[154:157], v[194:197], v[58:61]
	v_mfma_f32_16x16x32_bf16 v[50:53], v[182:185], v[190:193], v[50:53]
	v_mfma_f32_16x16x32_bf16 v[50:53], v[186:189], v[194:197], v[50:53]
	v_mfma_f32_16x16x32_bf16 v[34:37], v[182:185], v[198:201], v[34:37]
	v_mfma_f32_16x16x32_bf16 v[34:37], v[186:189], v[202:205], v[34:37]
	v_mfma_f32_16x16x32_bf16 v[42:45], v[150:153], v[198:201], v[42:45]
	v_mfma_f32_16x16x32_bf16 v[42:45], v[154:157], v[202:205], v[42:45]
	v_mfma_f32_16x16x32_bf16 v[26:29], v[150:153], v[206:209], v[26:29]
	v_mfma_f32_16x16x32_bf16 v[26:29], v[154:157], v[210:213], v[26:29]
	v_mfma_f32_16x16x32_bf16 v[18:21], v[182:185], v[206:209], v[18:21]
	v_mfma_f32_16x16x32_bf16 v[18:21], v[186:189], v[210:213], v[18:21]
	v_mfma_f32_16x16x32_bf16 v[2:5], v[182:185], v[214:217], v[2:5]
	v_mfma_f32_16x16x32_bf16 v[2:5], v[186:189], v[218:221], v[2:5]
	v_mfma_f32_16x16x32_bf16 v[10:13], v[150:153], v[214:217], v[10:13]
	v_mfma_f32_16x16x32_bf16 v[10:13], v[154:157], v[218:221], v[10:13]
	s_barrier
	s_setprio 0
	s_add_i32 s63, s63, 2
	s_addk_i32 s61, 0x100
	s_addk_i32 s62, 0x100
	s_cmp_gt_u32 s63, 29
	s_cbranch_scc0 .LBB0_1651
	s_and_b64 vcc, exec, s[48:49]
	s_cbranch_vccz .LBB0_1654
	s_barrier

; #define PG8_STAGEX(rs, bufoff, soff, voff) do { _Pragma("unroll") for (int _i = 0; _i < 2; ++_i) \
;         __builtin_amdgcn_raw_ptr_buffer_load_lds(rs, (LAS unsigned*)(lds + (bufoff) + ldsw + _i * 8192), 16, (voff)[_i], (soff), 0, 0); } while (0)
; #define PG8_LDA(dst, b, h) do { _Pragma("unroll") for (int m = 0; m < 4; ++m) _Pragma("unroll") for (int k = 0; k < 2; ++k) dst[m][k] = *(const LAS bf16x8*)(lds + PG8_SA(b, h) + aoff + m * 2048 + k * 1024); } while (0)
; #define PG8_LDB(dst, b, h) do { _Pragma("unroll") for (int n = 0; n < 2; ++n) _Pragma("unroll") for (int k = 0; k < 2; ++k) dst[n][k] = *(const LAS bf16x8*)(lds + PG8_SB(b, h) + boff + n * 2048 + k * 1024); } while (0)
; #define PG8_WAIT_V(n) asm volatile("s_waitcnt vmcnt(" #n ")" ::: "memory")
; #define PG8_WAIT_L(n) asm volatile("s_waitcnt lgkmcnt(" #n ")" ::: "memory")
; #define PG8_BAR __builtin_amdgcn_s_barrier()
; #define PG8_SCHED __builtin_amdgcn_sched_barrier(0)
;     ...
;                 if (w0) { PG8_LDB(B0, 0, 0); PG8_LDB(B1, 0, 1); PG8_SCHED; PG8_LDA(At, 0, 0); }
;                 PG8_WAIT_L(0); PG8_BAR; if (w0) { PG8_MMA(0, 0, At, B0); PG8_MMA(0, 1, At, B1); } PG8_BAR; PG8_SCHED;
;                 PG8_STAGEX(rsB, PG8_SB(0, 0), b2, voffB); PG8_STAGEX(rsB, PG8_SB(0, 1), b2 + hstepB, voffB); PG8_STAGEX(rsA, PG8_SA(0, 0), a2, voffA);
;                 PG8_WAIT_V(6); PG8_BAR; PG8_BAR; PG8_SCHED;
.LBB0_1668:
	v_add_u32_e32 v86, 0x10000, v72
	v_add_u32_e32 v102, 0x14000, v72
	ds_read_b128 v[74:77], v86
	ds_read_b128 v[78:81], v86 offset:1024
	ds_read_b128 v[82:85], v86 offset:2048
	ds_read_b128 v[86:89], v86 offset:3072
	ds_read_b128 v[90:93], v102
	ds_read_b128 v[94:97], v102 offset:1024
	ds_read_b128 v[98:101], v102 offset:2048
	ds_read_b128 v[102:105], v102 offset:3072
	s_cmp_lg_u32 s27, 28
	s_cselect_b32 s28, s26, 0
	s_add_i32 s29, s28, s17
	s_or_b32 s30, s29, 0x80
	s_add_i32 s28, s28, s10
	ds_read_b128 v[106:109], v73
	ds_read_b128 v[110:113], v73 offset:1024
	ds_read_b128 v[114:117], v73 offset:2048
	ds_read_b128 v[118:121], v73 offset:3072
	ds_read_b128 v[122:125], v73 offset:4096
	ds_read_b128 v[126:129], v73 offset:5120
	ds_read_b128 v[130:133], v73 offset:6144
	ds_read_b128 v[134:137], v73 offset:7168
	s_waitcnt lgkmcnt(0)
	s_setprio 1
	s_barrier
	v_mfma_f32_16x16x32_bf16 v[62:65], v[74:77], v[106:109], v[62:65]
	v_mfma_f32_16x16x32_bf16 v[62:65], v[78:81], v[110:113], v[62:65]
	v_mfma_f32_16x16x32_bf16 v[58:61], v[82:85], v[106:109], v[58:61]
	v_mfma_f32_16x16x32_bf16 v[58:61], v[86:89], v[110:113], v[58:61]
	v_mfma_f32_16x16x32_bf16 v[38:41], v[82:85], v[114:117], v[38:41]
	v_mfma_f32_16x16x32_bf16 v[38:41], v[86:89], v[118:121], v[38:41]
	v_mfma_f32_16x16x32_bf16 v[54:57], v[74:77], v[114:117], v[54:57]
	v_mfma_f32_16x16x32_bf16 v[54:57], v[78:81], v[118:121], v[54:57]
	v_mfma_f32_16x16x32_bf16 v[30:33], v[74:77], v[122:125], v[30:33]
	v_mfma_f32_16x16x32_bf16 v[30:33], v[78:81], v[126:129], v[30:33]
	v_mfma_f32_16x16x32_bf16 v[22:25], v[82:85], v[122:125], v[22:25]
	v_mfma_f32_16x16x32_bf16 v[22:25], v[86:89], v[126:129], v[22:25]
	v_mfma_f32_16x16x32_bf16 v[6:9], v[82:85], v[130:133], v[6:9]
	v_mfma_f32_16x16x32_bf16 v[6:9], v[86:89], v[134:137], v[6:9]
	v_mfma_f32_16x16x32_bf16 v[14:17], v[74:77], v[130:133], v[14:17]
	v_mfma_f32_16x16x32_bf16 v[14:17], v[78:81], v[134:137], v[14:17]
	v_mfma_f32_16x16x32_bf16 v[50:53], v[90:93], v[106:109], v[50:53]
	v_mfma_f32_16x16x32_bf16 v[50:53], v[94:97], v[110:113], v[50:53]
	v_mfma_f32_16x16x32_bf16 v[46:49], v[98:101], v[106:109], v[46:49]
	v_mfma_f32_16x16x32_bf16 v[46:49], v[102:105], v[110:113], v[46:49]
	v_mfma_f32_16x16x32_bf16 v[34:37], v[98:101], v[114:117], v[34:37]
	v_mfma_f32_16x16x32_bf16 v[34:37], v[102:105], v[118:121], v[34:37]
	v_mfma_f32_16x16x32_bf16 v[42:45], v[90:93], v[114:117], v[42:45]
	v_mfma_f32_16x16x32_bf16 v[42:45], v[94:97], v[118:121], v[42:45]
	v_mfma_f32_16x16x32_bf16 v[26:29], v[90:93], v[122:125], v[26:29]
	v_mfma_f32_16x16x32_bf16 v[26:29], v[94:97], v[126:129], v[26:29]
	v_mfma_f32_16x16x32_bf16 v[18:21], v[98:101], v[122:125], v[18:21]
	v_mfma_f32_16x16x32_bf16 v[18:21], v[102:105], v[126:129], v[18:21]
	v_mfma_f32_16x16x32_bf16 v[2:5], v[98:101], v[130:133], v[2:5]
	v_mfma_f32_16x16x32_bf16 v[2:5], v[102:105], v[134:137], v[2:5]
	v_mfma_f32_16x16x32_bf16 v[10:13], v[90:93], v[130:133], v[10:13]
	v_mfma_f32_16x16x32_bf16 v[10:13], v[94:97], v[134:137], v[10:13]
	s_barrier
	s_setprio 0
	s_mov_b32 m0, s13
	s_mov_b32 s42, s78
	s_mov_b32 s43, s79
	buffer_load_dwordx4 v67, s[40:43], s28 offen lds
	s_mov_b32 m0, s14
	s_add_i32 s31, s28, 0x80000
	buffer_load_dwordx4 v69, s[40:43], s28 offen lds
	s_mov_b32 m0, s15
	s_nop 0
	buffer_load_dwordx4 v67, s[40:43], s31 offen lds
	s_mov_b32 m0, s16
	s_nop 0
	buffer_load_dwordx4 v69, s[40:43], s31 offen lds
	s_mov_b32 m0, s12
	s_nop 0
	buffer_load_dwordx4 v66, s[76:79], s29 offen lds
	s_mov_b32 m0, s18
	s_nop 0
	buffer_load_dwordx4 v68, s[76:79], s29 offen lds
	s_waitcnt vmcnt(6)
	s_barrier
	s_barrier
; #define PG8_STAGEX(rs, bufoff, soff, voff) do { _Pragma("unroll") for (int _i = 0; _i < 2; ++_i) \
;         __builtin_amdgcn_raw_ptr_buffer_load_lds(rs, (LAS unsigned*)(lds + (bufoff) + ldsw + _i * 8192), 16, (voff)[_i], (soff), 0, 0); } while (0)
; #define PG8_LDA(dst, b, h) do { _Pragma("unroll") for (int m = 0; m < 4; ++m) _Pragma("unroll") for (int k = 0; k < 2; ++k) dst[m][k] = *(const LAS bf16x8*)(lds + PG8_SA(b, h) + aoff + m * 2048 + k * 1024); } while (0)
; #define PG8_LDB(dst, b, h) do { _Pragma("unroll") for (int n = 0; n < 2; ++n) _Pragma("unroll") for (int k = 0; k < 2; ++k) dst[n][k] = *(const LAS bf16x8*)(lds + PG8_SB(b, h) + boff + n * 2048 + k * 1024); } while (0)
; #define PG8_WAIT_V(n) asm volatile("s_waitcnt vmcnt(" #n ")" ::: "memory")
; #define PG8_WAIT_L(n) asm volatile("s_waitcnt lgkmcnt(" #n ")" ::: "memory")
; #define PG8_BAR __builtin_amdgcn_s_barrier()
; #define PG8_SCHED __builtin_amdgcn_sched_barrier(0)
;     ...
;                 if (w0) { PG8_LDB(B0, 1, 0); PG8_LDB(B1, 1, 1); PG8_SCHED; PG8_LDA(At, 1, 0); }
;                 PG8_WAIT_L(0); PG8_BAR; if (w0) { PG8_MMA(0, 0, At, B0); PG8_MMA(0, 1, At, B1); } PG8_BAR; PG8_SCHED;
;                 PG8_STAGEX(rsB, PG8_SB(1, 0), b3, voffB); PG8_STAGEX(rsB, PG8_SB(1, 1), b3 + hstepB, voffB); PG8_STAGEX(rsA, PG8_SA(1, 0), a3, voffA);
;                 PG8_WAIT_V(6); PG8_BAR; PG8_BAR; PG8_SCHED;
	v_add_u32_e32 v86, 0x18000, v72
	v_add_u32_e32 v102, 0x1c000, v72
	ds_read_b128 v[74:77], v86
	ds_read_b128 v[78:81], v86 offset:1024
	ds_read_b128 v[82:85], v86 offset:2048
	ds_read_b128 v[86:89], v86 offset:3072
	ds_read_b128 v[90:93], v102
	ds_read_b128 v[94:97], v102 offset:1024
	ds_read_b128 v[98:101], v102 offset:2048
	ds_read_b128 v[102:105], v102 offset:3072
	ds_read_b128 v[106:109], v73 offset:32768
	ds_read_b128 v[110:113], v73 offset:33792
	ds_read_b128 v[114:117], v73 offset:34816
	ds_read_b128 v[118:121], v73 offset:35840
	ds_read_b128 v[122:125], v73 offset:36864
	ds_read_b128 v[126:129], v73 offset:37888
	ds_read_b128 v[130:133], v73 offset:38912
	ds_read_b128 v[134:137], v73 offset:39936
	s_waitcnt lgkmcnt(0)
	s_setprio 1
	s_barrier
	v_mfma_f32_16x16x32_bf16 v[62:65], v[74:77], v[106:109], v[62:65]
	v_mfma_f32_16x16x32_bf16 v[58:61], v[82:85], v[106:109], v[58:61]
	v_mfma_f32_16x16x32_bf16 v[54:57], v[74:77], v[114:117], v[54:57]
	v_mfma_f32_16x16x32_bf16 v[38:41], v[82:85], v[114:117], v[38:41]
	v_mfma_f32_16x16x32_bf16 v[30:33], v[74:77], v[122:125], v[30:33]
	v_mfma_f32_16x16x32_bf16 v[22:25], v[82:85], v[122:125], v[22:25]
	v_mfma_f32_16x16x32_bf16 v[14:17], v[74:77], v[130:133], v[14:17]
	v_mfma_f32_16x16x32_bf16 v[6:9], v[82:85], v[130:133], v[6:9]
	v_mfma_f32_16x16x32_bf16 v[62:65], v[78:81], v[110:113], v[62:65]
	v_mfma_f32_16x16x32_bf16 v[58:61], v[86:89], v[110:113], v[58:61]
	v_mfma_f32_16x16x32_bf16 v[54:57], v[78:81], v[118:121], v[54:57]
	v_mfma_f32_16x16x32_bf16 v[38:41], v[86:89], v[118:121], v[38:41]
	v_mfma_f32_16x16x32_bf16 v[30:33], v[78:81], v[126:129], v[30:33]
	v_mfma_f32_16x16x32_bf16 v[22:25], v[86:89], v[126:129], v[22:25]
	v_mfma_f32_16x16x32_bf16 v[14:17], v[78:81], v[134:137], v[14:17]
	v_mfma_f32_16x16x32_bf16 v[6:9], v[86:89], v[134:137], v[6:9]
	v_mfma_f32_16x16x32_bf16 v[50:53], v[90:93], v[106:109], v[50:53]
	s_or_b32 s29, s28, 0x80
	v_mfma_f32_16x16x32_bf16 v[46:49], v[98:101], v[106:109], v[46:49]
	v_mfma_f32_16x16x32_bf16 v[42:45], v[90:93], v[114:117], v[42:45]
	v_mfma_f32_16x16x32_bf16 v[34:37], v[98:101], v[114:117], v[34:37]
	v_mfma_f32_16x16x32_bf16 v[26:29], v[90:93], v[122:125], v[26:29]
	v_mfma_f32_16x16x32_bf16 v[18:21], v[98:101], v[122:125], v[18:21]
	v_mfma_f32_16x16x32_bf16 v[10:13], v[90:93], v[130:133], v[10:13]
	v_mfma_f32_16x16x32_bf16 v[2:5], v[98:101], v[130:133], v[2:5]
	v_mfma_f32_16x16x32_bf16 v[50:53], v[94:97], v[110:113], v[50:53]
	v_mfma_f32_16x16x32_bf16 v[46:49], v[102:105], v[110:113], v[46:49]
	v_mfma_f32_16x16x32_bf16 v[42:45], v[94:97], v[118:121], v[42:45]
	v_mfma_f32_16x16x32_bf16 v[34:37], v[102:105], v[118:121], v[34:37]
	v_mfma_f32_16x16x32_bf16 v[26:29], v[94:97], v[126:129], v[26:29]
	v_mfma_f32_16x16x32_bf16 v[18:21], v[102:105], v[126:129], v[18:21]
	v_mfma_f32_16x16x32_bf16 v[10:13], v[94:97], v[134:137], v[10:13]
	v_mfma_f32_16x16x32_bf16 v[2:5], v[102:105], v[134:137], v[2:5]
	s_barrier
	s_setprio 0
	s_mov_b32 m0, s20
	s_add_i32 s28, s28, 0x80080
	buffer_load_dwordx4 v67, s[40:43], s29 offen lds
	s_mov_b32 m0, s21
	s_nop 0
	buffer_load_dwordx4 v69, s[40:43], s29 offen lds
	s_mov_b32 m0, s24
	s_nop 0
	buffer_load_dwordx4 v67, s[40:43], s28 offen lds
	s_mov_b32 m0, s25
	s_nop 0
	buffer_load_dwordx4 v69, s[40:43], s28 offen lds
	s_mov_b32 m0, s22
	s_nop 0
	buffer_load_dwordx4 v66, s[76:79], s30 offen lds
	s_mov_b32 m0, s23
	s_nop 0
	buffer_load_dwordx4 v68, s[76:79], s30 offen lds
	s_waitcnt vmcnt(6)
	s_barrier
	s_barrier
	s_addk_i32 s26, 0x100
	s_add_i32 s27, s27, 2
	s_cmp_gt_u32 s27, 29
	s_cbranch_scc0 .LBB0_1668
	s_cmpk_lt_u32 s11, 0x100
	s_cbranch_scc0 .LBB0_1671
	s_barrier

; #define PG8_STAGEX(rs, bufoff, soff, voff) do { _Pragma("unroll") for (int _i = 0; _i < 2; ++_i) \
;         __builtin_amdgcn_raw_ptr_buffer_load_lds(rs, (LAS unsigned*)(lds + (bufoff) + ldsw + _i * 8192), 16, (voff)[_i], (soff), 0, 0); } while (0)
; #define PG8_LDA(dst, b, h) do { _Pragma("unroll") for (int m = 0; m < 4; ++m) _Pragma("unroll") for (int k = 0; k < 2; ++k) dst[m][k] = *(const LAS bf16x8*)(lds + PG8_SA(b, h) + aoff + m * 2048 + k * 1024); } while (0)
; #define PG8_LDB(dst, b, h) do { _Pragma("unroll") for (int n = 0; n < 2; ++n) _Pragma("unroll") for (int k = 0; k < 2; ++k) dst[n][k] = *(const LAS bf16x8*)(lds + PG8_SB(b, h) + boff + n * 2048 + k * 1024); } while (0)
; #define PG8_WAIT_V(n) asm volatile("s_waitcnt vmcnt(" #n ")" ::: "memory")
; #define PG8_WAIT_L(n) asm volatile("s_waitcnt lgkmcnt(" #n ")" ::: "memory")
; #define PG8_BAR __builtin_amdgcn_s_barrier()
; #define PG8_SCHED __builtin_amdgcn_sched_barrier(0)
;     ...
;             PG8_LDB(B0, 0, 0); PG8_LDB(B1, 0, 1); PG8_SCHED; PG8_LDA(At, 0, 0); PG8_STAGEX(rsA, PG8_SA(1, 1), a1 + hstepA, voffA);
;             PG8_WAIT_V(8); PG8_WAIT_L(0); PG8_BAR; PG8_MMA(0, 0, At, B0); PG8_MMA(0, 1, At, B1); PG8_BAR; PG8_SCHED;
;             PG8_LDA(At, 0, 1); PG8_STAGEX(rsB, PG8_SB(0, 0), b2, voffB); PG8_STAGEX(rsB, PG8_SB(0, 1), b2 + hstepB, voffB); PG8_STAGEX(rsA, PG8_SA(0, 0), a2, voffA);
;             PG8_WAIT_V(8); PG8_WAIT_L(0); PG8_BAR; PG8_MMA(1, 0, At, B0); PG8_MMA(1, 1, At, B1); PG8_BAR; PG8_SCHED;
.LBB0_1750:
	v_add_u32_e32 v70, 0x10000, v241
	ds_read_b128 v[134:137], v70
	ds_read_b128 v[138:141], v70 offset:1024
	ds_read_b128 v[142:145], v70 offset:2048
	ds_read_b128 v[146:149], v70 offset:3072
	v_add_u32_e32 v70, 0x14000, v241
	ds_read_b128 v[150:153], v70
	ds_read_b128 v[154:157], v70 offset:1024
	ds_read_b128 v[158:161], v70 offset:2048
	ds_read_b128 v[162:165], v70 offset:3072
	s_add_i32 s46, s40, 0xffea8080
	s_cmpk_eq_i32 s60, 0x52
	s_cselect_b32 s63, s30, s46
	s_cselect_b32 s62, s31, s41
	s_or_b32 s61, s63, 0x80
	s_mov_b32 m0, s72
	ds_read_b128 v[166:169], v242
	ds_read_b128 v[170:173], v242 offset:1024
	ds_read_b128 v[184:187], v242 offset:2048
	ds_read_b128 v[188:191], v242 offset:3072
	ds_read_b128 v[192:195], v242 offset:4096
	ds_read_b128 v[196:199], v242 offset:5120
	ds_read_b128 v[200:203], v242 offset:6144
	ds_read_b128 v[204:207], v242 offset:7168
	buffer_load_dwordx4 v178, s[76:79], s40 offen lds
	s_mov_b32 m0, s73
	s_nop 0
	buffer_load_dwordx4 v237, s[76:79], s40 offen lds
	s_waitcnt vmcnt(8)
	s_waitcnt lgkmcnt(0)
	s_setprio 1
	s_barrier
	v_mfma_f32_16x16x32_bf16 v[130:133], v[134:137], v[166:169], v[130:133]
	v_mfma_f32_16x16x32_bf16 v[130:133], v[138:141], v[170:173], v[130:133]
	v_mfma_f32_16x16x32_bf16 v[126:129], v[142:145], v[166:169], v[126:129]
	v_mfma_f32_16x16x32_bf16 v[126:129], v[146:149], v[170:173], v[126:129]
	v_mfma_f32_16x16x32_bf16 v[118:121], v[142:145], v[184:187], v[118:121]
	v_mfma_f32_16x16x32_bf16 v[118:121], v[146:149], v[188:191], v[118:121]
	v_mfma_f32_16x16x32_bf16 v[122:125], v[134:137], v[184:187], v[122:125]
	v_mfma_f32_16x16x32_bf16 v[122:125], v[138:141], v[188:191], v[122:125]
	v_mfma_f32_16x16x32_bf16 v[114:117], v[134:137], v[192:195], v[114:117]
	v_mfma_f32_16x16x32_bf16 v[114:117], v[138:141], v[196:199], v[114:117]
	v_mfma_f32_16x16x32_bf16 v[110:113], v[142:145], v[192:195], v[110:113]
	v_mfma_f32_16x16x32_bf16 v[110:113], v[146:149], v[196:199], v[110:113]
	v_mfma_f32_16x16x32_bf16 v[102:105], v[142:145], v[200:203], v[102:105]
	v_mfma_f32_16x16x32_bf16 v[102:105], v[146:149], v[204:207], v[102:105]
	v_mfma_f32_16x16x32_bf16 v[106:109], v[134:137], v[200:203], v[106:109]
	v_mfma_f32_16x16x32_bf16 v[106:109], v[138:141], v[204:207], v[106:109]
	v_mfma_f32_16x16x32_bf16 v[62:65], v[150:153], v[166:169], v[62:65]
	v_mfma_f32_16x16x32_bf16 v[62:65], v[154:157], v[170:173], v[62:65]
	v_mfma_f32_16x16x32_bf16 v[58:61], v[158:161], v[166:169], v[58:61]
	v_mfma_f32_16x16x32_bf16 v[58:61], v[162:165], v[170:173], v[58:61]
	v_mfma_f32_16x16x32_bf16 v[50:53], v[158:161], v[184:187], v[50:53]
	v_mfma_f32_16x16x32_bf16 v[50:53], v[162:165], v[188:191], v[50:53]
	v_mfma_f32_16x16x32_bf16 v[54:57], v[150:153], v[184:187], v[54:57]
	v_mfma_f32_16x16x32_bf16 v[54:57], v[154:157], v[188:191], v[54:57]
	v_mfma_f32_16x16x32_bf16 v[46:49], v[150:153], v[192:195], v[46:49]
	v_mfma_f32_16x16x32_bf16 v[46:49], v[154:157], v[196:199], v[46:49]
	v_mfma_f32_16x16x32_bf16 v[42:45], v[158:161], v[192:195], v[42:45]
	v_mfma_f32_16x16x32_bf16 v[42:45], v[162:165], v[196:199], v[42:45]
	v_mfma_f32_16x16x32_bf16 v[34:37], v[158:161], v[200:203], v[34:37]
	v_mfma_f32_16x16x32_bf16 v[34:37], v[162:165], v[204:207], v[34:37]
	v_mfma_f32_16x16x32_bf16 v[38:41], v[150:153], v[200:203], v[38:41]
	v_mfma_f32_16x16x32_bf16 v[38:41], v[154:157], v[204:207], v[38:41]
	s_barrier
	s_setprio 0
	s_mov_b32 m0, s17
	s_mov_b32 s46, s78
	s_mov_b32 s47, s79
	ds_read_b128 v[166:169], v242 offset:16384
	ds_read_b128 v[170:173], v242 offset:17408
	ds_read_b128 v[184:187], v242 offset:18432
	ds_read_b128 v[188:191], v242 offset:19456
	ds_read_b128 v[192:195], v242 offset:20480
	ds_read_b128 v[196:199], v242 offset:21504
	ds_read_b128 v[200:203], v242 offset:22528
	ds_read_b128 v[204:207], v242 offset:23552
	buffer_load_dwordx4 v179, s[44:47], s62 offen lds
	s_mov_b32 m0, s18
	s_add_i32 s64, s62, 0x158000
	buffer_load_dwordx4 v238, s[44:47], s62 offen lds
	s_mov_b32 m0, s19
	s_nop 0
	buffer_load_dwordx4 v179, s[44:47], s64 offen lds
	s_mov_b32 m0, s20
	s_nop 0
	buffer_load_dwordx4 v238, s[44:47], s64 offen lds
	s_mov_b32 m0, s16
	s_nop 0
	buffer_load_dwordx4 v178, s[76:79], s63 offen lds
	s_mov_b32 m0, s21
	s_nop 0
	buffer_load_dwordx4 v237, s[76:79], s63 offen lds
	s_waitcnt vmcnt(8)
	s_waitcnt lgkmcnt(0)
	s_setprio 1
	s_barrier
	v_mfma_f32_16x16x32_bf16 v[98:101], v[134:137], v[166:169], v[98:101]
	v_mfma_f32_16x16x32_bf16 v[94:97], v[142:145], v[166:169], v[94:97]
	v_mfma_f32_16x16x32_bf16 v[90:93], v[134:137], v[184:187], v[90:93]
	v_mfma_f32_16x16x32_bf16 v[86:89], v[142:145], v[184:187], v[86:89]
	v_mfma_f32_16x16x32_bf16 v[82:85], v[134:137], v[192:195], v[82:85]
	v_mfma_f32_16x16x32_bf16 v[76:79], v[142:145], v[192:195], v[78:81]
	v_mfma_f32_16x16x32_bf16 v[70:73], v[134:137], v[200:203], v[72:75]
	v_mfma_f32_16x16x32_bf16 v[66:69], v[142:145], v[200:203], v[66:69]
	v_mfma_f32_16x16x32_bf16 v[98:101], v[138:141], v[170:173], v[98:101]
	v_mfma_f32_16x16x32_bf16 v[94:97], v[146:149], v[170:173], v[94:97]
	v_mfma_f32_16x16x32_bf16 v[90:93], v[138:141], v[188:191], v[90:93]
	v_mfma_f32_16x16x32_bf16 v[86:89], v[146:149], v[188:191], v[86:89]
	v_mfma_f32_16x16x32_bf16 v[82:85], v[138:141], v[196:199], v[82:85]
	v_mfma_f32_16x16x32_bf16 v[76:79], v[146:149], v[196:199], v[76:79]
	v_mfma_f32_16x16x32_bf16 v[70:73], v[138:141], v[204:207], v[70:73]
	v_mfma_f32_16x16x32_bf16 v[66:69], v[146:149], v[204:207], v[66:69]
	v_mfma_f32_16x16x32_bf16 v[30:33], v[150:153], v[166:169], v[30:33]
	v_mfma_f32_16x16x32_bf16 v[26:29], v[158:161], v[166:169], v[26:29]
	v_mfma_f32_16x16x32_bf16 v[22:25], v[150:153], v[184:187], v[22:25]
	v_mfma_f32_16x16x32_bf16 v[18:21], v[158:161], v[184:187], v[18:21]
	v_mfma_f32_16x16x32_bf16 v[14:17], v[150:153], v[192:195], v[14:17]
	v_mfma_f32_16x16x32_bf16 v[10:13], v[158:161], v[192:195], v[10:13]
	v_mfma_f32_16x16x32_bf16 v[6:9], v[150:153], v[200:203], v[6:9]
	v_mfma_f32_16x16x32_bf16 v[2:5], v[158:161], v[200:203], v[2:5]
	v_mfma_f32_16x16x32_bf16 v[30:33], v[154:157], v[170:173], v[30:33]
	v_mfma_f32_16x16x32_bf16 v[26:29], v[162:165], v[170:173], v[26:29]
	v_mfma_f32_16x16x32_bf16 v[22:25], v[154:157], v[188:191], v[22:25]
	v_mfma_f32_16x16x32_bf16 v[18:21], v[162:165], v[188:191], v[18:21]
	v_mfma_f32_16x16x32_bf16 v[14:17], v[154:157], v[196:199], v[14:17]
	v_mfma_f32_16x16x32_bf16 v[10:13], v[162:165], v[196:199], v[10:13]
	v_mfma_f32_16x16x32_bf16 v[6:9], v[154:157], v[204:207], v[6:9]
	v_mfma_f32_16x16x32_bf16 v[2:5], v[162:165], v[204:207], v[2:5]
	s_barrier
; #define PG8_STAGEX(rs, bufoff, soff, voff) do { _Pragma("unroll") for (int _i = 0; _i < 2; ++_i) \
;         __builtin_amdgcn_raw_ptr_buffer_load_lds(rs, (LAS unsigned*)(lds + (bufoff) + ldsw + _i * 8192), 16, (voff)[_i], (soff), 0, 0); } while (0)
; #define PG8_LDA(dst, b, h) do { _Pragma("unroll") for (int m = 0; m < 4; ++m) _Pragma("unroll") for (int k = 0; k < 2; ++k) dst[m][k] = *(const LAS bf16x8*)(lds + PG8_SA(b, h) + aoff + m * 2048 + k * 1024); } while (0)
; #define PG8_LDB(dst, b, h) do { _Pragma("unroll") for (int n = 0; n < 2; ++n) _Pragma("unroll") for (int k = 0; k < 2; ++k) dst[n][k] = *(const LAS bf16x8*)(lds + PG8_SB(b, h) + boff + n * 2048 + k * 1024); } while (0)
; #define PG8_WAIT_V(n) asm volatile("s_waitcnt vmcnt(" #n ")" ::: "memory")
; #define PG8_WAIT_L(n) asm volatile("s_waitcnt lgkmcnt(" #n ")" ::: "memory")
; #define PG8_BAR __builtin_amdgcn_s_barrier()
; #define PG8_SCHED __builtin_amdgcn_sched_barrier(0)
;     ...
;             PG8_LDB(B0, 1, 0); PG8_LDB(B1, 1, 1); PG8_SCHED; PG8_LDA(At, 1, 0); PG8_STAGEX(rsA, PG8_SA(0, 1), a2 + hstepA, voffA);
;             PG8_WAIT_V(8); PG8_WAIT_L(0); PG8_BAR; PG8_MMA(0, 0, At, B0); PG8_MMA(0, 1, At, B1); PG8_BAR; PG8_SCHED;
;             PG8_LDA(At, 1, 1); PG8_STAGEX(rsB, PG8_SB(1, 0), b3, voffB); PG8_STAGEX(rsB, PG8_SB(1, 1), b3 + hstepB, voffB); PG8_STAGEX(rsA, PG8_SA(1, 0), a3, voffA);
;             PG8_WAIT_V(8); PG8_WAIT_L(0); PG8_BAR; PG8_MMA(1, 0, At, B0); PG8_MMA(1, 1, At, B1); PG8_BAR; PG8_SCHED;
;         }
	s_setprio 0
	v_add_u32_e32 v74, 0x18000, v241
	ds_read_b128 v[134:137], v74
	ds_read_b128 v[138:141], v74 offset:1024
	ds_read_b128 v[142:145], v74 offset:2048
	ds_read_b128 v[146:149], v74 offset:3072
	v_add_u32_e32 v74, 0x1c000, v241
	ds_read_b128 v[150:153], v74
	ds_read_b128 v[154:157], v74 offset:1024
	ds_read_b128 v[158:161], v74 offset:2048
	ds_read_b128 v[162:165], v74 offset:3072
	s_add_i32 s63, s63, 0x158000
	s_mov_b32 m0, s22
	ds_read_b128 v[166:169], v242 offset:32768
	ds_read_b128 v[170:173], v242 offset:33792
	ds_read_b128 v[184:187], v242 offset:34816
	ds_read_b128 v[188:191], v242 offset:35840
	ds_read_b128 v[192:195], v242 offset:36864
	ds_read_b128 v[196:199], v242 offset:37888
	ds_read_b128 v[200:203], v242 offset:38912
	ds_read_b128 v[204:207], v242 offset:39936
	buffer_load_dwordx4 v178, s[76:79], s63 offen lds
	s_mov_b32 m0, s23
	s_nop 0
	buffer_load_dwordx4 v237, s[76:79], s63 offen lds
	s_waitcnt vmcnt(8)
	s_waitcnt lgkmcnt(0)
	s_setprio 1
	s_barrier
	v_mfma_f32_16x16x32_bf16 v[130:133], v[134:137], v[166:169], v[130:133]
	v_mfma_f32_16x16x32_bf16 v[130:133], v[138:141], v[170:173], v[130:133]
	v_mfma_f32_16x16x32_bf16 v[126:129], v[142:145], v[166:169], v[126:129]
	v_mfma_f32_16x16x32_bf16 v[126:129], v[146:149], v[170:173], v[126:129]
	v_mfma_f32_16x16x32_bf16 v[118:121], v[142:145], v[184:187], v[118:121]
	v_mfma_f32_16x16x32_bf16 v[118:121], v[146:149], v[188:191], v[118:121]
	v_mfma_f32_16x16x32_bf16 v[122:125], v[134:137], v[184:187], v[122:125]
	v_mfma_f32_16x16x32_bf16 v[122:125], v[138:141], v[188:191], v[122:125]
	v_mfma_f32_16x16x32_bf16 v[114:117], v[134:137], v[192:195], v[114:117]
	v_mfma_f32_16x16x32_bf16 v[114:117], v[138:141], v[196:199], v[114:117]
	v_mfma_f32_16x16x32_bf16 v[110:113], v[142:145], v[192:195], v[110:113]
	v_mfma_f32_16x16x32_bf16 v[110:113], v[146:149], v[196:199], v[110:113]
	v_mfma_f32_16x16x32_bf16 v[102:105], v[142:145], v[200:203], v[102:105]
	v_mfma_f32_16x16x32_bf16 v[102:105], v[146:149], v[204:207], v[102:105]
	v_mfma_f32_16x16x32_bf16 v[106:109], v[134:137], v[200:203], v[106:109]
	v_mfma_f32_16x16x32_bf16 v[106:109], v[138:141], v[204:207], v[106:109]
	v_mfma_f32_16x16x32_bf16 v[62:65], v[150:153], v[166:169], v[62:65]
	v_mfma_f32_16x16x32_bf16 v[62:65], v[154:157], v[170:173], v[62:65]
	v_mfma_f32_16x16x32_bf16 v[58:61], v[158:161], v[166:169], v[58:61]
	v_mfma_f32_16x16x32_bf16 v[58:61], v[162:165], v[170:173], v[58:61]
	v_mfma_f32_16x16x32_bf16 v[50:53], v[158:161], v[184:187], v[50:53]
	v_mfma_f32_16x16x32_bf16 v[50:53], v[162:165], v[188:191], v[50:53]
	v_mfma_f32_16x16x32_bf16 v[54:57], v[150:153], v[184:187], v[54:57]
	v_mfma_f32_16x16x32_bf16 v[54:57], v[154:157], v[188:191], v[54:57]
	v_mfma_f32_16x16x32_bf16 v[46:49], v[150:153], v[192:195], v[46:49]
	v_mfma_f32_16x16x32_bf16 v[46:49], v[154:157], v[196:199], v[46:49]
	v_mfma_f32_16x16x32_bf16 v[42:45], v[158:161], v[192:195], v[42:45]
	v_mfma_f32_16x16x32_bf16 v[42:45], v[162:165], v[196:199], v[42:45]
	v_mfma_f32_16x16x32_bf16 v[34:37], v[158:161], v[200:203], v[34:37]
	v_mfma_f32_16x16x32_bf16 v[34:37], v[162:165], v[204:207], v[34:37]
	v_mfma_f32_16x16x32_bf16 v[38:41], v[150:153], v[200:203], v[38:41]
	v_mfma_f32_16x16x32_bf16 v[38:41], v[154:157], v[204:207], v[38:41]
	s_barrier
	s_setprio 0
	s_mov_b32 m0, s54
	s_or_b32 s63, s62, 0x80
	ds_read_b128 v[166:169], v242 offset:49152
	ds_read_b128 v[170:173], v242 offset:50176
	ds_read_b128 v[184:187], v242 offset:51200
	ds_read_b128 v[188:191], v242 offset:52224
	ds_read_b128 v[192:195], v242 offset:53248
	ds_read_b128 v[196:199], v242 offset:54272
	ds_read_b128 v[200:203], v242 offset:55296
	ds_read_b128 v[204:207], v242 offset:56320
	buffer_load_dwordx4 v179, s[44:47], s63 offen lds
	s_mov_b32 m0, s55
	s_add_i32 s62, s62, 0x158080
	buffer_load_dwordx4 v238, s[44:47], s63 offen lds
	s_mov_b32 m0, s70
	s_nop 0
	buffer_load_dwordx4 v179, s[44:47], s62 offen lds
	s_mov_b32 m0, s71
	s_nop 0
	buffer_load_dwordx4 v238, s[44:47], s62 offen lds
	s_mov_b32 m0, s68
	s_nop 0
	buffer_load_dwordx4 v178, s[76:79], s61 offen lds
	s_mov_b32 m0, s69
	s_nop 0
	buffer_load_dwordx4 v237, s[76:79], s61 offen lds
	s_waitcnt vmcnt(8)
	s_waitcnt lgkmcnt(0)
	s_setprio 1
	s_barrier
	v_mfma_f32_16x16x32_bf16 v[98:101], v[134:137], v[166:169], v[98:101]
	v_mfma_f32_16x16x32_bf16 v[94:97], v[142:145], v[166:169], v[94:97]
	v_mfma_f32_16x16x32_bf16 v[90:93], v[134:137], v[184:187], v[90:93]
	v_mfma_f32_16x16x32_bf16 v[86:89], v[142:145], v[184:187], v[86:89]
	v_mfma_f32_16x16x32_bf16 v[80:83], v[134:137], v[192:195], v[82:85]
	v_mfma_f32_16x16x32_bf16 v[74:77], v[142:145], v[192:195], v[76:79]
	v_mfma_f32_16x16x32_bf16 v[70:73], v[134:137], v[200:203], v[70:73]
	v_mfma_f32_16x16x32_bf16 v[66:69], v[142:145], v[200:203], v[66:69]
	v_mfma_f32_16x16x32_bf16 v[98:101], v[138:141], v[170:173], v[98:101]
	v_mfma_f32_16x16x32_bf16 v[94:97], v[146:149], v[170:173], v[94:97]
	v_mfma_f32_16x16x32_bf16 v[90:93], v[138:141], v[188:191], v[90:93]
	v_mfma_f32_16x16x32_bf16 v[86:89], v[146:149], v[188:191], v[86:89]
	v_mfma_f32_16x16x32_bf16 v[82:85], v[138:141], v[196:199], v[80:83]
	v_mfma_f32_16x16x32_bf16 v[78:81], v[146:149], v[196:199], v[74:77]
	v_mfma_f32_16x16x32_bf16 v[72:75], v[138:141], v[204:207], v[70:73]
	v_mfma_f32_16x16x32_bf16 v[66:69], v[146:149], v[204:207], v[66:69]
	v_mfma_f32_16x16x32_bf16 v[30:33], v[150:153], v[166:169], v[30:33]
	v_mfma_f32_16x16x32_bf16 v[26:29], v[158:161], v[166:169], v[26:29]
	v_mfma_f32_16x16x32_bf16 v[22:25], v[150:153], v[184:187], v[22:25]
	v_mfma_f32_16x16x32_bf16 v[18:21], v[158:161], v[184:187], v[18:21]
	v_mfma_f32_16x16x32_bf16 v[14:17], v[150:153], v[192:195], v[14:17]
	v_mfma_f32_16x16x32_bf16 v[10:13], v[158:161], v[192:195], v[10:13]
	v_mfma_f32_16x16x32_bf16 v[6:9], v[150:153], v[200:203], v[6:9]
	v_mfma_f32_16x16x32_bf16 v[2:5], v[158:161], v[200:203], v[2:5]
	v_mfma_f32_16x16x32_bf16 v[30:33], v[154:157], v[170:173], v[30:33]
	v_mfma_f32_16x16x32_bf16 v[26:29], v[162:165], v[170:173], v[26:29]
	v_mfma_f32_16x16x32_bf16 v[22:25], v[154:157], v[188:191], v[22:25]
	v_mfma_f32_16x16x32_bf16 v[18:21], v[162:165], v[188:191], v[18:21]
	v_mfma_f32_16x16x32_bf16 v[14:17], v[154:157], v[196:199], v[14:17]
	v_mfma_f32_16x16x32_bf16 v[10:13], v[162:165], v[196:199], v[10:13]
	v_mfma_f32_16x16x32_bf16 v[6:9], v[154:157], v[204:207], v[6:9]
	v_mfma_f32_16x16x32_bf16 v[2:5], v[162:165], v[204:207], v[2:5]
	s_barrier
	s_setprio 0
	s_add_i32 s60, s60, 2
	s_addk_i32 s40, 0x100
	s_addk_i32 s41, 0x100
	s_cmpk_gt_u32 s60, 0x53
	s_cbranch_scc0 .LBB0_1750
	s_and_b64 vcc, exec, s[50:51]
	s_cbranch_vccz .LBB0_1753
	s_barrier
